# scan loop hand-scheduled; prep/readout per-token loads hoisted/prefetched; PH9 split-K tail epilogue de-serialized; GEMM ds_write blocks moved to iteration top
# baseline (speedup 1.0000x reference)
.LBB0_232:
	s_mul_hi_i32 s2, s8, 0x66666667
	s_lshr_b32 s3, s2, 31
	s_ashr_i32 s2, s2, 3
	s_add_i32 s34, s2, s3
	s_ashr_i32 s35, s34, 31
	v_readlane_b32 s36, v210, 50
	v_mov_b32_e32 v36, v133
	s_lshl_b64 s[2:3], s[34:35], 18
	v_readlane_b32 s38, v210, 52
	v_readlane_b32 s39, v210, 53
	v_ashrrev_i32_e32 v34, 3, v36
	s_add_u32 s2, s38, s2
	v_ashrrev_i32_e32 v35, 31, v34
	s_addc_u32 s3, s39, s3
	v_lshlrev_b64 v[2:3], 11, v[34:35]
	s_waitcnt vmcnt(0)
	v_lshlrev_b32_e32 v0, 4, v36
	v_lshl_add_u64 v[2:3], s[2:3], 0, v[2:3]
	v_and_b32_e32 v0, 0x70, v0
	s_mul_i32 s2, s34, 0xa00
	v_lshl_add_u64 v[66:67], v[2:3], 0, v[0:1]
	v_subrev_u32_e32 v2, s2, v34
	v_add_u32_e32 v2, s7, v2
	v_ashrrev_i32_e32 v3, 31, v2
	v_lshlrev_b64 v[2:3], 11, v[2:3]
	v_lshl_add_u64 v[2:3], s[0:1], 0, v[2:3]
	v_add_co_u32_e32 v70, vcc, s56, v66
	v_lshl_add_u64 v[68:69], v[2:3], 0, v[0:1]
	s_nop 0
	v_addc_co_u32_e32 v71, vcc, 0, v67, vcc
	v_add_co_u32_e32 v72, vcc, s56, v68
	global_load_dwordx4 v[2:5], v[66:67], off
	global_load_dwordx4 v[6:9], v[68:69], off
	v_addc_co_u32_e32 v73, vcc, 0, v69, vcc
	v_add_co_u32_e32 v74, vcc, s57, v66
	global_load_dwordx4 v[10:13], v[70:71], off
	s_nop 0
	v_addc_co_u32_e32 v75, vcc, 0, v67, vcc
	v_add_co_u32_e32 v76, vcc, s57, v68
	global_load_dwordx4 v[14:17], v[72:73], off
	s_nop 0
	v_addc_co_u32_e32 v77, vcc, 0, v69, vcc
	global_load_dwordx4 v[18:21], v[74:75], off
	v_add_co_u32_e32 v78, vcc, s58, v66
	global_load_dwordx4 v[22:25], v[76:77], off
	s_nop 0
	v_addc_co_u32_e32 v79, vcc, 0, v67, vcc
	global_load_dwordx4 v[26:29], v[78:79], off
	v_add_co_u32_e32 v80, vcc, s58, v68
	v_lshlrev_b32_e32 v0, 7, v34
	s_nop 0
	v_addc_co_u32_e32 v81, vcc, 0, v69, vcc
	global_load_dwordx4 v[30:33], v[80:81], off
	global_load_dwordx4 v[94:97], v[66:67], off offset:128
	global_load_dwordx4 v[98:101], v[68:69], off offset:128
	global_load_dwordx4 v[102:105], v[70:71], off offset:128
	global_load_dwordx4 v[106:109], v[72:73], off offset:128
	global_load_dwordx4 v[110:113], v[74:75], off offset:128
	global_load_dwordx4 v[114:117], v[76:77], off offset:128
	global_load_dwordx4 v[118:121], v[78:79], off offset:128
	global_load_dwordx4 v[122:125], v[80:81], off offset:128
	v_lshrrev_b32_e32 v34, 1, v34
	v_xor_b32_e32 v34, v34, v36
	v_lshlrev_b32_e32 v34, 4, v34
	v_and_or_b32 v0, v34, s59, v0
	v_and_b32_e32 v84, 31, v36
	v_bfe_u32 v82, v36, 5, 1
	v_ashrrev_i32_e32 v83, 7, v36
	v_bfe_u32 v85, v36, 6, 1
	v_readlane_b32 s40, v210, 54
	v_readlane_b32 s41, v210, 55
	v_readlane_b32 s37, v210, 51
	v_readlane_b32 s42, v210, 56
	v_readlane_b32 s43, v210, 57
	v_readlane_b32 s44, v210, 58
	v_readlane_b32 s45, v210, 59
	v_readlane_b32 s46, v210, 60
	v_readlane_b32 s47, v210, 61
	v_readlane_b32 s48, v210, 62
	v_readlane_b32 s49, v210, 63
	v_readlane_b32 s50, v209, 0
	v_readlane_b32 s51, v209, 1
	s_waitcnt vmcnt(15)
	ds_write_b128 v0, v[2:5]
	s_waitcnt vmcnt(14)
	ds_write_b128 v0, v[6:9] offset:32768
	s_waitcnt vmcnt(13)
	ds_write_b128 v0, v[10:13] offset:4096
	s_waitcnt vmcnt(12)
	ds_write_b128 v0, v[14:17] offset:36864
	s_waitcnt vmcnt(11)
	ds_write_b128 v0, v[18:21] offset:8192
	s_waitcnt vmcnt(10)
	ds_write_b128 v0, v[22:25] offset:40960
	s_waitcnt vmcnt(9)
	ds_write_b128 v0, v[26:29] offset:12288
	s_waitcnt vmcnt(8)
	ds_write_b128 v0, v[30:33] offset:45056
	s_waitcnt lgkmcnt(0)
	s_barrier
	global_load_dwordx4 v[126:129], v[66:67], off offset:256
	global_load_dwordx4 v[134:137], v[68:69], off offset:256
	global_load_dwordx4 v[138:141], v[70:71], off offset:256
	global_load_dwordx4 v[142:145], v[72:73], off offset:256
	global_load_dwordx4 v[146:149], v[74:75], off offset:256
	global_load_dwordx4 v[150:153], v[76:77], off offset:256
	global_load_dwordx4 v[154:157], v[78:79], off offset:256
	global_load_dwordx4 v[158:161], v[80:81], off offset:256
	s_waitcnt vmcnt(15)
	ds_write_b128 v0, v[94:97] offset:16384
	s_waitcnt vmcnt(14)
	ds_write_b128 v0, v[98:101] offset:49152
	s_waitcnt vmcnt(13)
	ds_write_b128 v0, v[102:105] offset:20480
	s_waitcnt vmcnt(12)
	ds_write_b128 v0, v[106:109] offset:53248
	s_waitcnt vmcnt(11)
	ds_write_b128 v0, v[110:113] offset:24576
	s_waitcnt vmcnt(10)
	ds_write_b128 v0, v[114:117] offset:57344
	s_waitcnt vmcnt(9)
	ds_write_b128 v0, v[118:121] offset:28672
	s_waitcnt vmcnt(8)
	ds_write_b128 v0, v[122:125] offset:61440
	v_lshrrev_b32_e32 v4, 1, v36
	v_lshlrev_b32_e32 v2, 7, v84
	v_bitop3_b32 v4, v4, v82, 7 bitop3:0x6c
	v_lshl_or_b32 v3, v83, 13, v2
	v_bfe_u32 v5, v36, 1, 3
	v_lshlrev_b32_e32 v4, 4, v4
	v_lshl_or_b32 v2, v85, 13, v2
	v_or_b32_e32 v91, v3, v4
	v_or_b32_e32 v92, v2, v4
	v_bitop3_b32 v4, v82, v5, 2 bitop3:0x36
	v_lshlrev_b32_e32 v4, 4, v4
	v_or_b32_e32 v93, v3, v4
	v_or_b32_e32 v90, v2, v4
	v_bitop3_b32 v4, v82, v5, 4 bitop3:0x36
	v_lshlrev_b32_e32 v4, 4, v4
	v_or_b32_e32 v89, v3, v4
	v_or_b32_e32 v88, v2, v4
	v_bitop3_b32 v4, v82, v5, 6 bitop3:0x36
	v_lshlrev_b32_e32 v4, 4, v4
	v_or_b32_e32 v87, v3, v4
	v_or_b32_e32 v86, v2, v4
	ds_read_b128 v[2:5], v91
	ds_read_b128 v[6:9], v92 offset:32768
	ds_read_b128 v[10:13], v91 offset:4096
	ds_read_b128 v[14:17], v92 offset:36864
	ds_read_b128 v[162:165], v93
	ds_read_b128 v[166:169], v90 offset:32768
	ds_read_b128 v[182:185], v93 offset:4096
	ds_read_b128 v[186:189], v90 offset:36864
	s_waitcnt lgkmcnt(6)
	v_mfma_f32_32x32x16_bf16 v[50:65], v[2:5], v[6:9], 0
	s_waitcnt lgkmcnt(4)
	v_mfma_f32_32x32x16_bf16 v[34:49], v[2:5], v[14:17], 0
	v_mfma_f32_32x32x16_bf16 v[18:33], v[10:13], v[6:9], 0
	v_mfma_f32_32x32x16_bf16 v[2:17], v[10:13], v[14:17], 0
	ds_read_b128 v[190:193], v89
	ds_read_b128 v[194:197], v89 offset:4096
	ds_read_b128 v[198:201], v88 offset:32768
	ds_read_b128 v[202:205], v88 offset:36864
	s_waitcnt lgkmcnt(6)
	v_mfma_f32_32x32x16_bf16 v[50:65], v[162:165], v[166:169], v[50:65]
	s_waitcnt lgkmcnt(4)
	v_mfma_f32_32x32x16_bf16 v[34:49], v[162:165], v[186:189], v[34:49]
	v_mfma_f32_32x32x16_bf16 v[18:33], v[182:185], v[166:169], v[18:33]
	v_mfma_f32_32x32x16_bf16 v[2:17], v[182:185], v[186:189], v[2:17]
	ds_read_b128 v[162:165], v87
	ds_read_b128 v[166:169], v87 offset:4096
	ds_read_b128 v[182:185], v86 offset:32768
	ds_read_b128 v[186:189], v86 offset:36864
	s_waitcnt lgkmcnt(0)
	s_barrier
	global_load_dwordx4 v[94:97], v[66:67], off offset:384
	global_load_dwordx4 v[98:101], v[68:69], off offset:384
	global_load_dwordx4 v[102:105], v[70:71], off offset:384
	global_load_dwordx4 v[106:109], v[72:73], off offset:384
	global_load_dwordx4 v[110:113], v[74:75], off offset:384
	global_load_dwordx4 v[114:117], v[76:77], off offset:384
	global_load_dwordx4 v[118:121], v[78:79], off offset:384
	global_load_dwordx4 v[122:125], v[80:81], off offset:384
	s_waitcnt vmcnt(15)
	ds_write_b128 v0, v[126:129]
	s_waitcnt vmcnt(14)
	ds_write_b128 v0, v[134:137] offset:32768
	s_waitcnt vmcnt(13)
	ds_write_b128 v0, v[138:141] offset:4096
	s_waitcnt vmcnt(12)
	ds_write_b128 v0, v[142:145] offset:36864
	s_waitcnt vmcnt(11)
	ds_write_b128 v0, v[146:149] offset:8192
	s_waitcnt vmcnt(10)
	ds_write_b128 v0, v[150:153] offset:40960
	s_waitcnt vmcnt(9)
	ds_write_b128 v0, v[154:157] offset:12288
	s_waitcnt vmcnt(8)
	ds_write_b128 v0, v[158:161] offset:45056
	v_mfma_f32_32x32x16_bf16 v[50:65], v[190:193], v[198:201], v[50:65]
	v_mfma_f32_32x32x16_bf16 v[34:49], v[190:193], v[202:205], v[34:49]
	v_mfma_f32_32x32x16_bf16 v[18:33], v[194:197], v[198:201], v[18:33]
	v_mfma_f32_32x32x16_bf16 v[2:17], v[194:197], v[202:205], v[2:17]
	v_mfma_f32_32x32x16_bf16 v[50:65], v[162:165], v[182:185], v[50:65]
	v_mfma_f32_32x32x16_bf16 v[34:49], v[162:165], v[186:189], v[34:49]
	v_mfma_f32_32x32x16_bf16 v[18:33], v[166:169], v[182:185], v[18:33]
	v_mfma_f32_32x32x16_bf16 v[2:17], v[166:169], v[186:189], v[2:17]
	ds_read_b128 v[162:165], v91 offset:16384
	ds_read_b128 v[166:169], v92 offset:49152
	ds_read_b128 v[182:185], v91 offset:20480
	ds_read_b128 v[186:189], v92 offset:53248
	ds_read_b128 v[190:193], v93 offset:16384
	ds_read_b128 v[194:197], v90 offset:49152
	ds_read_b128 v[198:201], v93 offset:20480
	ds_read_b128 v[202:205], v90 offset:53248
	s_waitcnt lgkmcnt(6)
	v_mfma_f32_32x32x16_bf16 v[50:65], v[162:165], v[166:169], v[50:65]
	s_waitcnt lgkmcnt(4)
	v_mfma_f32_32x32x16_bf16 v[34:49], v[162:165], v[186:189], v[34:49]
	v_mfma_f32_32x32x16_bf16 v[18:33], v[182:185], v[166:169], v[18:33]
	v_mfma_f32_32x32x16_bf16 v[2:17], v[182:185], v[186:189], v[2:17]
	ds_read_b128 v[162:165], v89 offset:16384
	ds_read_b128 v[166:169], v89 offset:20480
	ds_read_b128 v[182:185], v88 offset:49152
	ds_read_b128 v[186:189], v88 offset:53248
	s_waitcnt lgkmcnt(6)
	v_mfma_f32_32x32x16_bf16 v[50:65], v[190:193], v[194:197], v[50:65]
	s_waitcnt lgkmcnt(4)
	v_mfma_f32_32x32x16_bf16 v[34:49], v[190:193], v[202:205], v[34:49]
	v_mfma_f32_32x32x16_bf16 v[18:33], v[198:201], v[194:197], v[18:33]
	v_mfma_f32_32x32x16_bf16 v[2:17], v[198:201], v[202:205], v[2:17]
	ds_read_b128 v[190:193], v87 offset:16384
	ds_read_b128 v[194:197], v87 offset:20480
	ds_read_b128 v[198:201], v86 offset:49152
	ds_read_b128 v[202:205], v86 offset:53248
	s_waitcnt lgkmcnt(0)
	s_barrier
	global_load_dwordx4 v[126:129], v[66:67], off offset:512
	global_load_dwordx4 v[134:137], v[68:69], off offset:512
	global_load_dwordx4 v[138:141], v[70:71], off offset:512
	global_load_dwordx4 v[142:145], v[72:73], off offset:512
	global_load_dwordx4 v[146:149], v[74:75], off offset:512
	global_load_dwordx4 v[150:153], v[76:77], off offset:512
	global_load_dwordx4 v[154:157], v[78:79], off offset:512
	global_load_dwordx4 v[158:161], v[80:81], off offset:512
	s_waitcnt vmcnt(15)
	ds_write_b128 v0, v[94:97] offset:16384
	s_waitcnt vmcnt(14)
	ds_write_b128 v0, v[98:101] offset:49152
	s_waitcnt vmcnt(13)
	ds_write_b128 v0, v[102:105] offset:20480
	s_waitcnt vmcnt(12)
	ds_write_b128 v0, v[106:109] offset:53248
	s_waitcnt vmcnt(11)
	ds_write_b128 v0, v[110:113] offset:24576
	s_waitcnt vmcnt(10)
	ds_write_b128 v0, v[114:117] offset:57344
	s_waitcnt vmcnt(9)
	ds_write_b128 v0, v[118:121] offset:28672
	s_waitcnt vmcnt(8)
	ds_write_b128 v0, v[122:125] offset:61440
	v_mfma_f32_32x32x16_bf16 v[50:65], v[162:165], v[182:185], v[50:65]
	v_mfma_f32_32x32x16_bf16 v[34:49], v[162:165], v[186:189], v[34:49]
	v_mfma_f32_32x32x16_bf16 v[18:33], v[166:169], v[182:185], v[18:33]
	v_mfma_f32_32x32x16_bf16 v[2:17], v[166:169], v[186:189], v[2:17]
	v_mfma_f32_32x32x16_bf16 v[50:65], v[190:193], v[198:201], v[50:65]
	v_mfma_f32_32x32x16_bf16 v[34:49], v[190:193], v[202:205], v[34:49]
	v_mfma_f32_32x32x16_bf16 v[18:33], v[194:197], v[198:201], v[18:33]
	v_mfma_f32_32x32x16_bf16 v[2:17], v[194:197], v[202:205], v[2:17]
	ds_read_b128 v[162:165], v91
	ds_read_b128 v[166:169], v92 offset:32768
	ds_read_b128 v[182:185], v91 offset:4096
	ds_read_b128 v[186:189], v92 offset:36864
	ds_read_b128 v[190:193], v93
	ds_read_b128 v[194:197], v90 offset:32768
	ds_read_b128 v[198:201], v93 offset:4096
	ds_read_b128 v[202:205], v90 offset:36864
	s_waitcnt lgkmcnt(6)
	v_mfma_f32_32x32x16_bf16 v[50:65], v[162:165], v[166:169], v[50:65]
	s_waitcnt lgkmcnt(4)
	v_mfma_f32_32x32x16_bf16 v[34:49], v[162:165], v[186:189], v[34:49]
	v_mfma_f32_32x32x16_bf16 v[18:33], v[182:185], v[166:169], v[18:33]
	v_mfma_f32_32x32x16_bf16 v[2:17], v[182:185], v[186:189], v[2:17]
	ds_read_b128 v[162:165], v89
	ds_read_b128 v[166:169], v89 offset:4096
	ds_read_b128 v[182:185], v88 offset:32768
	ds_read_b128 v[186:189], v88 offset:36864
	s_waitcnt lgkmcnt(6)
	v_mfma_f32_32x32x16_bf16 v[50:65], v[190:193], v[194:197], v[50:65]
	s_waitcnt lgkmcnt(4)
	v_mfma_f32_32x32x16_bf16 v[34:49], v[190:193], v[202:205], v[34:49]
	v_mfma_f32_32x32x16_bf16 v[18:33], v[198:201], v[194:197], v[18:33]
	v_mfma_f32_32x32x16_bf16 v[2:17], v[198:201], v[202:205], v[2:17]
	ds_read_b128 v[190:193], v87
	ds_read_b128 v[194:197], v87 offset:4096
	ds_read_b128 v[198:201], v86 offset:32768
	ds_read_b128 v[202:205], v86 offset:36864
	s_waitcnt lgkmcnt(0)
	s_barrier
	global_load_dwordx4 v[94:97], v[66:67], off offset:640
	global_load_dwordx4 v[98:101], v[68:69], off offset:640
	global_load_dwordx4 v[102:105], v[70:71], off offset:640
	global_load_dwordx4 v[106:109], v[72:73], off offset:640
	global_load_dwordx4 v[110:113], v[74:75], off offset:640
	global_load_dwordx4 v[114:117], v[76:77], off offset:640
	global_load_dwordx4 v[118:121], v[78:79], off offset:640
	global_load_dwordx4 v[122:125], v[80:81], off offset:640
	s_waitcnt vmcnt(15)
	ds_write_b128 v0, v[126:129]
	s_waitcnt vmcnt(14)
	ds_write_b128 v0, v[134:137] offset:32768
	s_waitcnt vmcnt(13)
	ds_write_b128 v0, v[138:141] offset:4096
	s_waitcnt vmcnt(12)
	ds_write_b128 v0, v[142:145] offset:36864
	s_waitcnt vmcnt(11)
	ds_write_b128 v0, v[146:149] offset:8192
	s_waitcnt vmcnt(10)
	ds_write_b128 v0, v[150:153] offset:40960
	s_waitcnt vmcnt(9)
	ds_write_b128 v0, v[154:157] offset:12288
	s_waitcnt vmcnt(8)
	ds_write_b128 v0, v[158:161] offset:45056
	v_mfma_f32_32x32x16_bf16 v[50:65], v[162:165], v[182:185], v[50:65]
	v_mfma_f32_32x32x16_bf16 v[34:49], v[162:165], v[186:189], v[34:49]
	v_mfma_f32_32x32x16_bf16 v[18:33], v[166:169], v[182:185], v[18:33]
	v_mfma_f32_32x32x16_bf16 v[2:17], v[166:169], v[186:189], v[2:17]
	v_mfma_f32_32x32x16_bf16 v[50:65], v[190:193], v[198:201], v[50:65]
	v_mfma_f32_32x32x16_bf16 v[34:49], v[190:193], v[202:205], v[34:49]
	v_mfma_f32_32x32x16_bf16 v[18:33], v[194:197], v[198:201], v[18:33]
	v_mfma_f32_32x32x16_bf16 v[2:17], v[194:197], v[202:205], v[2:17]
	ds_read_b128 v[162:165], v91 offset:16384
	ds_read_b128 v[166:169], v92 offset:49152
	ds_read_b128 v[182:185], v91 offset:20480
	ds_read_b128 v[186:189], v92 offset:53248
	ds_read_b128 v[190:193], v93 offset:16384
	ds_read_b128 v[194:197], v90 offset:49152
	ds_read_b128 v[198:201], v93 offset:20480
	ds_read_b128 v[202:205], v90 offset:53248
	s_waitcnt lgkmcnt(6)
	v_mfma_f32_32x32x16_bf16 v[50:65], v[162:165], v[166:169], v[50:65]
	s_waitcnt lgkmcnt(4)
	v_mfma_f32_32x32x16_bf16 v[34:49], v[162:165], v[186:189], v[34:49]
	v_mfma_f32_32x32x16_bf16 v[18:33], v[182:185], v[166:169], v[18:33]
	v_mfma_f32_32x32x16_bf16 v[2:17], v[182:185], v[186:189], v[2:17]
	ds_read_b128 v[162:165], v89 offset:16384
	ds_read_b128 v[166:169], v89 offset:20480
	ds_read_b128 v[182:185], v88 offset:49152
	ds_read_b128 v[186:189], v88 offset:53248
	s_waitcnt lgkmcnt(6)
	v_mfma_f32_32x32x16_bf16 v[50:65], v[190:193], v[194:197], v[50:65]
	s_waitcnt lgkmcnt(4)
	v_mfma_f32_32x32x16_bf16 v[34:49], v[190:193], v[202:205], v[34:49]
	v_mfma_f32_32x32x16_bf16 v[18:33], v[198:201], v[194:197], v[18:33]
	v_mfma_f32_32x32x16_bf16 v[2:17], v[198:201], v[202:205], v[2:17]
	ds_read_b128 v[190:193], v87 offset:16384
	ds_read_b128 v[194:197], v87 offset:20480
	ds_read_b128 v[198:201], v86 offset:49152
	ds_read_b128 v[202:205], v86 offset:53248
	s_waitcnt lgkmcnt(0)
	s_barrier
	global_load_dwordx4 v[126:129], v[66:67], off offset:768
	global_load_dwordx4 v[134:137], v[68:69], off offset:768
	global_load_dwordx4 v[138:141], v[70:71], off offset:768
	global_load_dwordx4 v[142:145], v[72:73], off offset:768
	global_load_dwordx4 v[146:149], v[74:75], off offset:768
	global_load_dwordx4 v[150:153], v[76:77], off offset:768
	global_load_dwordx4 v[154:157], v[78:79], off offset:768
	global_load_dwordx4 v[158:161], v[80:81], off offset:768
	s_waitcnt vmcnt(15)
	ds_write_b128 v0, v[94:97] offset:16384
	s_waitcnt vmcnt(14)
	ds_write_b128 v0, v[98:101] offset:49152
	s_waitcnt vmcnt(13)
	ds_write_b128 v0, v[102:105] offset:20480
	s_waitcnt vmcnt(12)
	ds_write_b128 v0, v[106:109] offset:53248
	s_waitcnt vmcnt(11)
	ds_write_b128 v0, v[110:113] offset:24576
	s_waitcnt vmcnt(10)
	ds_write_b128 v0, v[114:117] offset:57344
	s_waitcnt vmcnt(9)
	ds_write_b128 v0, v[118:121] offset:28672
	s_waitcnt vmcnt(8)
	ds_write_b128 v0, v[122:125] offset:61440
	v_mfma_f32_32x32x16_bf16 v[50:65], v[162:165], v[182:185], v[50:65]
	v_mfma_f32_32x32x16_bf16 v[34:49], v[162:165], v[186:189], v[34:49]
	v_mfma_f32_32x32x16_bf16 v[18:33], v[166:169], v[182:185], v[18:33]
	v_mfma_f32_32x32x16_bf16 v[2:17], v[166:169], v[186:189], v[2:17]
	v_mfma_f32_32x32x16_bf16 v[50:65], v[190:193], v[198:201], v[50:65]
	v_mfma_f32_32x32x16_bf16 v[34:49], v[190:193], v[202:205], v[34:49]
	v_mfma_f32_32x32x16_bf16 v[18:33], v[194:197], v[198:201], v[18:33]
	v_mfma_f32_32x32x16_bf16 v[2:17], v[194:197], v[202:205], v[2:17]
	ds_read_b128 v[162:165], v91
	ds_read_b128 v[166:169], v92 offset:32768
	ds_read_b128 v[182:185], v91 offset:4096
	ds_read_b128 v[186:189], v92 offset:36864
	ds_read_b128 v[190:193], v93
	ds_read_b128 v[194:197], v90 offset:32768
	ds_read_b128 v[198:201], v93 offset:4096
	ds_read_b128 v[202:205], v90 offset:36864
	s_waitcnt lgkmcnt(6)
	v_mfma_f32_32x32x16_bf16 v[50:65], v[162:165], v[166:169], v[50:65]
	s_waitcnt lgkmcnt(4)
	v_mfma_f32_32x32x16_bf16 v[34:49], v[162:165], v[186:189], v[34:49]
	v_mfma_f32_32x32x16_bf16 v[18:33], v[182:185], v[166:169], v[18:33]
	v_mfma_f32_32x32x16_bf16 v[2:17], v[182:185], v[186:189], v[2:17]
	ds_read_b128 v[162:165], v89
	ds_read_b128 v[166:169], v89 offset:4096
	ds_read_b128 v[182:185], v88 offset:32768
	ds_read_b128 v[186:189], v88 offset:36864
	s_waitcnt lgkmcnt(6)
	v_mfma_f32_32x32x16_bf16 v[50:65], v[190:193], v[194:197], v[50:65]
	s_waitcnt lgkmcnt(4)
	v_mfma_f32_32x32x16_bf16 v[34:49], v[190:193], v[202:205], v[34:49]
	v_mfma_f32_32x32x16_bf16 v[18:33], v[198:201], v[194:197], v[18:33]
	v_mfma_f32_32x32x16_bf16 v[2:17], v[198:201], v[202:205], v[2:17]
	ds_read_b128 v[190:193], v87
	ds_read_b128 v[194:197], v87 offset:4096
	ds_read_b128 v[198:201], v86 offset:32768
	ds_read_b128 v[202:205], v86 offset:36864
	s_waitcnt lgkmcnt(0)
	s_barrier
	global_load_dwordx4 v[94:97], v[66:67], off offset:896
	global_load_dwordx4 v[98:101], v[68:69], off offset:896
	global_load_dwordx4 v[102:105], v[70:71], off offset:896
	global_load_dwordx4 v[106:109], v[72:73], off offset:896
	global_load_dwordx4 v[110:113], v[74:75], off offset:896
	global_load_dwordx4 v[114:117], v[76:77], off offset:896
	global_load_dwordx4 v[118:121], v[78:79], off offset:896
	global_load_dwordx4 v[122:125], v[80:81], off offset:896
	s_waitcnt vmcnt(15)
	ds_write_b128 v0, v[126:129]
	s_waitcnt vmcnt(14)
	ds_write_b128 v0, v[134:137] offset:32768
	s_waitcnt vmcnt(13)
	ds_write_b128 v0, v[138:141] offset:4096
	s_waitcnt vmcnt(12)
	ds_write_b128 v0, v[142:145] offset:36864
	s_waitcnt vmcnt(11)
	ds_write_b128 v0, v[146:149] offset:8192
	s_waitcnt vmcnt(10)
	ds_write_b128 v0, v[150:153] offset:40960
	s_waitcnt vmcnt(9)
	ds_write_b128 v0, v[154:157] offset:12288
	s_waitcnt vmcnt(8)
	ds_write_b128 v0, v[158:161] offset:45056
	v_mfma_f32_32x32x16_bf16 v[50:65], v[162:165], v[182:185], v[50:65]
	v_mfma_f32_32x32x16_bf16 v[34:49], v[162:165], v[186:189], v[34:49]
	v_mfma_f32_32x32x16_bf16 v[18:33], v[166:169], v[182:185], v[18:33]
	v_mfma_f32_32x32x16_bf16 v[2:17], v[166:169], v[186:189], v[2:17]
	v_mfma_f32_32x32x16_bf16 v[50:65], v[190:193], v[198:201], v[50:65]
	v_mfma_f32_32x32x16_bf16 v[34:49], v[190:193], v[202:205], v[34:49]
	v_mfma_f32_32x32x16_bf16 v[18:33], v[194:197], v[198:201], v[18:33]
	v_mfma_f32_32x32x16_bf16 v[2:17], v[194:197], v[202:205], v[2:17]
	ds_read_b128 v[162:165], v91 offset:16384
	ds_read_b128 v[166:169], v92 offset:49152
	ds_read_b128 v[182:185], v91 offset:20480
	ds_read_b128 v[186:189], v92 offset:53248
	ds_read_b128 v[190:193], v93 offset:16384
	ds_read_b128 v[194:197], v90 offset:49152
	ds_read_b128 v[198:201], v93 offset:20480
	ds_read_b128 v[202:205], v90 offset:53248
	s_waitcnt lgkmcnt(6)
	v_mfma_f32_32x32x16_bf16 v[50:65], v[162:165], v[166:169], v[50:65]
	s_waitcnt lgkmcnt(4)
	v_mfma_f32_32x32x16_bf16 v[34:49], v[162:165], v[186:189], v[34:49]
	v_mfma_f32_32x32x16_bf16 v[18:33], v[182:185], v[166:169], v[18:33]
	v_mfma_f32_32x32x16_bf16 v[2:17], v[182:185], v[186:189], v[2:17]
	ds_read_b128 v[162:165], v89 offset:16384
	ds_read_b128 v[166:169], v89 offset:20480
	ds_read_b128 v[182:185], v88 offset:49152
	ds_read_b128 v[186:189], v88 offset:53248
	s_waitcnt lgkmcnt(6)
	v_mfma_f32_32x32x16_bf16 v[50:65], v[190:193], v[194:197], v[50:65]
	s_waitcnt lgkmcnt(4)
	v_mfma_f32_32x32x16_bf16 v[34:49], v[190:193], v[202:205], v[34:49]
	v_mfma_f32_32x32x16_bf16 v[18:33], v[198:201], v[194:197], v[18:33]
	v_mfma_f32_32x32x16_bf16 v[2:17], v[198:201], v[202:205], v[2:17]
	ds_read_b128 v[190:193], v87 offset:16384
	ds_read_b128 v[194:197], v87 offset:20480
	ds_read_b128 v[198:201], v86 offset:49152
	ds_read_b128 v[202:205], v86 offset:53248
	s_waitcnt lgkmcnt(0)
	s_barrier
	global_load_dwordx4 v[126:129], v[66:67], off offset:1024
	global_load_dwordx4 v[134:137], v[68:69], off offset:1024
	global_load_dwordx4 v[138:141], v[70:71], off offset:1024
	global_load_dwordx4 v[142:145], v[72:73], off offset:1024
	global_load_dwordx4 v[146:149], v[74:75], off offset:1024
	global_load_dwordx4 v[150:153], v[76:77], off offset:1024
	global_load_dwordx4 v[154:157], v[78:79], off offset:1024
	global_load_dwordx4 v[158:161], v[80:81], off offset:1024
	s_waitcnt vmcnt(15)
	ds_write_b128 v0, v[94:97] offset:16384
	s_waitcnt vmcnt(14)
	ds_write_b128 v0, v[98:101] offset:49152
	s_waitcnt vmcnt(13)
	ds_write_b128 v0, v[102:105] offset:20480
	s_waitcnt vmcnt(12)
	ds_write_b128 v0, v[106:109] offset:53248
	s_waitcnt vmcnt(11)
	ds_write_b128 v0, v[110:113] offset:24576
	s_waitcnt vmcnt(10)
	ds_write_b128 v0, v[114:117] offset:57344
	s_waitcnt vmcnt(9)
	ds_write_b128 v0, v[118:121] offset:28672
	s_waitcnt vmcnt(8)
	ds_write_b128 v0, v[122:125] offset:61440
	v_mfma_f32_32x32x16_bf16 v[50:65], v[162:165], v[182:185], v[50:65]
	v_mfma_f32_32x32x16_bf16 v[34:49], v[162:165], v[186:189], v[34:49]
	v_mfma_f32_32x32x16_bf16 v[18:33], v[166:169], v[182:185], v[18:33]
	v_mfma_f32_32x32x16_bf16 v[2:17], v[166:169], v[186:189], v[2:17]
	v_mfma_f32_32x32x16_bf16 v[50:65], v[190:193], v[198:201], v[50:65]
	v_mfma_f32_32x32x16_bf16 v[34:49], v[190:193], v[202:205], v[34:49]
	v_mfma_f32_32x32x16_bf16 v[18:33], v[194:197], v[198:201], v[18:33]
	v_mfma_f32_32x32x16_bf16 v[2:17], v[194:197], v[202:205], v[2:17]
	ds_read_b128 v[162:165], v91
	ds_read_b128 v[166:169], v92 offset:32768
	ds_read_b128 v[182:185], v91 offset:4096
	ds_read_b128 v[186:189], v92 offset:36864
	ds_read_b128 v[190:193], v93
	ds_read_b128 v[194:197], v90 offset:32768
	ds_read_b128 v[198:201], v93 offset:4096
	ds_read_b128 v[202:205], v90 offset:36864
	s_waitcnt lgkmcnt(6)
	v_mfma_f32_32x32x16_bf16 v[50:65], v[162:165], v[166:169], v[50:65]
	s_waitcnt lgkmcnt(4)
	v_mfma_f32_32x32x16_bf16 v[34:49], v[162:165], v[186:189], v[34:49]
	v_mfma_f32_32x32x16_bf16 v[18:33], v[182:185], v[166:169], v[18:33]
	v_mfma_f32_32x32x16_bf16 v[2:17], v[182:185], v[186:189], v[2:17]
	ds_read_b128 v[162:165], v89
	ds_read_b128 v[166:169], v89 offset:4096
	ds_read_b128 v[182:185], v88 offset:32768
	ds_read_b128 v[186:189], v88 offset:36864
	s_waitcnt lgkmcnt(6)
	v_mfma_f32_32x32x16_bf16 v[50:65], v[190:193], v[194:197], v[50:65]
	s_waitcnt lgkmcnt(4)
	v_mfma_f32_32x32x16_bf16 v[34:49], v[190:193], v[202:205], v[34:49]
	v_mfma_f32_32x32x16_bf16 v[18:33], v[198:201], v[194:197], v[18:33]
	v_mfma_f32_32x32x16_bf16 v[2:17], v[198:201], v[202:205], v[2:17]
	ds_read_b128 v[190:193], v87
	ds_read_b128 v[194:197], v87 offset:4096
	ds_read_b128 v[198:201], v86 offset:32768
	ds_read_b128 v[202:205], v86 offset:36864
	s_waitcnt lgkmcnt(0)
	s_barrier
	global_load_dwordx4 v[94:97], v[66:67], off offset:1152
	global_load_dwordx4 v[98:101], v[68:69], off offset:1152
	global_load_dwordx4 v[102:105], v[70:71], off offset:1152
	global_load_dwordx4 v[106:109], v[72:73], off offset:1152
	global_load_dwordx4 v[110:113], v[74:75], off offset:1152
	global_load_dwordx4 v[114:117], v[76:77], off offset:1152
	global_load_dwordx4 v[118:121], v[78:79], off offset:1152
	global_load_dwordx4 v[122:125], v[80:81], off offset:1152
	s_waitcnt vmcnt(15)
	ds_write_b128 v0, v[126:129]
	s_waitcnt vmcnt(14)
	ds_write_b128 v0, v[134:137] offset:32768
	s_waitcnt vmcnt(13)
	ds_write_b128 v0, v[138:141] offset:4096
	s_waitcnt vmcnt(12)
	ds_write_b128 v0, v[142:145] offset:36864
	s_waitcnt vmcnt(11)
	ds_write_b128 v0, v[146:149] offset:8192
	s_waitcnt vmcnt(10)
	ds_write_b128 v0, v[150:153] offset:40960
	s_waitcnt vmcnt(9)
	ds_write_b128 v0, v[154:157] offset:12288
	s_waitcnt vmcnt(8)
	ds_write_b128 v0, v[158:161] offset:45056
	v_mfma_f32_32x32x16_bf16 v[50:65], v[162:165], v[182:185], v[50:65]
	v_mfma_f32_32x32x16_bf16 v[34:49], v[162:165], v[186:189], v[34:49]
	v_mfma_f32_32x32x16_bf16 v[18:33], v[166:169], v[182:185], v[18:33]
	v_mfma_f32_32x32x16_bf16 v[2:17], v[166:169], v[186:189], v[2:17]
	v_mfma_f32_32x32x16_bf16 v[50:65], v[190:193], v[198:201], v[50:65]
	v_mfma_f32_32x32x16_bf16 v[34:49], v[190:193], v[202:205], v[34:49]
	v_mfma_f32_32x32x16_bf16 v[18:33], v[194:197], v[198:201], v[18:33]
	v_mfma_f32_32x32x16_bf16 v[2:17], v[194:197], v[202:205], v[2:17]
	ds_read_b128 v[162:165], v91 offset:16384
	ds_read_b128 v[166:169], v92 offset:49152
	ds_read_b128 v[182:185], v91 offset:20480
	ds_read_b128 v[186:189], v92 offset:53248
	ds_read_b128 v[190:193], v93 offset:16384
	ds_read_b128 v[194:197], v90 offset:49152
	ds_read_b128 v[198:201], v93 offset:20480
	ds_read_b128 v[202:205], v90 offset:53248
	s_waitcnt lgkmcnt(6)
	v_mfma_f32_32x32x16_bf16 v[50:65], v[162:165], v[166:169], v[50:65]
	s_waitcnt lgkmcnt(4)
	v_mfma_f32_32x32x16_bf16 v[34:49], v[162:165], v[186:189], v[34:49]
	v_mfma_f32_32x32x16_bf16 v[18:33], v[182:185], v[166:169], v[18:33]
	v_mfma_f32_32x32x16_bf16 v[2:17], v[182:185], v[186:189], v[2:17]
	ds_read_b128 v[162:165], v89 offset:16384
	ds_read_b128 v[166:169], v89 offset:20480
	ds_read_b128 v[182:185], v88 offset:49152
	ds_read_b128 v[186:189], v88 offset:53248
	s_waitcnt lgkmcnt(6)
	v_mfma_f32_32x32x16_bf16 v[50:65], v[190:193], v[194:197], v[50:65]
	s_waitcnt lgkmcnt(4)
	v_mfma_f32_32x32x16_bf16 v[34:49], v[190:193], v[202:205], v[34:49]
	v_mfma_f32_32x32x16_bf16 v[18:33], v[198:201], v[194:197], v[18:33]
	v_mfma_f32_32x32x16_bf16 v[2:17], v[198:201], v[202:205], v[2:17]
	ds_read_b128 v[190:193], v87 offset:16384
	ds_read_b128 v[194:197], v87 offset:20480
	ds_read_b128 v[198:201], v86 offset:49152
	ds_read_b128 v[202:205], v86 offset:53248
	s_waitcnt lgkmcnt(0)
	s_barrier
	global_load_dwordx4 v[126:129], v[66:67], off offset:1280
	global_load_dwordx4 v[134:137], v[68:69], off offset:1280
	global_load_dwordx4 v[138:141], v[70:71], off offset:1280
	global_load_dwordx4 v[142:145], v[72:73], off offset:1280
	global_load_dwordx4 v[146:149], v[74:75], off offset:1280
	global_load_dwordx4 v[150:153], v[76:77], off offset:1280
	global_load_dwordx4 v[154:157], v[78:79], off offset:1280
	global_load_dwordx4 v[158:161], v[80:81], off offset:1280
	s_waitcnt vmcnt(15)
	ds_write_b128 v0, v[94:97] offset:16384
	s_waitcnt vmcnt(14)
	ds_write_b128 v0, v[98:101] offset:49152
	s_waitcnt vmcnt(13)
	ds_write_b128 v0, v[102:105] offset:20480
	s_waitcnt vmcnt(12)
	ds_write_b128 v0, v[106:109] offset:53248
	s_waitcnt vmcnt(11)
	ds_write_b128 v0, v[110:113] offset:24576
	s_waitcnt vmcnt(10)
	ds_write_b128 v0, v[114:117] offset:57344
	s_waitcnt vmcnt(9)
	ds_write_b128 v0, v[118:121] offset:28672
	s_waitcnt vmcnt(8)
	ds_write_b128 v0, v[122:125] offset:61440
	v_mfma_f32_32x32x16_bf16 v[50:65], v[162:165], v[182:185], v[50:65]
	v_mfma_f32_32x32x16_bf16 v[34:49], v[162:165], v[186:189], v[34:49]
	v_mfma_f32_32x32x16_bf16 v[18:33], v[166:169], v[182:185], v[18:33]
	v_mfma_f32_32x32x16_bf16 v[2:17], v[166:169], v[186:189], v[2:17]
	v_mfma_f32_32x32x16_bf16 v[50:65], v[190:193], v[198:201], v[50:65]
	v_mfma_f32_32x32x16_bf16 v[34:49], v[190:193], v[202:205], v[34:49]
	v_mfma_f32_32x32x16_bf16 v[18:33], v[194:197], v[198:201], v[18:33]
	v_mfma_f32_32x32x16_bf16 v[2:17], v[194:197], v[202:205], v[2:17]
	ds_read_b128 v[162:165], v91
	ds_read_b128 v[166:169], v92 offset:32768
	ds_read_b128 v[182:185], v91 offset:4096
	ds_read_b128 v[186:189], v92 offset:36864
	ds_read_b128 v[190:193], v93
	ds_read_b128 v[194:197], v90 offset:32768
	ds_read_b128 v[198:201], v93 offset:4096
	ds_read_b128 v[202:205], v90 offset:36864
	s_waitcnt lgkmcnt(6)
	v_mfma_f32_32x32x16_bf16 v[50:65], v[162:165], v[166:169], v[50:65]
	s_waitcnt lgkmcnt(4)
	v_mfma_f32_32x32x16_bf16 v[34:49], v[162:165], v[186:189], v[34:49]
	v_mfma_f32_32x32x16_bf16 v[18:33], v[182:185], v[166:169], v[18:33]
	v_mfma_f32_32x32x16_bf16 v[2:17], v[182:185], v[186:189], v[2:17]
	ds_read_b128 v[162:165], v89
	ds_read_b128 v[166:169], v89 offset:4096
	ds_read_b128 v[182:185], v88 offset:32768
	ds_read_b128 v[186:189], v88 offset:36864
	s_waitcnt lgkmcnt(6)
	v_mfma_f32_32x32x16_bf16 v[50:65], v[190:193], v[194:197], v[50:65]
	s_waitcnt lgkmcnt(4)
	v_mfma_f32_32x32x16_bf16 v[34:49], v[190:193], v[202:205], v[34:49]
	v_mfma_f32_32x32x16_bf16 v[18:33], v[198:201], v[194:197], v[18:33]
	v_mfma_f32_32x32x16_bf16 v[2:17], v[198:201], v[202:205], v[2:17]
	ds_read_b128 v[190:193], v87
	ds_read_b128 v[194:197], v87 offset:4096
	ds_read_b128 v[198:201], v86 offset:32768
	ds_read_b128 v[202:205], v86 offset:36864
	s_waitcnt lgkmcnt(0)
	s_barrier
	global_load_dwordx4 v[94:97], v[66:67], off offset:1408
	global_load_dwordx4 v[98:101], v[68:69], off offset:1408
	global_load_dwordx4 v[102:105], v[70:71], off offset:1408
	global_load_dwordx4 v[106:109], v[72:73], off offset:1408
	global_load_dwordx4 v[110:113], v[74:75], off offset:1408
	global_load_dwordx4 v[114:117], v[76:77], off offset:1408
	global_load_dwordx4 v[118:121], v[78:79], off offset:1408
	global_load_dwordx4 v[122:125], v[80:81], off offset:1408
	s_waitcnt vmcnt(15)
	ds_write_b128 v0, v[126:129]
	s_waitcnt vmcnt(14)
	ds_write_b128 v0, v[134:137] offset:32768
	s_waitcnt vmcnt(13)
	ds_write_b128 v0, v[138:141] offset:4096
	s_waitcnt vmcnt(12)
	ds_write_b128 v0, v[142:145] offset:36864
	s_waitcnt vmcnt(11)
	ds_write_b128 v0, v[146:149] offset:8192
	s_waitcnt vmcnt(10)
	ds_write_b128 v0, v[150:153] offset:40960
	s_waitcnt vmcnt(9)
	ds_write_b128 v0, v[154:157] offset:12288
	s_waitcnt vmcnt(8)
	ds_write_b128 v0, v[158:161] offset:45056
	v_mfma_f32_32x32x16_bf16 v[50:65], v[162:165], v[182:185], v[50:65]
	v_mfma_f32_32x32x16_bf16 v[34:49], v[162:165], v[186:189], v[34:49]
	v_mfma_f32_32x32x16_bf16 v[18:33], v[166:169], v[182:185], v[18:33]
	v_mfma_f32_32x32x16_bf16 v[2:17], v[166:169], v[186:189], v[2:17]
	v_mfma_f32_32x32x16_bf16 v[50:65], v[190:193], v[198:201], v[50:65]
	v_mfma_f32_32x32x16_bf16 v[34:49], v[190:193], v[202:205], v[34:49]
	v_mfma_f32_32x32x16_bf16 v[18:33], v[194:197], v[198:201], v[18:33]
	v_mfma_f32_32x32x16_bf16 v[2:17], v[194:197], v[202:205], v[2:17]
	ds_read_b128 v[162:165], v91 offset:16384
	ds_read_b128 v[166:169], v92 offset:49152
	ds_read_b128 v[182:185], v91 offset:20480
	ds_read_b128 v[186:189], v92 offset:53248
	ds_read_b128 v[190:193], v93 offset:16384
	ds_read_b128 v[194:197], v90 offset:49152
	ds_read_b128 v[198:201], v93 offset:20480
	ds_read_b128 v[202:205], v90 offset:53248
	s_waitcnt lgkmcnt(6)
	v_mfma_f32_32x32x16_bf16 v[50:65], v[162:165], v[166:169], v[50:65]
	s_waitcnt lgkmcnt(4)
	v_mfma_f32_32x32x16_bf16 v[34:49], v[162:165], v[186:189], v[34:49]
	v_mfma_f32_32x32x16_bf16 v[18:33], v[182:185], v[166:169], v[18:33]
	v_mfma_f32_32x32x16_bf16 v[2:17], v[182:185], v[186:189], v[2:17]
	ds_read_b128 v[162:165], v89 offset:16384
	ds_read_b128 v[166:169], v89 offset:20480
	ds_read_b128 v[182:185], v88 offset:49152
	ds_read_b128 v[186:189], v88 offset:53248
	s_waitcnt lgkmcnt(6)
	v_mfma_f32_32x32x16_bf16 v[50:65], v[190:193], v[194:197], v[50:65]
	s_waitcnt lgkmcnt(4)
	v_mfma_f32_32x32x16_bf16 v[34:49], v[190:193], v[202:205], v[34:49]
	v_mfma_f32_32x32x16_bf16 v[18:33], v[198:201], v[194:197], v[18:33]
	v_mfma_f32_32x32x16_bf16 v[2:17], v[198:201], v[202:205], v[2:17]
	ds_read_b128 v[190:193], v87 offset:16384
	ds_read_b128 v[194:197], v87 offset:20480
	ds_read_b128 v[198:201], v86 offset:49152
	ds_read_b128 v[202:205], v86 offset:53248
	s_waitcnt lgkmcnt(0)
	s_barrier
	global_load_dwordx4 v[126:129], v[66:67], off offset:1536
	global_load_dwordx4 v[134:137], v[68:69], off offset:1536
	global_load_dwordx4 v[138:141], v[70:71], off offset:1536
	global_load_dwordx4 v[142:145], v[72:73], off offset:1536
	global_load_dwordx4 v[146:149], v[74:75], off offset:1536
	global_load_dwordx4 v[150:153], v[76:77], off offset:1536
	global_load_dwordx4 v[154:157], v[78:79], off offset:1536
	global_load_dwordx4 v[158:161], v[80:81], off offset:1536
	s_waitcnt vmcnt(15)
	ds_write_b128 v0, v[94:97] offset:16384
	s_waitcnt vmcnt(14)
	ds_write_b128 v0, v[98:101] offset:49152
	s_waitcnt vmcnt(13)
	ds_write_b128 v0, v[102:105] offset:20480
	s_waitcnt vmcnt(12)
	ds_write_b128 v0, v[106:109] offset:53248
	s_waitcnt vmcnt(11)
	ds_write_b128 v0, v[110:113] offset:24576
	s_waitcnt vmcnt(10)
	ds_write_b128 v0, v[114:117] offset:57344
	s_waitcnt vmcnt(9)
	ds_write_b128 v0, v[118:121] offset:28672
	s_waitcnt vmcnt(8)
	ds_write_b128 v0, v[122:125] offset:61440
	v_mfma_f32_32x32x16_bf16 v[50:65], v[162:165], v[182:185], v[50:65]
	v_mfma_f32_32x32x16_bf16 v[34:49], v[162:165], v[186:189], v[34:49]
	v_mfma_f32_32x32x16_bf16 v[18:33], v[166:169], v[182:185], v[18:33]
	v_mfma_f32_32x32x16_bf16 v[2:17], v[166:169], v[186:189], v[2:17]
	v_mfma_f32_32x32x16_bf16 v[50:65], v[190:193], v[198:201], v[50:65]
	v_mfma_f32_32x32x16_bf16 v[34:49], v[190:193], v[202:205], v[34:49]
	v_mfma_f32_32x32x16_bf16 v[18:33], v[194:197], v[198:201], v[18:33]
	v_mfma_f32_32x32x16_bf16 v[2:17], v[194:197], v[202:205], v[2:17]
	ds_read_b128 v[162:165], v91
	ds_read_b128 v[166:169], v92 offset:32768
	ds_read_b128 v[182:185], v91 offset:4096
	ds_read_b128 v[186:189], v92 offset:36864
	ds_read_b128 v[190:193], v93
	ds_read_b128 v[194:197], v90 offset:32768
	ds_read_b128 v[198:201], v93 offset:4096
	ds_read_b128 v[202:205], v90 offset:36864
	s_waitcnt lgkmcnt(6)
	v_mfma_f32_32x32x16_bf16 v[50:65], v[162:165], v[166:169], v[50:65]
	s_waitcnt lgkmcnt(4)
	v_mfma_f32_32x32x16_bf16 v[34:49], v[162:165], v[186:189], v[34:49]
	v_mfma_f32_32x32x16_bf16 v[18:33], v[182:185], v[166:169], v[18:33]
	v_mfma_f32_32x32x16_bf16 v[2:17], v[182:185], v[186:189], v[2:17]
	ds_read_b128 v[162:165], v89
	ds_read_b128 v[166:169], v89 offset:4096
	ds_read_b128 v[182:185], v88 offset:32768
	ds_read_b128 v[186:189], v88 offset:36864
	s_waitcnt lgkmcnt(6)
	v_mfma_f32_32x32x16_bf16 v[50:65], v[190:193], v[194:197], v[50:65]
	s_waitcnt lgkmcnt(4)
	v_mfma_f32_32x32x16_bf16 v[34:49], v[190:193], v[202:205], v[34:49]
	v_mfma_f32_32x32x16_bf16 v[18:33], v[198:201], v[194:197], v[18:33]
	v_mfma_f32_32x32x16_bf16 v[2:17], v[198:201], v[202:205], v[2:17]
	ds_read_b128 v[190:193], v87
	ds_read_b128 v[194:197], v87 offset:4096
	ds_read_b128 v[198:201], v86 offset:32768
	ds_read_b128 v[202:205], v86 offset:36864
	s_waitcnt lgkmcnt(0)
	s_barrier
	global_load_dwordx4 v[94:97], v[66:67], off offset:1664
	global_load_dwordx4 v[98:101], v[68:69], off offset:1664
	global_load_dwordx4 v[102:105], v[70:71], off offset:1664
	global_load_dwordx4 v[106:109], v[72:73], off offset:1664
	global_load_dwordx4 v[110:113], v[74:75], off offset:1664
	global_load_dwordx4 v[114:117], v[76:77], off offset:1664
	global_load_dwordx4 v[118:121], v[78:79], off offset:1664
	global_load_dwordx4 v[122:125], v[80:81], off offset:1664
	s_waitcnt vmcnt(15)
	ds_write_b128 v0, v[126:129]
	s_waitcnt vmcnt(14)
	ds_write_b128 v0, v[134:137] offset:32768
	s_waitcnt vmcnt(13)
	ds_write_b128 v0, v[138:141] offset:4096
	s_waitcnt vmcnt(12)
	ds_write_b128 v0, v[142:145] offset:36864
	s_waitcnt vmcnt(11)
	ds_write_b128 v0, v[146:149] offset:8192
	s_waitcnt vmcnt(10)
	ds_write_b128 v0, v[150:153] offset:40960
	s_waitcnt vmcnt(9)
	ds_write_b128 v0, v[154:157] offset:12288
	s_waitcnt vmcnt(8)
	ds_write_b128 v0, v[158:161] offset:45056
	v_mfma_f32_32x32x16_bf16 v[50:65], v[162:165], v[182:185], v[50:65]
	v_mfma_f32_32x32x16_bf16 v[34:49], v[162:165], v[186:189], v[34:49]
	v_mfma_f32_32x32x16_bf16 v[18:33], v[166:169], v[182:185], v[18:33]
	v_mfma_f32_32x32x16_bf16 v[2:17], v[166:169], v[186:189], v[2:17]
	v_mfma_f32_32x32x16_bf16 v[50:65], v[190:193], v[198:201], v[50:65]
	v_mfma_f32_32x32x16_bf16 v[34:49], v[190:193], v[202:205], v[34:49]
	v_mfma_f32_32x32x16_bf16 v[18:33], v[194:197], v[198:201], v[18:33]
	v_mfma_f32_32x32x16_bf16 v[2:17], v[194:197], v[202:205], v[2:17]
	ds_read_b128 v[162:165], v91 offset:16384
	ds_read_b128 v[166:169], v92 offset:49152
	ds_read_b128 v[182:185], v91 offset:20480
	ds_read_b128 v[186:189], v92 offset:53248
	ds_read_b128 v[190:193], v93 offset:16384
	ds_read_b128 v[194:197], v90 offset:49152
	ds_read_b128 v[198:201], v93 offset:20480
	ds_read_b128 v[202:205], v90 offset:53248
	s_waitcnt lgkmcnt(6)
	v_mfma_f32_32x32x16_bf16 v[50:65], v[162:165], v[166:169], v[50:65]
	s_waitcnt lgkmcnt(4)
	v_mfma_f32_32x32x16_bf16 v[34:49], v[162:165], v[186:189], v[34:49]
	v_mfma_f32_32x32x16_bf16 v[18:33], v[182:185], v[166:169], v[18:33]
	v_mfma_f32_32x32x16_bf16 v[2:17], v[182:185], v[186:189], v[2:17]
	ds_read_b128 v[162:165], v89 offset:16384
	ds_read_b128 v[166:169], v89 offset:20480
	ds_read_b128 v[182:185], v88 offset:49152
	ds_read_b128 v[186:189], v88 offset:53248
	s_waitcnt lgkmcnt(6)
	v_mfma_f32_32x32x16_bf16 v[50:65], v[190:193], v[194:197], v[50:65]
	s_waitcnt lgkmcnt(4)
	v_mfma_f32_32x32x16_bf16 v[34:49], v[190:193], v[202:205], v[34:49]
	v_mfma_f32_32x32x16_bf16 v[18:33], v[198:201], v[194:197], v[18:33]
	v_mfma_f32_32x32x16_bf16 v[2:17], v[198:201], v[202:205], v[2:17]
	ds_read_b128 v[190:193], v87 offset:16384
	ds_read_b128 v[194:197], v87 offset:20480
	ds_read_b128 v[198:201], v86 offset:49152
	ds_read_b128 v[202:205], v86 offset:53248
	s_waitcnt lgkmcnt(0)
	s_barrier
	global_load_dwordx4 v[126:129], v[66:67], off offset:1792
	global_load_dwordx4 v[134:137], v[68:69], off offset:1792
	global_load_dwordx4 v[138:141], v[70:71], off offset:1792
	global_load_dwordx4 v[142:145], v[72:73], off offset:1792
	global_load_dwordx4 v[146:149], v[74:75], off offset:1792
	global_load_dwordx4 v[150:153], v[76:77], off offset:1792
	global_load_dwordx4 v[154:157], v[78:79], off offset:1792
	global_load_dwordx4 v[158:161], v[80:81], off offset:1792
	s_waitcnt vmcnt(15)
	ds_write_b128 v0, v[94:97] offset:16384
	s_waitcnt vmcnt(14)
	ds_write_b128 v0, v[98:101] offset:49152
	s_waitcnt vmcnt(13)
	ds_write_b128 v0, v[102:105] offset:20480
	s_waitcnt vmcnt(12)
	ds_write_b128 v0, v[106:109] offset:53248
	s_waitcnt vmcnt(11)
	ds_write_b128 v0, v[110:113] offset:24576
	s_waitcnt vmcnt(10)
	ds_write_b128 v0, v[114:117] offset:57344
	s_waitcnt vmcnt(9)
	ds_write_b128 v0, v[118:121] offset:28672
	s_waitcnt vmcnt(8)
	ds_write_b128 v0, v[122:125] offset:61440
	v_mfma_f32_32x32x16_bf16 v[50:65], v[162:165], v[182:185], v[50:65]
	v_mfma_f32_32x32x16_bf16 v[34:49], v[162:165], v[186:189], v[34:49]
	v_mfma_f32_32x32x16_bf16 v[18:33], v[166:169], v[182:185], v[18:33]
	v_mfma_f32_32x32x16_bf16 v[2:17], v[166:169], v[186:189], v[2:17]
	v_mfma_f32_32x32x16_bf16 v[50:65], v[190:193], v[198:201], v[50:65]
	v_mfma_f32_32x32x16_bf16 v[34:49], v[190:193], v[202:205], v[34:49]
	v_mfma_f32_32x32x16_bf16 v[18:33], v[194:197], v[198:201], v[18:33]
	v_mfma_f32_32x32x16_bf16 v[2:17], v[194:197], v[202:205], v[2:17]
	ds_read_b128 v[162:165], v91
	ds_read_b128 v[166:169], v92 offset:32768
	ds_read_b128 v[182:185], v91 offset:4096
	ds_read_b128 v[186:189], v92 offset:36864
	ds_read_b128 v[190:193], v93
	ds_read_b128 v[194:197], v90 offset:32768
	ds_read_b128 v[198:201], v93 offset:4096
	ds_read_b128 v[202:205], v90 offset:36864
	s_waitcnt lgkmcnt(6)
	v_mfma_f32_32x32x16_bf16 v[50:65], v[162:165], v[166:169], v[50:65]
	s_waitcnt lgkmcnt(4)
	v_mfma_f32_32x32x16_bf16 v[34:49], v[162:165], v[186:189], v[34:49]
	v_mfma_f32_32x32x16_bf16 v[18:33], v[182:185], v[166:169], v[18:33]
	v_mfma_f32_32x32x16_bf16 v[2:17], v[182:185], v[186:189], v[2:17]
	ds_read_b128 v[162:165], v89
	ds_read_b128 v[166:169], v89 offset:4096
	ds_read_b128 v[182:185], v88 offset:32768
	ds_read_b128 v[186:189], v88 offset:36864
	s_waitcnt lgkmcnt(6)
	v_mfma_f32_32x32x16_bf16 v[50:65], v[190:193], v[194:197], v[50:65]
	s_waitcnt lgkmcnt(4)
	v_mfma_f32_32x32x16_bf16 v[34:49], v[190:193], v[202:205], v[34:49]
	v_mfma_f32_32x32x16_bf16 v[18:33], v[198:201], v[194:197], v[18:33]
	v_mfma_f32_32x32x16_bf16 v[2:17], v[198:201], v[202:205], v[2:17]
	ds_read_b128 v[190:193], v87
	ds_read_b128 v[194:197], v87 offset:4096
	ds_read_b128 v[198:201], v86 offset:32768
	ds_read_b128 v[202:205], v86 offset:36864
	s_waitcnt lgkmcnt(0)
	s_barrier
	global_load_dwordx4 v[94:97], v[66:67], off offset:1920
	s_nop 0
	global_load_dwordx4 v[66:69], v[68:69], off offset:1920
	s_nop 0
	global_load_dwordx4 v[98:101], v[70:71], off offset:1920
	s_nop 0
	global_load_dwordx4 v[70:73], v[72:73], off offset:1920
	s_nop 0
	global_load_dwordx4 v[102:105], v[74:75], off offset:1920
	s_nop 0
	global_load_dwordx4 v[74:77], v[76:77], off offset:1920
	s_nop 0
	global_load_dwordx4 v[106:109], v[78:79], off offset:1920
	s_nop 0
	global_load_dwordx4 v[78:81], v[80:81], off offset:1920
	s_waitcnt vmcnt(15)
	ds_write_b128 v0, v[126:129]
	s_waitcnt vmcnt(14)
	ds_write_b128 v0, v[134:137] offset:32768
	s_waitcnt vmcnt(13)
	ds_write_b128 v0, v[138:141] offset:4096
	s_waitcnt vmcnt(12)
	ds_write_b128 v0, v[142:145] offset:36864
	s_waitcnt vmcnt(11)
	ds_write_b128 v0, v[146:149] offset:8192
	s_waitcnt vmcnt(10)
	ds_write_b128 v0, v[150:153] offset:40960
	s_waitcnt vmcnt(9)
	ds_write_b128 v0, v[154:157] offset:12288
	s_waitcnt vmcnt(8)
	ds_write_b128 v0, v[158:161] offset:45056
	v_mfma_f32_32x32x16_bf16 v[50:65], v[162:165], v[182:185], v[50:65]
	v_mfma_f32_32x32x16_bf16 v[34:49], v[162:165], v[186:189], v[34:49]
	v_mfma_f32_32x32x16_bf16 v[18:33], v[166:169], v[182:185], v[18:33]
	v_mfma_f32_32x32x16_bf16 v[2:17], v[166:169], v[186:189], v[2:17]
	ds_read_b128 v[110:113], v91 offset:16384
	ds_read_b128 v[114:117], v91 offset:20480
	ds_read_b128 v[118:121], v92 offset:49152
	ds_read_b128 v[122:125], v92 offset:53248
	ds_read_b128 v[162:165], v93 offset:16384
	ds_read_b128 v[166:169], v93 offset:20480
	ds_read_b128 v[182:185], v90 offset:49152
	ds_read_b128 v[186:189], v90 offset:53248
	v_mfma_f32_32x32x16_bf16 v[50:65], v[190:193], v[198:201], v[50:65]
	v_mfma_f32_32x32x16_bf16 v[34:49], v[190:193], v[202:205], v[34:49]
	v_mfma_f32_32x32x16_bf16 v[18:33], v[194:197], v[198:201], v[18:33]
	v_mfma_f32_32x32x16_bf16 v[2:17], v[194:197], v[202:205], v[2:17]
	s_waitcnt lgkmcnt(5)
	v_mfma_f32_32x32x16_bf16 v[50:65], v[110:113], v[118:121], v[50:65]
	s_waitcnt lgkmcnt(4)
	v_mfma_f32_32x32x16_bf16 v[34:49], v[110:113], v[122:125], v[34:49]
	v_mfma_f32_32x32x16_bf16 v[18:33], v[114:117], v[118:121], v[18:33]
	v_mfma_f32_32x32x16_bf16 v[2:17], v[114:117], v[122:125], v[2:17]
	ds_read_b128 v[110:113], v89 offset:16384
	ds_read_b128 v[114:117], v89 offset:20480
	ds_read_b128 v[118:121], v88 offset:49152
	ds_read_b128 v[122:125], v88 offset:53248
	s_waitcnt lgkmcnt(5)
	v_mfma_f32_32x32x16_bf16 v[50:65], v[162:165], v[182:185], v[50:65]
	s_waitcnt lgkmcnt(4)
	v_mfma_f32_32x32x16_bf16 v[34:49], v[162:165], v[186:189], v[34:49]
	v_mfma_f32_32x32x16_bf16 v[18:33], v[166:169], v[182:185], v[18:33]
	v_mfma_f32_32x32x16_bf16 v[2:17], v[166:169], v[186:189], v[2:17]
	ds_read_b128 v[162:165], v87 offset:16384
	ds_read_b128 v[166:169], v87 offset:20480
	ds_read_b128 v[182:185], v86 offset:49152
	ds_read_b128 v[186:189], v86 offset:53248
	s_waitcnt lgkmcnt(5)
	v_mfma_f32_32x32x16_bf16 v[50:65], v[110:113], v[118:121], v[50:65]
	s_waitcnt lgkmcnt(0)
	s_barrier
	s_waitcnt vmcnt(7)
	ds_write_b128 v0, v[94:97] offset:16384
	s_waitcnt vmcnt(6)
	ds_write_b128 v0, v[66:69] offset:49152
	s_waitcnt vmcnt(5)
	ds_write_b128 v0, v[98:101] offset:20480
	s_waitcnt vmcnt(4)
	ds_write_b128 v0, v[70:73] offset:53248
	s_waitcnt vmcnt(3)
	ds_write_b128 v0, v[102:105] offset:24576
	s_waitcnt vmcnt(2)
	ds_write_b128 v0, v[74:77] offset:57344
	s_waitcnt vmcnt(1)
	ds_write_b128 v0, v[106:109] offset:28672
	s_waitcnt vmcnt(0)
	ds_write_b128 v0, v[78:81] offset:61440
	v_mfma_f32_32x32x16_bf16 v[34:49], v[110:113], v[122:125], v[34:49]
	v_mfma_f32_32x32x16_bf16 v[18:33], v[114:117], v[118:121], v[18:33]
	v_mfma_f32_32x32x16_bf16 v[2:17], v[114:117], v[122:125], v[2:17]
	ds_read_b128 v[110:113], v91
	ds_read_b128 v[114:117], v91 offset:4096
	ds_read_b128 v[118:121], v92 offset:32768
	ds_read_b128 v[122:125], v92 offset:36864
	ds_read_b128 v[126:129], v93
	ds_read_b128 v[134:137], v93 offset:4096
	ds_read_b128 v[138:141], v90 offset:32768
	ds_read_b128 v[142:145], v90 offset:36864
	v_mfma_f32_32x32x16_bf16 v[50:65], v[162:165], v[182:185], v[50:65]
	v_mfma_f32_32x32x16_bf16 v[34:49], v[162:165], v[186:189], v[34:49]
	v_mfma_f32_32x32x16_bf16 v[18:33], v[166:169], v[182:185], v[18:33]
	v_mfma_f32_32x32x16_bf16 v[2:17], v[166:169], v[186:189], v[2:17]
	s_waitcnt lgkmcnt(5)
	v_mfma_f32_32x32x16_bf16 v[50:65], v[110:113], v[118:121], v[50:65]
	s_waitcnt lgkmcnt(4)
	v_mfma_f32_32x32x16_bf16 v[34:49], v[110:113], v[122:125], v[34:49]
	v_mfma_f32_32x32x16_bf16 v[18:33], v[114:117], v[118:121], v[18:33]
	v_mfma_f32_32x32x16_bf16 v[2:17], v[114:117], v[122:125], v[2:17]
	ds_read_b128 v[110:113], v89
	ds_read_b128 v[114:117], v89 offset:4096
	ds_read_b128 v[118:121], v88 offset:32768
	ds_read_b128 v[122:125], v88 offset:36864
	s_waitcnt lgkmcnt(5)
	v_mfma_f32_32x32x16_bf16 v[50:65], v[126:129], v[138:141], v[50:65]
	s_waitcnt lgkmcnt(4)
	v_mfma_f32_32x32x16_bf16 v[34:49], v[126:129], v[142:145], v[34:49]
	v_mfma_f32_32x32x16_bf16 v[18:33], v[134:137], v[138:141], v[18:33]
	v_mfma_f32_32x32x16_bf16 v[2:17], v[134:137], v[142:145], v[2:17]
	ds_read_b128 v[126:129], v87
	ds_read_b128 v[134:137], v87 offset:4096
	ds_read_b128 v[138:141], v86 offset:32768
	ds_read_b128 v[142:145], v86 offset:36864
	s_waitcnt lgkmcnt(5)
	v_mfma_f32_32x32x16_bf16 v[50:65], v[110:113], v[118:121], v[50:65]
	s_waitcnt lgkmcnt(0)
	s_barrier
	ds_read_b128 v[66:69], v91 offset:16384
	ds_read_b128 v[70:73], v91 offset:20480
	ds_read_b128 v[74:77], v92 offset:49152
	ds_read_b128 v[78:81], v92 offset:53248
	ds_read_b128 v[94:97], v93 offset:16384
	ds_read_b128 v[98:101], v93 offset:20480
	ds_read_b128 v[102:105], v90 offset:49152
	ds_read_b128 v[90:93], v90 offset:53248
	v_mfma_f32_32x32x16_bf16 v[34:49], v[110:113], v[122:125], v[34:49]
	v_mfma_f32_32x32x16_bf16 v[18:33], v[114:117], v[118:121], v[18:33]
	v_mfma_f32_32x32x16_bf16 v[2:17], v[114:117], v[122:125], v[2:17]
	v_mfma_f32_32x32x16_bf16 v[50:65], v[126:129], v[138:141], v[50:65]
	v_mfma_f32_32x32x16_bf16 v[34:49], v[126:129], v[142:145], v[34:49]
	v_mfma_f32_32x32x16_bf16 v[18:33], v[134:137], v[138:141], v[18:33]
	v_mfma_f32_32x32x16_bf16 v[2:17], v[134:137], v[142:145], v[2:17]
	s_waitcnt lgkmcnt(5)
	v_mfma_f32_32x32x16_bf16 v[50:65], v[66:69], v[74:77], v[50:65]
	s_waitcnt lgkmcnt(4)
	v_mfma_f32_32x32x16_bf16 v[34:49], v[66:69], v[78:81], v[34:49]
	v_mfma_f32_32x32x16_bf16 v[18:33], v[70:73], v[74:77], v[18:33]
	v_mfma_f32_32x32x16_bf16 v[2:17], v[70:73], v[78:81], v[2:17]
	ds_read_b128 v[66:69], v89 offset:16384
	ds_read_b128 v[70:73], v89 offset:20480
	ds_read_b128 v[74:77], v88 offset:49152
	ds_read_b128 v[78:81], v88 offset:53248
	s_waitcnt lgkmcnt(5)
	v_mfma_f32_32x32x16_bf16 v[50:65], v[94:97], v[102:105], v[50:65]
	s_waitcnt lgkmcnt(4)
	v_mfma_f32_32x32x16_bf16 v[34:49], v[94:97], v[90:93], v[34:49]
	v_mfma_f32_32x32x16_bf16 v[18:33], v[98:101], v[102:105], v[18:33]
	v_mfma_f32_32x32x16_bf16 v[2:17], v[98:101], v[90:93], v[2:17]
	ds_read_b128 v[88:91], v87 offset:16384
	ds_read_b128 v[92:95], v87 offset:20480
	ds_read_b128 v[96:99], v86 offset:49152
	ds_read_b128 v[100:103], v86 offset:53248
	s_waitcnt lgkmcnt(5)
	v_mfma_f32_32x32x16_bf16 v[50:65], v[66:69], v[74:77], v[50:65]
	v_lshlrev_b32_e32 v0, 6, v85
	v_subrev_u32_e32 v0, s2, v0
	s_lshl_b32 s3, s34, 7
	s_movk_i32 s2, 0x9c0
	s_waitcnt lgkmcnt(0)
	s_barrier
	v_mfma_f32_32x32x16_bf16 v[34:49], v[66:69], v[78:81], v[34:49]
	v_add_u32_e32 v66, s7, v0
	v_lshl_add_u32 v68, v83, 6, s3
	v_add_u32_e32 v0, v66, v84
	v_cmp_lt_i32_e64 s[40:41], s63, v0
	v_cmp_gt_u32_e32 vcc, s2, v66
	v_lshl_add_u64 v[66:67], v[0:1], 1, s[48:49]
	v_mfma_f32_32x32x16_bf16 v[18:33], v[70:73], v[74:77], v[18:33]
	v_mfma_f32_32x32x16_bf16 v[2:17], v[70:73], v[78:81], v[2:17]
	v_lshl_or_b32 v70, v82, 2, v68
	v_mfma_f32_32x32x16_bf16 v[50:65], v[88:91], v[96:99], v[50:65]
	v_mfma_f32_32x32x16_bf16 v[34:49], v[88:91], v[100:103], v[34:49]
	v_mfma_f32_32x32x16_bf16 v[18:33], v[92:95], v[96:99], v[18:33]
	v_mfma_f32_32x32x16_bf16 v[2:17], v[92:95], v[100:103], v[2:17]
	s_and_saveexec_b64 s[2:3], s[40:41]
	s_xor_b64 s[2:3], exec, s[2:3]
	s_cbranch_execz .LBB0_236
	s_and_saveexec_b64 s[4:5], vcc
	s_cbranch_execz .LBB0_235
	s_nop 3
	v_cvt_pk_bf16_f32 v71, v50, s0
	v_mad_i64_i32 v[68:69], s[34:35], v70, s68, v[66:67]
	global_store_short v[68:69], v71, off offset:-1920

.LBB0_702:
	s_and_b64 vcc, exec, s[0:1]
	s_cbranch_vccz .LBB0_672
	s_waitcnt vmcnt(0)
	s_mov_b64 s[2:3], exec
	v_and_b32_e32 v0, 0x7f, v133
	v_cmp_gt_u32_e32 vcc, 64, v0
	v_lshrrev_b32_e32 v2, 7, v133
	s_mul_i32 s0, s34, 34
	v_add_u32_e32 v2, s0, v2
	v_mul_u32_u24_e32 v2, 0xf00, v2
	v_lshl_add_u32 v2, v0, 2, v2
	s_add_u32 s4, s12, 0xc00
	s_addc_u32 s5, s13, 0
	global_load_dword v6, v2, s[4:5]
	s_add_u32 s4, s4, 0x1e00
	s_addc_u32 s5, s5, 0
	global_load_dword v7, v2, s[4:5]
	s_add_u32 s4, s4, 0x1e00
	s_addc_u32 s5, s5, 0
	global_load_dword v8, v2, s[4:5]
	s_add_u32 s4, s4, 0x1e00
	s_addc_u32 s5, s5, 0
	global_load_dword v9, v2, s[4:5]
	s_add_u32 s4, s4, 0x1e00
	s_addc_u32 s5, s5, 0
	global_load_dword v10, v2, s[4:5]
	s_add_u32 s4, s4, 0x1e00
	s_addc_u32 s5, s5, 0
	global_load_dword v11, v2, s[4:5]
	s_add_u32 s4, s4, 0x1e00
	s_addc_u32 s5, s5, 0
	global_load_dword v12, v2, s[4:5]
	s_add_u32 s4, s4, 0x1e00
	s_addc_u32 s5, s5, 0
	global_load_dword v13, v2, s[4:5]
	s_add_u32 s4, s4, 0x1e00
	s_addc_u32 s5, s5, 0
	global_load_dword v14, v2, s[4:5]
	s_add_u32 s4, s4, 0x1e00
	s_addc_u32 s5, s5, 0
	global_load_dword v15, v2, s[4:5]
	s_add_u32 s4, s4, 0x1e00
	s_addc_u32 s5, s5, 0
	global_load_dword v16, v2, s[4:5]
	s_add_u32 s4, s4, 0x1e00
	s_addc_u32 s5, s5, 0
	global_load_dword v17, v2, s[4:5]
	s_add_u32 s4, s4, 0x1e00
	s_addc_u32 s5, s5, 0
	global_load_dword v18, v2, s[4:5]
	s_add_u32 s4, s4, 0x1e00
	s_addc_u32 s5, s5, 0
	global_load_dword v19, v2, s[4:5]
	s_add_u32 s4, s4, 0x1e00
	s_addc_u32 s5, s5, 0
	global_load_dword v20, v2, s[4:5]
	s_add_u32 s4, s4, 0x1e00
	s_addc_u32 s5, s5, 0
	global_load_dword v21, v2, s[4:5]
	s_add_u32 s4, s4, 0x1e00
	s_addc_u32 s5, s5, 0
	global_load_dword v22, v2, s[4:5]
	v_lshlrev_b32_e32 v0, 2, v133
	s_waitcnt vmcnt(16)
	v_add_f32_e32 v23, v6, v6
	v_mul_f32_e32 v23, 0xbfb8aa3b, v23
	v_exp_f32_e32 v23, v23
	s_nop 0
	v_add_f32_e32 v23, 1.0, v23
	v_rcp_f32_e32 v23, v23
	s_nop 0
	v_fma_f32 v23, v23, 2.0, -1.0
	v_cndmask_b32_e32 v6, v6, v23, vcc
	ds_write_b32 v0, v6 offset:0
	s_waitcnt vmcnt(15)
	v_add_f32_e32 v24, v7, v7
	v_mul_f32_e32 v24, 0xbfb8aa3b, v24
	v_exp_f32_e32 v24, v24
	s_nop 0
	v_add_f32_e32 v24, 1.0, v24
	v_rcp_f32_e32 v24, v24
	s_nop 0
	v_fma_f32 v24, v24, 2.0, -1.0
	v_cndmask_b32_e32 v7, v7, v24, vcc
	ds_write_b32 v0, v7 offset:1024
	s_waitcnt vmcnt(14)
	v_add_f32_e32 v23, v8, v8
	v_mul_f32_e32 v23, 0xbfb8aa3b, v23
	v_exp_f32_e32 v23, v23
	s_nop 0
	v_add_f32_e32 v23, 1.0, v23
	v_rcp_f32_e32 v23, v23
	s_nop 0
	v_fma_f32 v23, v23, 2.0, -1.0
	v_cndmask_b32_e32 v8, v8, v23, vcc
	ds_write_b32 v0, v8 offset:2048
	s_waitcnt vmcnt(13)
	v_add_f32_e32 v24, v9, v9
	v_mul_f32_e32 v24, 0xbfb8aa3b, v24
	v_exp_f32_e32 v24, v24
	s_nop 0
	v_add_f32_e32 v24, 1.0, v24
	v_rcp_f32_e32 v24, v24
	s_nop 0
	v_fma_f32 v24, v24, 2.0, -1.0
	v_cndmask_b32_e32 v9, v9, v24, vcc
	ds_write_b32 v0, v9 offset:3072
	s_waitcnt vmcnt(12)
	v_add_f32_e32 v23, v10, v10
	v_mul_f32_e32 v23, 0xbfb8aa3b, v23
	v_exp_f32_e32 v23, v23
	s_nop 0
	v_add_f32_e32 v23, 1.0, v23
	v_rcp_f32_e32 v23, v23
	s_nop 0
	v_fma_f32 v23, v23, 2.0, -1.0
	v_cndmask_b32_e32 v10, v10, v23, vcc
	ds_write_b32 v0, v10 offset:4096
	s_waitcnt vmcnt(11)
	v_add_f32_e32 v24, v11, v11
	v_mul_f32_e32 v24, 0xbfb8aa3b, v24
	v_exp_f32_e32 v24, v24
	s_nop 0
	v_add_f32_e32 v24, 1.0, v24
	v_rcp_f32_e32 v24, v24
	s_nop 0
	v_fma_f32 v24, v24, 2.0, -1.0
	v_cndmask_b32_e32 v11, v11, v24, vcc
	ds_write_b32 v0, v11 offset:5120
	s_waitcnt vmcnt(10)
	v_add_f32_e32 v23, v12, v12
	v_mul_f32_e32 v23, 0xbfb8aa3b, v23
	v_exp_f32_e32 v23, v23
	s_nop 0
	v_add_f32_e32 v23, 1.0, v23
	v_rcp_f32_e32 v23, v23
	s_nop 0
	v_fma_f32 v23, v23, 2.0, -1.0
	v_cndmask_b32_e32 v12, v12, v23, vcc
	ds_write_b32 v0, v12 offset:6144
	s_waitcnt vmcnt(9)
	v_add_f32_e32 v24, v13, v13
	v_mul_f32_e32 v24, 0xbfb8aa3b, v24
	v_exp_f32_e32 v24, v24
	s_nop 0
	v_add_f32_e32 v24, 1.0, v24
	v_rcp_f32_e32 v24, v24
	s_nop 0
	v_fma_f32 v24, v24, 2.0, -1.0
	v_cndmask_b32_e32 v13, v13, v24, vcc
	ds_write_b32 v0, v13 offset:7168
	s_waitcnt vmcnt(8)
	v_add_f32_e32 v23, v14, v14
	v_mul_f32_e32 v23, 0xbfb8aa3b, v23
	v_exp_f32_e32 v23, v23
	s_nop 0
	v_add_f32_e32 v23, 1.0, v23
	v_rcp_f32_e32 v23, v23
	s_nop 0
	v_fma_f32 v23, v23, 2.0, -1.0
	v_cndmask_b32_e32 v14, v14, v23, vcc
	ds_write_b32 v0, v14 offset:8192
	s_waitcnt vmcnt(7)
	v_add_f32_e32 v24, v15, v15
	v_mul_f32_e32 v24, 0xbfb8aa3b, v24
	v_exp_f32_e32 v24, v24
	s_nop 0
	v_add_f32_e32 v24, 1.0, v24
	v_rcp_f32_e32 v24, v24
	s_nop 0
	v_fma_f32 v24, v24, 2.0, -1.0
	v_cndmask_b32_e32 v15, v15, v24, vcc
	ds_write_b32 v0, v15 offset:9216
	s_waitcnt vmcnt(6)
	v_add_f32_e32 v23, v16, v16
	v_mul_f32_e32 v23, 0xbfb8aa3b, v23
	v_exp_f32_e32 v23, v23
	s_nop 0
	v_add_f32_e32 v23, 1.0, v23
	v_rcp_f32_e32 v23, v23
	s_nop 0
	v_fma_f32 v23, v23, 2.0, -1.0
	v_cndmask_b32_e32 v16, v16, v23, vcc
	ds_write_b32 v0, v16 offset:10240
	s_waitcnt vmcnt(5)
	v_add_f32_e32 v24, v17, v17
	v_mul_f32_e32 v24, 0xbfb8aa3b, v24
	v_exp_f32_e32 v24, v24
	s_nop 0
	v_add_f32_e32 v24, 1.0, v24
	v_rcp_f32_e32 v24, v24
	s_nop 0
	v_fma_f32 v24, v24, 2.0, -1.0
	v_cndmask_b32_e32 v17, v17, v24, vcc
	ds_write_b32 v0, v17 offset:11264
	s_waitcnt vmcnt(4)
	v_add_f32_e32 v23, v18, v18
	v_mul_f32_e32 v23, 0xbfb8aa3b, v23
	v_exp_f32_e32 v23, v23
	s_nop 0
	v_add_f32_e32 v23, 1.0, v23
	v_rcp_f32_e32 v23, v23
	s_nop 0
	v_fma_f32 v23, v23, 2.0, -1.0
	v_cndmask_b32_e32 v18, v18, v23, vcc
	ds_write_b32 v0, v18 offset:12288
	s_waitcnt vmcnt(3)
	v_add_f32_e32 v24, v19, v19
	v_mul_f32_e32 v24, 0xbfb8aa3b, v24
	v_exp_f32_e32 v24, v24
	s_nop 0
	v_add_f32_e32 v24, 1.0, v24
	v_rcp_f32_e32 v24, v24
	s_nop 0
	v_fma_f32 v24, v24, 2.0, -1.0
	v_cndmask_b32_e32 v19, v19, v24, vcc
	ds_write_b32 v0, v19 offset:13312
	s_waitcnt vmcnt(2)
	v_add_f32_e32 v23, v20, v20
	v_mul_f32_e32 v23, 0xbfb8aa3b, v23
	v_exp_f32_e32 v23, v23
	s_nop 0
	v_add_f32_e32 v23, 1.0, v23
	v_rcp_f32_e32 v23, v23
	s_nop 0
	v_fma_f32 v23, v23, 2.0, -1.0
	v_cndmask_b32_e32 v20, v20, v23, vcc
	ds_write_b32 v0, v20 offset:14336
	s_waitcnt vmcnt(1)
	v_add_f32_e32 v24, v21, v21
	v_mul_f32_e32 v24, 0xbfb8aa3b, v24
	v_exp_f32_e32 v24, v24
	s_nop 0
	v_add_f32_e32 v24, 1.0, v24
	v_rcp_f32_e32 v24, v24
	s_nop 0
	v_fma_f32 v24, v24, 2.0, -1.0
	v_cndmask_b32_e32 v21, v21, v24, vcc
	ds_write_b32 v0, v21 offset:15360
	s_waitcnt vmcnt(0)
	v_add_f32_e32 v23, v22, v22
	v_mul_f32_e32 v23, 0xbfb8aa3b, v23
	v_exp_f32_e32 v23, v23
	s_nop 0
	v_add_f32_e32 v23, 1.0, v23
	v_rcp_f32_e32 v23, v23
	s_nop 0
	v_fma_f32 v23, v23, 2.0, -1.0
	v_cndmask_b32_e32 v22, v22, v23, vcc
	ds_write_b32 v0, v22 offset:16384
	v_mov_b32_e32 v2, v133

.LBB0_707:
	v_mov_b32_e32 v94, s2
	ds_read_b128 v[74:77], v94
	ds_read_b128 v[78:81], v94 offset:16
	ds_read_b128 v[82:85], v94 offset:32
	ds_read_b128 v[86:89], v94 offset:48
	ds_read_b128 v[90:93], v94 offset:128
	s_waitcnt lgkmcnt(0)
	v_mul_f32_e32 v75, v58, v75
	v_fmac_f32_e32 v75, v56, v74
	v_fmac_f32_e32 v75, v60, v76
	v_fmac_f32_e32 v75, v63, v77
	v_mul_f32_e32 v74, v59, v91
	v_fmac_f32_e32 v74, v57, v90
	v_fmac_f32_e32 v74, v61, v92
	v_fmac_f32_e32 v74, v62, v93
	v_add_f32_e32 v95, v72, v75
	v_add_f32_e32 v90, v73, v74
	ds_read_b128 v[74:77], v94 offset:144
	v_mul_f32_e32 v79, v66, v79
	v_fmac_f32_e32 v79, v64, v78
	v_fmac_f32_e32 v79, v68, v80
	v_fmac_f32_e32 v79, v71, v81
	s_waitcnt lgkmcnt(0)
	v_mul_f32_e32 v75, v67, v75
	v_fmac_f32_e32 v75, v65, v74
	v_fmac_f32_e32 v75, v69, v76
	v_fmac_f32_e32 v75, v70, v77
	v_add_f32_e32 v90, v90, v75
	v_mov_b32_e32 v75, v86
	v_mov_b32_e32 v86, v83
	v_mov_b32_e32 v74, v82
	v_pk_mul_f32 v[76:77], v[10:11], v[86:87]
	v_add_f32_e32 v78, v95, v79
	v_pk_fma_f32 v[74:75], v[6:7], v[74:75], v[76:77]
	v_mov_b32_e32 v76, v84
	v_mov_b32_e32 v77, v88
	v_pk_fma_f32 v[74:75], v[14:15], v[76:77], v[74:75]
	v_mov_b32_e32 v88, v85
	v_pk_fma_f32 v[74:75], v[20:21], v[88:89], v[74:75]
	s_ashr_i32 s1, s0, 31
	v_add_f32_e32 v74, v78, v74
	v_add_f32_e32 v84, v74, v75
	ds_read_b128 v[74:77], v94 offset:176
	ds_read_b128 v[78:81], v94 offset:160
	s_lshl_b64 s[4:5], s[0:1], 8
	s_addk_i32 s2, 0x200
	s_add_i32 s0, s0, 1
	s_waitcnt lgkmcnt(1)
	v_mov_b32_e32 v83, v74
	s_waitcnt lgkmcnt(0)
	v_mov_b32_e32 v74, v79
	v_mov_b32_e32 v82, v78
	v_pk_mul_f32 v[74:75], v[12:13], v[74:75]
	v_mov_b32_e32 v78, v80
	v_pk_fma_f32 v[74:75], v[8:9], v[82:83], v[74:75]
	v_mov_b32_e32 v79, v76
	v_pk_fma_f32 v[74:75], v[16:17], v[78:79], v[74:75]
	v_mov_b32_e32 v76, v81
	v_pk_fma_f32 v[74:75], v[18:19], v[76:77], v[74:75]
	s_cmpk_eq_i32 s2, 0x4400
	v_add_f32_e32 v74, v90, v74
	v_add_f32_e32 v85, v74, v75
	ds_read_b128 v[74:77], v94 offset:80
	ds_read_b128 v[78:81], v94 offset:64
	s_waitcnt lgkmcnt(1)
	v_mov_b32_e32 v83, v74
	s_waitcnt lgkmcnt(0)
	v_mov_b32_e32 v74, v79
	v_mov_b32_e32 v82, v78
	v_pk_mul_f32 v[74:75], v[26:27], v[74:75]
	v_mov_b32_e32 v78, v80
	v_pk_fma_f32 v[74:75], v[22:23], v[82:83], v[74:75]
	v_mov_b32_e32 v79, v76
	v_pk_fma_f32 v[74:75], v[30:31], v[78:79], v[74:75]
	v_mov_b32_e32 v76, v81
	v_pk_fma_f32 v[74:75], v[36:37], v[76:77], v[74:75]
	s_nop 0
	v_add_f32_e32 v74, v84, v74
	v_add_f32_e32 v84, v74, v75
	ds_read_b128 v[74:77], v94 offset:208
	ds_read_b128 v[78:81], v94 offset:192
	s_waitcnt lgkmcnt(1)
	v_mov_b32_e32 v83, v74
	s_waitcnt lgkmcnt(0)
	v_mov_b32_e32 v74, v79
	v_mov_b32_e32 v82, v78
	v_pk_mul_f32 v[74:75], v[28:29], v[74:75]
	v_mov_b32_e32 v78, v80
	v_pk_fma_f32 v[74:75], v[24:25], v[82:83], v[74:75]
	v_mov_b32_e32 v79, v76
	v_pk_fma_f32 v[74:75], v[32:33], v[78:79], v[74:75]
	v_mov_b32_e32 v76, v81
	v_pk_fma_f32 v[74:75], v[34:35], v[76:77], v[74:75]
	s_nop 0
	v_add_f32_e32 v74, v85, v74
	v_add_f32_e32 v85, v74, v75
	ds_read_b128 v[74:77], v94 offset:112
	ds_read_b128 v[78:81], v94 offset:96
	s_waitcnt lgkmcnt(1)
	v_mov_b32_e32 v83, v74
	s_waitcnt lgkmcnt(0)
	v_mov_b32_e32 v74, v79
	v_mov_b32_e32 v82, v78
	v_pk_mul_f32 v[74:75], v[42:43], v[74:75]
	v_mov_b32_e32 v78, v80
	v_pk_fma_f32 v[74:75], v[38:39], v[82:83], v[74:75]
	v_mov_b32_e32 v79, v76
	v_pk_fma_f32 v[74:75], v[46:47], v[78:79], v[74:75]
	v_mov_b32_e32 v76, v81
	v_pk_fma_f32 v[74:75], v[52:53], v[76:77], v[74:75]
	s_nop 0
	v_add_f32_e32 v74, v84, v74
	v_add_f32_e32 v84, v74, v75
	ds_read_b128 v[74:77], v94 offset:240
	ds_read_b128 v[78:81], v94 offset:224
	s_waitcnt lgkmcnt(1)
	v_mov_b32_e32 v83, v74
	s_waitcnt lgkmcnt(0)
	v_mov_b32_e32 v74, v79
	v_mov_b32_e32 v82, v78
	v_pk_mul_f32 v[74:75], v[44:45], v[74:75]
	v_mov_b32_e32 v78, v80
	v_pk_fma_f32 v[74:75], v[40:41], v[82:83], v[74:75]
	v_mov_b32_e32 v79, v76
	v_pk_fma_f32 v[74:75], v[48:49], v[78:79], v[74:75]
	v_mov_b32_e32 v76, v81
	v_pk_fma_f32 v[74:75], v[50:51], v[76:77], v[74:75]
	s_nop 0
	v_add_f32_e32 v74, v85, v74
	v_add_f32_e32 v78, v74, v75
	v_mul_f32_e32 v74, 0xbfb8aa3b, v84
	v_exp_f32_e32 v74, v74
	s_nop 0
	v_add_f32_e32 v74, 1.0, v74
	v_rcp_f32_e32 v74, v74
	s_nop 0
	v_mul_f32_e32 v74, 0xbf60028a, v74
	v_exp_f32_e32 v79, v74
	v_lshl_add_u64 v[74:75], s[4:5], 0, v[2:3]
	v_lshlrev_b64 v[74:75], 2, v[74:75]
	v_lshl_add_u64 v[76:77], s[14:15], 0, v[74:75]
	global_store_dword v[76:77], v79, off
	v_mul_f32_e32 v76, 0xbfb8aa3b, v78
	v_exp_f32_e32 v76, v76
	v_lshl_add_u64 v[74:75], s[16:17], 0, v[74:75]
	v_add_f32_e32 v76, 1.0, v76
	v_rcp_f32_e32 v76, v76
	s_nop 0
	v_mul_f32_e32 v76, 0xbf60028a, v76
	v_exp_f32_e32 v76, v76
	global_store_dword v[74:75], v76, off
	s_cbranch_scc0 .LBB0_707
	v_lshlrev_b64 v[6:7], 2, v[2:3]
	v_lshl_add_u64 v[66:67], s[68:69], 0, v[6:7]
	s_mov_b32 s0, 0xc000
	v_add_co_u32_e32 v14, vcc, 0x8000, v66
	v_readlane_b32 s44, v210, 18
	s_nop 0
	v_addc_co_u32_e32 v15, vcc, 0, v67, vcc
	v_add_co_u32_e32 v24, vcc, 0x1000, v66
	flat_load_dword v8, v[66:67]
	flat_load_dword v9, v[14:15]
	flat_load_dword v10, v[66:67] offset:1024
	flat_load_dword v11, v[14:15] offset:1024
	flat_load_dword v12, v[66:67] offset:2048
	flat_load_dword v13, v[14:15] offset:2048
	s_nop 0
	flat_load_dword v14, v[14:15] offset:3072
	s_nop 0
	flat_load_dword v15, v[66:67] offset:3072
	v_addc_co_u32_e32 v25, vcc, 0, v67, vcc
	v_add_co_u32_e32 v22, vcc, 0x9000, v66
	v_readlane_b32 s52, v210, 26
	s_nop 0
	v_addc_co_u32_e32 v23, vcc, 0, v67, vcc
	v_add_co_u32_e32 v32, vcc, 0x2000, v66
	flat_load_dword v16, v[24:25]
	flat_load_dword v17, v[22:23]
	flat_load_dword v18, v[24:25] offset:1024
	flat_load_dword v19, v[22:23] offset:1024
	flat_load_dword v20, v[24:25] offset:2048
	flat_load_dword v21, v[22:23] offset:2048
	s_nop 0
	flat_load_dword v22, v[22:23] offset:3072
	s_nop 0
	flat_load_dword v23, v[24:25] offset:3072
	v_addc_co_u32_e32 v33, vcc, 0, v67, vcc
	v_add_co_u32_e32 v30, vcc, 0xa000, v66
	v_readlane_b32 s53, v210, 27
	s_nop 0
	v_addc_co_u32_e32 v31, vcc, 0, v67, vcc
	v_add_co_u32_e32 v40, vcc, 0x3000, v66
	flat_load_dword v24, v[32:33]
	flat_load_dword v25, v[30:31]
	flat_load_dword v26, v[32:33] offset:1024
	flat_load_dword v27, v[30:31] offset:1024
	flat_load_dword v28, v[32:33] offset:2048
	flat_load_dword v29, v[30:31] offset:2048
	s_nop 0
	flat_load_dword v30, v[30:31] offset:3072
	s_nop 0
	flat_load_dword v31, v[32:33] offset:3072
	v_addc_co_u32_e32 v41, vcc, 0, v67, vcc
	v_add_co_u32_e32 v38, vcc, 0xb000, v66
	v_lshl_add_u64 v[4:5], v[4:5], 2, s[52:53]
	s_nop 0
	v_addc_co_u32_e32 v39, vcc, 0, v67, vcc
	v_add_co_u32_e32 v48, vcc, s3, v66
	flat_load_dword v32, v[40:41]
	flat_load_dword v33, v[38:39]
	flat_load_dword v34, v[40:41] offset:1024
	flat_load_dword v35, v[38:39] offset:1024
	flat_load_dword v36, v[40:41] offset:2048
	flat_load_dword v37, v[38:39] offset:2048
	s_nop 0
	flat_load_dword v38, v[38:39] offset:3072
	s_nop 0
	flat_load_dword v39, v[40:41] offset:3072
	v_addc_co_u32_e32 v49, vcc, 0, v67, vcc
	v_add_co_u32_e32 v46, vcc, s0, v66
	s_movk_i32 s0, 0x5000
	s_nop 0
	v_addc_co_u32_e32 v47, vcc, 0, v67, vcc
	v_add_co_u32_e32 v58, vcc, s0, v66
	s_mov_b32 s0, 0xd000
	s_nop 0
	v_addc_co_u32_e32 v59, vcc, 0, v67, vcc
	v_add_co_u32_e32 v56, vcc, s0, v66
	s_movk_i32 s0, 0x6000
	s_nop 0
	v_addc_co_u32_e32 v57, vcc, 0, v67, vcc
	v_add_co_u32_e32 v68, vcc, s0, v66
	s_mov_b32 s0, 0xe000
	s_nop 0
	v_addc_co_u32_e32 v69, vcc, 0, v67, vcc
	v_add_co_u32_e32 v64, vcc, s0, v66
	s_movk_i32 s0, 0x7000
	s_nop 0
	v_addc_co_u32_e32 v65, vcc, 0, v67, vcc
	v_add_co_u32_e32 v74, vcc, s0, v66
	s_mov_b32 s0, 0xf000
	s_nop 0
	v_addc_co_u32_e32 v75, vcc, 0, v67, vcc
	v_add_co_u32_e32 v72, vcc, s0, v66
	flat_load_dword v40, v[48:49]
	flat_load_dword v41, v[46:47]
	flat_load_dword v42, v[48:49] offset:1024
	flat_load_dword v43, v[46:47] offset:1024
	flat_load_dword v44, v[48:49] offset:2048
	flat_load_dword v45, v[46:47] offset:2048
	s_nop 0
	flat_load_dword v46, v[46:47] offset:3072
	s_nop 0
	flat_load_dword v47, v[48:49] offset:3072
	v_addc_co_u32_e32 v73, vcc, 0, v67, vcc
	flat_load_dword v48, v[58:59]
	flat_load_dword v49, v[56:57]
	flat_load_dword v50, v[58:59] offset:1024
	flat_load_dword v51, v[56:57] offset:1024
	flat_load_dword v52, v[58:59] offset:2048
	flat_load_dword v53, v[56:57] offset:2048
	s_nop 0
	flat_load_dword v56, v[56:57] offset:3072
	s_nop 0
	flat_load_dword v57, v[58:59] offset:3072
	s_nop 0
	flat_load_dword v58, v[68:69]
	flat_load_dword v59, v[64:65]
	flat_load_dword v60, v[68:69] offset:1024
	flat_load_dword v61, v[64:65] offset:1024
	flat_load_dword v62, v[68:69] offset:2048
	flat_load_dword v63, v[64:65] offset:2048
	s_nop 0
	flat_load_dword v64, v[64:65] offset:3072
	s_nop 0
	flat_load_dword v65, v[68:69] offset:3072
	flat_load_dword v66, v[74:75]
	flat_load_dword v67, v[72:73]
	s_nop 0
	flat_load_dword v68, v[74:75] offset:1024
	flat_load_dword v69, v[72:73] offset:1024
	flat_load_dword v70, v[74:75] offset:2048
	flat_load_dword v71, v[72:73] offset:2048
	s_nop 0
	flat_load_dword v72, v[72:73] offset:3072
	s_nop 0
	flat_load_dword v73, v[74:75] offset:3072
	s_nop 0
	global_load_dword v74, v[4:5], off
	global_load_dword v75, v[4:5], off offset:1024
	v_and_b32_e32 v5, 63, v2
	v_ashrrev_i32_e32 v4, 6, v2
	v_readlane_b32 s56, v210, 30
	v_readlane_b32 s57, v210, 31
	v_readlane_b32 s58, v210, 32
	v_readlane_b32 s59, v210, 33
	v_cmp_eq_u32_e32 vcc, 0, v5
	v_ashrrev_i32_e32 v5, 31, v4
	v_readlane_b32 s80, v208, 27
	s_movk_i32 s61, 0x4000
	s_mov_b32 s6, 0
	v_lshl_add_u64 v[4:5], v[4:5], 2, s[24:25]
	v_lshl_add_u64 v[6:7], s[12:13], 0, v[6:7]
	s_movk_i32 s7, 0x100
	v_readlane_b32 s81, v208, 28
	v_readlane_b32 s82, v208, 29
	v_readlane_b32 s83, v208, 30
	v_readlane_b32 s84, v208, 31
	v_readlane_b32 s85, v208, 32
	v_readlane_b32 s86, v208, 33
	v_readlane_b32 s87, v208, 34
	v_readlane_b32 s88, v208, 35
	v_readlane_b32 s89, v208, 36
	v_readlane_b32 s90, v208, 37
	v_readlane_b32 s91, v208, 38
	v_readlane_b32 s92, v208, 39
	v_readlane_b32 s93, v208, 40
	v_readlane_b32 s94, v208, 41
	v_readlane_b32 s95, v208, 42
	s_mov_b32 s56, 0x10000
	s_mov_b32 s57, 0x20000
	s_mov_b32 s58, 0x30000
	s_movk_i32 s59, 0x70
	v_readlane_b32 s45, v210, 19
	v_readlane_b32 s46, v210, 20
	v_readlane_b32 s47, v210, 21
	v_readlane_b32 s48, v210, 22
	v_readlane_b32 s49, v210, 23
	v_readlane_b32 s50, v210, 24
	v_readlane_b32 s51, v210, 25
	v_readlane_b32 s54, v210, 28
	v_readlane_b32 s55, v210, 29
	s_waitcnt vmcnt(0) lgkmcnt(0)
	s_branch .LBB0_710

.LBB0_710:
	v_mov_b32_e32 v96, s7
	ds_read_b128 v[76:79], v96
	ds_read_b128 v[80:83], v96 offset:16
	ds_read_b128 v[84:87], v96 offset:32
	ds_read_b128 v[88:91], v96 offset:48
	ds_read_b128 v[92:95], v96 offset:128
	s_waitcnt lgkmcnt(0)
	s_add_i32 s0, s97, s6
	v_mad_i64_i32 v[212:213], s[2:3], s0, v178, v[6:7]
	global_load_dword v211, v[212:213], off
	global_load_dword v214, v[212:213], off offset:1024
	v_mul_f32_e32 v77, v10, v77
	v_fmac_f32_e32 v77, v8, v76
	v_fmac_f32_e32 v77, v12, v78
	v_fmac_f32_e32 v77, v15, v79
	v_mul_f32_e32 v76, v11, v93
	v_fmac_f32_e32 v76, v9, v92
	v_fmac_f32_e32 v76, v13, v94
	v_fmac_f32_e32 v76, v14, v95
	v_add_f32_e32 v97, v74, v77
	v_add_f32_e32 v92, v75, v76
	ds_read_b128 v[76:79], v96 offset:144
	v_mul_f32_e32 v81, v18, v81
	v_fmac_f32_e32 v81, v16, v80
	v_fmac_f32_e32 v81, v20, v82
	v_fmac_f32_e32 v81, v23, v83
	s_waitcnt lgkmcnt(0)
	v_mul_f32_e32 v77, v19, v77
	v_fmac_f32_e32 v77, v17, v76
	v_fmac_f32_e32 v77, v21, v78
	v_fmac_f32_e32 v77, v22, v79
	v_add_f32_e32 v80, v97, v81
	v_add_f32_e32 v81, v92, v77
	ds_read_b128 v[76:79], v96 offset:160
	v_mul_f32_e32 v82, v26, v85
	v_fmac_f32_e32 v82, v24, v84
	v_fmac_f32_e32 v82, v28, v86
	v_fmac_f32_e32 v82, v31, v87
	s_waitcnt lgkmcnt(0)
	v_mul_f32_e32 v77, v27, v77
	v_fmac_f32_e32 v77, v25, v76
	v_fmac_f32_e32 v77, v29, v78
	v_fmac_f32_e32 v77, v30, v79
	v_add_f32_e32 v81, v81, v77
	ds_read_b128 v[76:79], v96 offset:176
	v_add_f32_e32 v80, v80, v82
	v_mul_f32_e32 v82, v34, v89
	v_fmac_f32_e32 v82, v32, v88
	v_fmac_f32_e32 v82, v36, v90
	s_waitcnt lgkmcnt(0)
	v_mul_f32_e32 v77, v35, v77
	v_fmac_f32_e32 v77, v33, v76
	v_fmac_f32_e32 v77, v37, v78
	v_fmac_f32_e32 v82, v39, v91
	v_fmac_f32_e32 v77, v38, v79
	v_add_f32_e32 v84, v80, v82
	v_add_f32_e32 v85, v81, v77
	ds_read_b128 v[76:79], v96 offset:64
	ds_read_b128 v[80:83], v96 offset:192
	s_add_i32 s0, s97, s6
	s_ashr_i32 s1, s0, 31
	s_waitcnt lgkmcnt(1)
	v_mul_f32_e32 v77, v42, v77
	v_fmac_f32_e32 v77, v40, v76
	s_waitcnt lgkmcnt(0)
	v_mul_f32_e32 v76, v43, v81
	v_fmac_f32_e32 v76, v41, v80
	v_fmac_f32_e32 v77, v44, v78
	v_fmac_f32_e32 v76, v45, v82
	v_fmac_f32_e32 v77, v47, v79
	v_fmac_f32_e32 v76, v46, v83
	v_add_f32_e32 v84, v84, v77
	v_add_f32_e32 v85, v85, v76
	ds_read_b128 v[76:79], v96 offset:80
	ds_read_b128 v[80:83], v96 offset:208
	s_waitcnt lgkmcnt(1)
	v_mul_f32_e32 v77, v50, v77
	v_fmac_f32_e32 v77, v48, v76
	s_waitcnt lgkmcnt(0)
	v_mul_f32_e32 v76, v51, v81
	v_fmac_f32_e32 v76, v49, v80
	v_fmac_f32_e32 v77, v52, v78
	v_fmac_f32_e32 v76, v53, v82
	v_fmac_f32_e32 v77, v57, v79
	v_fmac_f32_e32 v76, v56, v83
	v_add_f32_e32 v84, v84, v77
	v_add_f32_e32 v85, v85, v76
	ds_read_b128 v[76:79], v96 offset:96
	ds_read_b128 v[80:83], v96 offset:224
	s_waitcnt lgkmcnt(1)
	v_mul_f32_e32 v77, v60, v77
	v_fmac_f32_e32 v77, v58, v76
	s_waitcnt lgkmcnt(0)
	v_mul_f32_e32 v76, v61, v81
	v_fmac_f32_e32 v76, v59, v80
	v_fmac_f32_e32 v77, v62, v78
	v_fmac_f32_e32 v76, v63, v82
	v_fmac_f32_e32 v77, v65, v79
	v_fmac_f32_e32 v76, v64, v83
	v_add_f32_e32 v84, v84, v77
	v_add_f32_e32 v85, v85, v76
	ds_read_b128 v[76:79], v96 offset:112
	ds_read_b128 v[80:83], v96 offset:240
	s_waitcnt lgkmcnt(1)
	v_mul_f32_e32 v77, v68, v77
	v_fmac_f32_e32 v77, v66, v76
	v_fmac_f32_e32 v77, v70, v78
	v_fmac_f32_e32 v77, v73, v79
	v_add_f32_e32 v76, v84, v77
	s_waitcnt lgkmcnt(0)
	v_mul_f32_e32 v77, v69, v81
	v_fmac_f32_e32 v77, v67, v80
	v_fmac_f32_e32 v77, v71, v82
	v_fmac_f32_e32 v77, v72, v83
	v_add_f32_e32 v77, v85, v77
	v_mul_f32_e32 v77, 0xbfb8aa3b, v77
	v_mul_f32_e32 v76, 0xbfb8aa3b, v76
	v_exp_f32_e32 v77, v77
	v_exp_f32_e32 v76, v76
	v_add_f32_e32 v77, 1.0, v77
	v_add_f32_e32 v76, 1.0, v76
	v_rcp_f32_e32 v77, v77
	v_rcp_f32_e32 v76, v76
	s_waitcnt vmcnt(0)
	v_mul_f32_e32 v82, v0, v214
	v_mul_f32_e32 v78, v82, v82
	s_nop 1
	v_mov_b32_dpp v78, v78 quad_perm:[1,0,3,2] row_mask:0xf bank_mask:0xf bound_ctrl:1
	v_fmac_f32_e32 v78, v82, v82
	s_nop 1
	v_add_f32_dpp v78, v78, v78 quad_perm:[2,3,0,1] row_mask:0xf bank_mask:0xf bound_ctrl:1
	s_nop 1
	v_add_f32_dpp v78, v78, v78 row_half_mirror row_mask:0xf bank_mask:0xf bound_ctrl:1
	s_nop 1
	v_add_f32_dpp v78, v78, v78 row_mirror row_mask:0xf bank_mask:0xf bound_ctrl:1
	s_nop 0
	v_readlane_b32 s4, v78, 16
	v_readlane_b32 s5, v78, 48
	v_readlane_b32 s2, v78, 0
	v_readlane_b32 s3, v78, 32
	v_mov_b32_e32 v78, s4
	v_mov_b32_e32 v79, s5
	v_pk_add_f32 v[78:79], s[2:3], v[78:79]
	s_lshl_b64 s[4:5], s[0:1], 8
	v_add_f32_e32 v78, v78, v79
	v_max_f32_e32 v78, 0x179abe15, v78
	v_rsq_f32_e32 v78, v78
	v_add_f32_e32 v79, -1.0, v77
	v_fma_f32 v79, v54, v79, 1.0
	v_mul_f32_e32 v79, v214, v79
	v_mul_f32_e32 v82, v82, v78
	v_add_f32_e32 v78, -1.0, v76
	v_fma_f32 v78, v54, v78, 1.0
	v_fmac_f32_e32 v79, v214, v78
	v_mul_f32_e32 v78, v211, v79
	v_mul_f32_e32 v79, v55, v78
	s_nop 1
	v_mov_b32_dpp v79, v79 quad_perm:[1,0,3,2] row_mask:0xf bank_mask:0xf bound_ctrl:1
	v_fmac_f32_e32 v79, v55, v78
	s_nop 1
	v_add_f32_dpp v78, v79, v79 quad_perm:[2,3,0,1] row_mask:0xf bank_mask:0xf bound_ctrl:1
	s_nop 1
	v_add_f32_dpp v78, v78, v78 row_half_mirror row_mask:0xf bank_mask:0xf bound_ctrl:1
	s_nop 1
	v_add_f32_dpp v78, v78, v78 row_mirror row_mask:0xf bank_mask:0xf bound_ctrl:1
	s_nop 0
	v_readlane_b32 s2, v78, 0
	v_readlane_b32 s8, v78, 16
	v_readlane_b32 s3, v78, 32
	v_readlane_b32 s9, v78, 48
	v_lshl_add_u64 v[78:79], s[4:5], 0, v[2:3]
	v_lshlrev_b64 v[78:79], 2, v[78:79]
	v_lshl_add_u64 v[80:81], s[18:19], 0, v[78:79]
	global_store_dword v[80:81], v76, off
	v_lshl_add_u64 v[80:81], s[20:21], 0, v[78:79]
	global_store_dword v[80:81], v77, off
	v_lshl_add_u64 v[76:77], s[22:23], 0, v[78:79]
	global_store_dword v[76:77], v82, off
	s_and_saveexec_b64 s[4:5], vcc
	s_cbranch_execz .LBB0_709
	v_mov_b32_e32 v76, s8
	v_mov_b32_e32 v77, s9
	v_pk_add_f32 v[76:77], s[2:3], v[76:77]
	s_nop 0
	v_add_f32_e32 v78, v76, v77
	v_lshl_add_u64 v[76:77], s[0:1], 4, v[4:5]
	global_store_dword v[76:77], v78, off
	s_branch .LBB0_709

.LBB0_1125:
	v_mov_b32_e32 v48, v133
	s_mov_b64 s[2:3], exec
	v_and_b32_e32 v0, 63, v48
	v_lshrrev_b32_e32 v2, 6, v48
	s_mul_i32 s9, s8, 34
	v_add_u32_e32 v2, s9, v2
	v_mul_u32_u24_e32 v2, 0xf00, v2
	v_lshl_add_u32 v2, v0, 2, v2
	s_add_u32 s4, s12, 0xe00
	s_addc_u32 s5, s13, 0
	global_load_dword v6, v2, s[4:5]
	s_add_u32 s4, s4, 0x3c00
	s_addc_u32 s5, s5, 0
	global_load_dword v7, v2, s[4:5]
	s_add_u32 s4, s4, 0x3c00
	s_addc_u32 s5, s5, 0
	global_load_dword v8, v2, s[4:5]
	s_add_u32 s4, s4, 0x3c00
	s_addc_u32 s5, s5, 0
	global_load_dword v9, v2, s[4:5]
	s_add_u32 s4, s4, 0x3c00
	s_addc_u32 s5, s5, 0
	global_load_dword v10, v2, s[4:5]
	s_add_u32 s4, s4, 0x3c00
	s_addc_u32 s5, s5, 0
	global_load_dword v11, v2, s[4:5]
	s_add_u32 s4, s4, 0x3c00
	s_addc_u32 s5, s5, 0
	global_load_dword v12, v2, s[4:5]
	s_add_u32 s4, s4, 0x3c00
	s_addc_u32 s5, s5, 0
	global_load_dword v13, v2, s[4:5]
	s_add_u32 s4, s4, 0x3c00
	s_addc_u32 s5, s5, 0
	v_cmp_gt_u32_e32 vcc, 0x80, v48
	s_and_b64 exec, exec, vcc
	global_load_dword v14, v2, s[4:5]
	s_mov_b64 exec, s[2:3]
	v_lshlrev_b32_e32 v0, 2, v48
	s_waitcnt vmcnt(8)
	v_mul_f32_e32 v23, 0xbfb8aa3b, v6
	v_exp_f32_e32 v23, v23
	s_nop 0
	v_add_f32_e32 v23, 1.0, v23
	v_rcp_f32_e32 v6, v23
	s_nop 0
	ds_write_b32 v0, v6 offset:0
	s_waitcnt vmcnt(7)
	v_mul_f32_e32 v23, 0xbfb8aa3b, v7
	v_exp_f32_e32 v23, v23
	s_nop 0
	v_add_f32_e32 v23, 1.0, v23
	v_rcp_f32_e32 v7, v23
	s_nop 0
	ds_write_b32 v0, v7 offset:1024
	s_waitcnt vmcnt(6)
	v_mul_f32_e32 v23, 0xbfb8aa3b, v8
	v_exp_f32_e32 v23, v23
	s_nop 0
	v_add_f32_e32 v23, 1.0, v23
	v_rcp_f32_e32 v8, v23
	s_nop 0
	ds_write_b32 v0, v8 offset:2048
	s_waitcnt vmcnt(5)
	v_mul_f32_e32 v23, 0xbfb8aa3b, v9
	v_exp_f32_e32 v23, v23
	s_nop 0
	v_add_f32_e32 v23, 1.0, v23
	v_rcp_f32_e32 v9, v23
	s_nop 0
	ds_write_b32 v0, v9 offset:3072
	s_waitcnt vmcnt(4)
	v_mul_f32_e32 v23, 0xbfb8aa3b, v10
	v_exp_f32_e32 v23, v23
	s_nop 0
	v_add_f32_e32 v23, 1.0, v23
	v_rcp_f32_e32 v10, v23
	s_nop 0
	ds_write_b32 v0, v10 offset:4096
	s_waitcnt vmcnt(3)
	v_mul_f32_e32 v23, 0xbfb8aa3b, v11
	v_exp_f32_e32 v23, v23
	s_nop 0
	v_add_f32_e32 v23, 1.0, v23
	v_rcp_f32_e32 v11, v23
	s_nop 0
	ds_write_b32 v0, v11 offset:5120
	s_waitcnt vmcnt(2)
	v_mul_f32_e32 v23, 0xbfb8aa3b, v12
	v_exp_f32_e32 v23, v23
	s_nop 0
	v_add_f32_e32 v23, 1.0, v23
	v_rcp_f32_e32 v12, v23
	s_nop 0
	ds_write_b32 v0, v12 offset:6144
	s_waitcnt vmcnt(1)
	v_mul_f32_e32 v23, 0xbfb8aa3b, v13
	v_exp_f32_e32 v23, v23
	s_nop 0
	v_add_f32_e32 v23, 1.0, v23
	v_rcp_f32_e32 v13, v23
	s_nop 0
	ds_write_b32 v0, v13 offset:7168
	s_waitcnt vmcnt(0)
	s_and_b64 exec, exec, vcc
	v_mul_f32_e32 v23, 0xbfb8aa3b, v14
	v_exp_f32_e32 v23, v23
	s_nop 0
	v_add_f32_e32 v23, 1.0, v23
	v_rcp_f32_e32 v14, v23
	s_nop 0
	ds_write_b32 v0, v14 offset:8192
.LBB0_1128:
	s_or_b64 exec, exec, s[2:3]
	v_ashrrev_i32_e32 v49, 31, v48
	v_lshlrev_b64 v[54:55], 2, v[48:49]
	v_lshl_add_u64 v[42:43], s[0:1], 0, v[54:55]
	s_movk_i32 s2, 0x1000
	s_movk_i32 s3, 0x2000
	v_add_co_u32_e32 v2, vcc, s2, v42
	s_movk_i32 s2, 0x3000
	s_nop 0
	v_addc_co_u32_e32 v3, vcc, 0, v43, vcc
	flat_load_dword v0, v[42:43]
	flat_load_dword v58, v[42:43] offset:1024
	flat_load_dword v59, v[42:43] offset:2048
	flat_load_dword v60, v[42:43] offset:3072
	flat_load_dword v61, v[2:3]
	flat_load_dword v62, v[2:3] offset:1024
	flat_load_dword v63, v[2:3] offset:2048
	flat_load_dword v64, v[2:3] offset:3072
	v_add_co_u32_e32 v2, vcc, s3, v42
	s_mov_b32 s4, 0xb000
	s_nop 0
	v_addc_co_u32_e32 v3, vcc, 0, v43, vcc
	v_add_co_u32_e32 v4, vcc, s2, v42
	s_movk_i32 s2, 0x5000
	s_nop 0
	v_addc_co_u32_e32 v5, vcc, 0, v43, vcc
	flat_load_dword v65, v[2:3]
	flat_load_dword v66, v[2:3] offset:1024
	flat_load_dword v67, v[2:3] offset:2048
	flat_load_dword v68, v[2:3] offset:3072
	flat_load_dword v69, v[4:5]
	flat_load_dword v70, v[4:5] offset:1024
	flat_load_dword v71, v[4:5] offset:2048
	flat_load_dword v72, v[4:5] offset:3072
	v_add_co_u32_e32 v2, vcc, s61, v42
	v_readlane_b32 s44, v210, 34
	s_nop 0
	v_addc_co_u32_e32 v3, vcc, 0, v43, vcc
	v_add_co_u32_e32 v8, vcc, s2, v42
	s_movk_i32 s2, 0x6000
	s_nop 0
	v_addc_co_u32_e32 v9, vcc, 0, v43, vcc
	v_add_co_u32_e32 v10, vcc, s2, v42
	s_movk_i32 s2, 0x7000
	s_nop 0
	v_addc_co_u32_e32 v11, vcc, 0, v43, vcc
	v_add_co_u32_e32 v16, vcc, s2, v42
	s_mov_b32 s2, 0x8000
	s_nop 0
	v_addc_co_u32_e32 v17, vcc, 0, v43, vcc
	v_add_co_u32_e32 v18, vcc, s2, v42
	s_mov_b32 s2, 0x9000
	s_nop 0
	v_addc_co_u32_e32 v19, vcc, 0, v43, vcc
	v_add_co_u32_e32 v24, vcc, s2, v42
	s_mov_b32 s2, 0xa000
	s_nop 0
	v_addc_co_u32_e32 v25, vcc, 0, v43, vcc
	v_add_co_u32_e32 v26, vcc, s2, v42
	s_mov_b32 s2, 0xc000
	s_nop 0
	v_addc_co_u32_e32 v27, vcc, 0, v43, vcc
	v_add_co_u32_e32 v32, vcc, s4, v42
	flat_load_dword v73, v[2:3]
	flat_load_dword v74, v[2:3] offset:1024
	flat_load_dword v75, v[2:3] offset:2048
	flat_load_dword v76, v[2:3] offset:3072
	s_nop 0
	flat_load_dword v2, v[8:9]
	flat_load_dword v4, v[8:9] offset:1024
	flat_load_dword v6, v[8:9] offset:2048
	s_nop 0
	flat_load_dword v8, v[8:9] offset:3072
	v_addc_co_u32_e32 v33, vcc, 0, v43, vcc
	v_add_co_u32_e32 v34, vcc, s2, v42
	s_mov_b32 s2, 0xd000
	s_nop 0
	v_addc_co_u32_e32 v35, vcc, 0, v43, vcc
	v_add_co_u32_e32 v40, vcc, s2, v42
	s_mov_b32 s2, 0xe000
	s_nop 0
	v_addc_co_u32_e32 v41, vcc, 0, v43, vcc
	v_add_co_u32_e32 v44, vcc, s2, v42
	s_mov_b32 s2, 0xf000
	s_nop 0
	v_addc_co_u32_e32 v45, vcc, 0, v43, vcc
	v_add_co_u32_e32 v46, vcc, s2, v42
	flat_load_dword v3, v[10:11]
	flat_load_dword v5, v[10:11] offset:1024
	flat_load_dword v7, v[10:11] offset:2048
	flat_load_dword v9, v[10:11] offset:3072
	s_nop 0
	flat_load_dword v10, v[16:17]
	flat_load_dword v12, v[16:17] offset:1024
	flat_load_dword v14, v[16:17] offset:2048
	s_nop 0
	flat_load_dword v16, v[16:17] offset:3072
	s_nop 0
	flat_load_dword v11, v[18:19]
	flat_load_dword v13, v[18:19] offset:1024
	flat_load_dword v15, v[18:19] offset:2048
	flat_load_dword v17, v[18:19] offset:3072
	s_nop 0
	flat_load_dword v18, v[24:25]
	flat_load_dword v20, v[24:25] offset:1024
	flat_load_dword v22, v[24:25] offset:2048
	s_nop 0
	flat_load_dword v24, v[24:25] offset:3072
	s_nop 0
	flat_load_dword v19, v[26:27]
	flat_load_dword v21, v[26:27] offset:1024
	flat_load_dword v23, v[26:27] offset:2048
	flat_load_dword v25, v[26:27] offset:3072
	s_nop 0
	flat_load_dword v26, v[32:33]
	flat_load_dword v28, v[32:33] offset:1024
	flat_load_dword v30, v[32:33] offset:2048
	s_nop 0
	flat_load_dword v32, v[32:33] offset:3072
	s_nop 0
	flat_load_dword v27, v[34:35]
	flat_load_dword v29, v[34:35] offset:1024
	flat_load_dword v31, v[34:35] offset:2048
	flat_load_dword v33, v[34:35] offset:3072
	s_nop 0
	flat_load_dword v34, v[40:41]
	flat_load_dword v36, v[40:41] offset:1024
	flat_load_dword v38, v[40:41] offset:2048
	s_nop 0
	flat_load_dword v40, v[40:41] offset:3072
	v_addc_co_u32_e32 v47, vcc, 0, v43, vcc
	flat_load_dword v35, v[44:45]
	flat_load_dword v37, v[44:45] offset:1024
	flat_load_dword v39, v[44:45] offset:2048
	flat_load_dword v41, v[44:45] offset:3072
	flat_load_dword v42, v[46:47]
	flat_load_dword v43, v[46:47] offset:1024
	flat_load_dword v77, v[46:47] offset:2048
	s_nop 0
	flat_load_dword v45, v[46:47] offset:3072
	v_add_u32_e32 v46, s7, v48
	v_ashrrev_i32_e32 v47, 31, v46
	v_lshlrev_b64 v[46:47], 2, v[46:47]
	v_readlane_b32 s48, v210, 38
	v_readlane_b32 s49, v210, 39
	v_readlane_b32 s50, v210, 40
	v_readlane_b32 s51, v210, 41
	v_lshl_add_u64 v[50:51], s[48:49], 0, v[46:47]
	global_load_dword v78, v[50:51], off
	v_lshl_add_u64 v[46:47], s[50:51], 0, v[46:47]
	global_load_dword v46, v[46:47], off
	v_readlane_b32 s45, v210, 35
	v_readlane_b32 s46, v210, 36
	v_readlane_b32 s47, v210, 37
	v_readlane_b32 s52, v210, 42
	v_readlane_b32 s53, v210, 43
	v_readlane_b32 s54, v210, 44
	v_readlane_b32 s55, v210, 45
	v_readlane_b32 s56, v210, 46
	v_readlane_b32 s57, v210, 47
	v_readlane_b32 s58, v210, 48
	v_readlane_b32 s59, v210, 49
	s_ashr_i32 s35, s34, 31
	v_readlane_b32 s44, v210, 50
	s_lshl_b64 s[2:3], s[34:35], 11
	s_lshl_b64 s[36:37], s[34:35], 4
	s_lshl_b64 s[38:39], s[34:35], 10
	v_readlane_b32 s46, v210, 52
	v_readlane_b32 s47, v210, 53
	s_add_u32 s2, s46, s2
	s_addc_u32 s3, s47, s3
	s_mul_i32 s9, s34, 0xf00
	v_ashrrev_i32_e32 v52, 6, v48
	v_lshl_add_u64 v[48:49], v[48:49], 1, s[2:3]
	v_readlane_b32 s2, v208, 22
	s_mul_hi_i32 s5, s34, 0xf00
	s_add_u32 s2, s2, s9
	s_addc_u32 s3, s69, s5
	v_lshl_add_u64 v[50:51], s[2:3], 0, v[54:55]
	s_add_u32 s2, s24, s36
	v_ashrrev_i32_e32 v53, 31, v52
	v_readlane_b32 s45, v210, 51
	s_addc_u32 s3, s25, s37
	v_lshl_add_u64 v[56:57], s[38:39], 0, v[54:55]
	s_mov_b32 s4, 0
	v_lshl_add_u64 v[52:53], v[52:53], 2, s[2:3]
	v_lshl_add_u64 v[54:55], s[26:27], 0, v[56:57]
	v_lshl_add_u64 v[56:57], s[44:45], 0, v[56:57]
	s_mov_b64 s[2:3], 0
	s_waitcnt lgkmcnt(0)
	s_barrier
	v_readlane_b32 s48, v210, 54
	v_readlane_b32 s49, v210, 55
	v_readlane_b32 s50, v210, 56
	v_readlane_b32 s51, v210, 57
	v_readlane_b32 s52, v210, 58
	v_readlane_b32 s53, v210, 59
	v_readlane_b32 s54, v210, 60
	v_readlane_b32 s55, v210, 61
	v_readlane_b32 s56, v210, 62
	v_readlane_b32 s57, v210, 63
	v_readlane_b32 s58, v209, 0
	v_readlane_b32 s59, v209, 1
	v_lshl_add_u64 v[80:81], v[54:55], 0, s[2:3]
	global_load_dword v211, v[80:81], off
	v_lshl_add_u64 v[80:81], v[56:57], 0, s[2:3]
	global_load_dword v212, v[80:81], off
	s_add_u32 s2, s2, 0x400
	s_addc_u32 s3, s3, 0
.LBB0_1129:
	s_waitcnt vmcnt(0)
	v_add_f32_e32 v44, v211, v212
	v_lshl_add_u64 v[80:81], v[54:55], 0, s[2:3]
	global_load_dword v211, v[80:81], off
	v_lshl_add_u64 v[80:81], v[56:57], 0, s[2:3]
	global_load_dword v212, v[80:81], off
	s_add_u32 s2, s2, 0x400
	s_addc_u32 s3, s3, 0
	s_nop 1
	v_add_f32_dpp v47, v44, v44 quad_perm:[1,0,3,2] row_mask:0xf bank_mask:0xf bound_ctrl:1
	s_nop 1
	v_add_f32_dpp v47, v47, v47 quad_perm:[2,3,0,1] row_mask:0xf bank_mask:0xf bound_ctrl:1
	s_nop 1
	v_add_f32_dpp v47, v47, v47 row_half_mirror row_mask:0xf bank_mask:0xf bound_ctrl:1
	s_nop 1
	v_add_f32_dpp v47, v47, v47 row_mirror row_mask:0xf bank_mask:0xf bound_ctrl:1
	s_nop 0
	v_readlane_b32 s5, v47, 16
	v_readlane_b32 s9, v47, 48
	v_readlane_b32 s36, v47, 0
	v_readlane_b32 s37, v47, 32
	v_mov_b32_e32 v80, s5
	v_mov_b32_e32 v81, s9
	v_pk_add_f32 v[80:81], s[36:37], v[80:81]
	s_nop 0
	v_add_f32_e32 v47, v80, v81
	v_fmac_f32_e32 v44, 0xbc800000, v47
	v_mul_f32_e32 v47, v44, v44
	s_nop 1
	v_mov_b32_dpp v47, v47 quad_perm:[1,0,3,2] row_mask:0xf bank_mask:0xf bound_ctrl:1
	v_fmac_f32_e32 v47, v44, v44
	s_nop 1
	v_add_f32_dpp v47, v47, v47 quad_perm:[2,3,0,1] row_mask:0xf bank_mask:0xf bound_ctrl:1
	s_nop 1
	v_add_f32_dpp v47, v47, v47 row_half_mirror row_mask:0xf bank_mask:0xf bound_ctrl:1
	s_nop 1
	v_add_f32_dpp v47, v47, v47 row_mirror row_mask:0xf bank_mask:0xf bound_ctrl:1
	s_nop 0
	v_readlane_b32 s5, v47, 16
	v_readlane_b32 s9, v47, 48
	v_readlane_b32 s36, v47, 0
	v_readlane_b32 s37, v47, 32
	v_mov_b32_e32 v80, s5
	v_mov_b32_e32 v81, s9
	v_pk_add_f32 v[80:81], s[36:37], v[80:81]
	s_mov_b64 s[36:37], 0x800
	v_add_f32_e32 v47, v80, v81
	v_fmamk_f32 v47, v47, 0x3c800000, v176
	v_cmp_gt_f32_e32 vcc, s96, v47
	v_mul_f32_e32 v79, 0x4b800000, v47
	s_nop 0
	v_cndmask_b32_e32 v47, v47, v79, vcc
	v_rsq_f32_e32 v47, v47
	s_nop 0
	v_mul_f32_e32 v79, 0x45800000, v47
	v_cndmask_b32_e32 v47, v47, v79, vcc
	v_mul_f32_e32 v44, v44, v47
	v_mov_b32_e32 v47, s4
	v_mul_f32_e32 v96, v78, v44
	global_load_dword v44, v[52:53], off
	global_load_dword v98, v[50:51], off
	ds_read_b128 v[80:83], v47
	ds_read_b128 v[84:87], v47 offset:16
	ds_read_b128 v[88:91], v47 offset:32
	ds_read_b128 v[92:95], v47 offset:48
	s_addk_i32 s4, 0x100
	s_waitcnt lgkmcnt(3)
	v_mul_f32_e32 v79, v58, v81
	v_fmac_f32_e32 v79, v0, v80
	s_waitcnt lgkmcnt(2)
	v_mul_f32_e32 v80, v62, v85
	v_fmac_f32_e32 v79, v59, v82
	v_fmac_f32_e32 v80, v61, v84
	v_fmac_f32_e32 v79, v60, v83
	v_fmac_f32_e32 v80, v63, v86
	v_add_f32_e32 v79, 0, v79
	v_fmac_f32_e32 v80, v64, v87
	v_add_f32_e32 v79, v79, v80
	s_waitcnt lgkmcnt(1)
	v_mul_f32_e32 v80, v66, v89
	v_fmac_f32_e32 v80, v65, v88
	v_fmac_f32_e32 v80, v67, v90
	v_fmac_f32_e32 v80, v68, v91
	v_add_f32_e32 v79, v79, v80
	s_waitcnt lgkmcnt(0)
	v_mul_f32_e32 v80, v70, v93
	v_fmac_f32_e32 v80, v69, v92
	v_fmac_f32_e32 v80, v71, v94
	v_fmac_f32_e32 v80, v72, v95
	v_add_f32_e32 v79, v79, v80
	ds_read_b128 v[80:83], v47 offset:64
	v_lshl_add_u64 v[52:53], v[52:53], 0, 16
	s_cmpk_lg_u32 s2, 0x8c00
	s_waitcnt lgkmcnt(0)
	v_mul_f32_e32 v81, v74, v81
	v_fmac_f32_e32 v81, v73, v80
	v_fmac_f32_e32 v81, v75, v82
	v_fmac_f32_e32 v81, v76, v83
	v_add_f32_e32 v79, v79, v81
	ds_read_b128 v[80:83], v47 offset:96
	ds_read_b128 v[84:87], v47 offset:80
	s_waitcnt lgkmcnt(1)
	v_mov_b32_e32 v89, v80
	s_waitcnt lgkmcnt(0)
	v_mov_b32_e32 v80, v85
	v_mov_b32_e32 v88, v84
	v_pk_mul_f32 v[80:81], v[4:5], v[80:81]
	v_mov_b32_e32 v84, v86
	v_pk_fma_f32 v[80:81], v[2:3], v[88:89], v[80:81]
	v_mov_b32_e32 v85, v82
	v_pk_fma_f32 v[80:81], v[6:7], v[84:85], v[80:81]
	v_mov_b32_e32 v82, v87
	v_pk_fma_f32 v[80:81], v[8:9], v[82:83], v[80:81]
	s_nop 0
	v_add_f32_e32 v79, v79, v80
	v_add_f32_e32 v79, v79, v81
	ds_read_b128 v[80:83], v47 offset:128
	ds_read_b128 v[84:87], v47 offset:112
	s_waitcnt lgkmcnt(1)
	v_mov_b32_e32 v89, v80
	s_waitcnt lgkmcnt(0)
	v_mov_b32_e32 v80, v85
	v_mov_b32_e32 v88, v84
	v_pk_mul_f32 v[80:81], v[12:13], v[80:81]
	v_mov_b32_e32 v84, v86
	v_pk_fma_f32 v[80:81], v[10:11], v[88:89], v[80:81]
	v_mov_b32_e32 v85, v82
	v_pk_fma_f32 v[80:81], v[14:15], v[84:85], v[80:81]
	v_mov_b32_e32 v82, v87
	v_pk_fma_f32 v[80:81], v[16:17], v[82:83], v[80:81]
	s_nop 0
	v_add_f32_e32 v79, v79, v80
	v_add_f32_e32 v79, v79, v81
	ds_read_b128 v[80:83], v47 offset:160
	ds_read_b128 v[84:87], v47 offset:144
	s_waitcnt lgkmcnt(1)
	v_mov_b32_e32 v89, v80
	s_waitcnt lgkmcnt(0)
	v_mov_b32_e32 v80, v85
	v_mov_b32_e32 v88, v84
	v_pk_mul_f32 v[80:81], v[20:21], v[80:81]
	v_mov_b32_e32 v84, v86
	v_pk_fma_f32 v[80:81], v[18:19], v[88:89], v[80:81]
	v_mov_b32_e32 v85, v82
	v_pk_fma_f32 v[80:81], v[22:23], v[84:85], v[80:81]
	v_mov_b32_e32 v82, v87
	v_pk_fma_f32 v[80:81], v[24:25], v[82:83], v[80:81]
	s_nop 0
	v_add_f32_e32 v79, v79, v80
	v_add_f32_e32 v79, v79, v81
	ds_read_b128 v[80:83], v47 offset:192
	ds_read_b128 v[84:87], v47 offset:176
	s_waitcnt lgkmcnt(1)
	v_mov_b32_e32 v89, v80
	s_waitcnt lgkmcnt(0)
	v_mov_b32_e32 v80, v85
	v_mov_b32_e32 v88, v84
	v_pk_mul_f32 v[80:81], v[28:29], v[80:81]
	v_mov_b32_e32 v84, v86
	v_pk_fma_f32 v[80:81], v[26:27], v[88:89], v[80:81]
	v_mov_b32_e32 v85, v82
	v_pk_fma_f32 v[80:81], v[30:31], v[84:85], v[80:81]
	v_mov_b32_e32 v82, v87
	v_pk_fma_f32 v[80:81], v[32:33], v[82:83], v[80:81]
	s_nop 0
	v_add_f32_e32 v79, v79, v80
	v_add_f32_e32 v79, v79, v81
	ds_read_b128 v[80:83], v47 offset:224
	ds_read_b128 v[84:87], v47 offset:208
	s_waitcnt lgkmcnt(1)
	v_mov_b32_e32 v89, v80
	s_waitcnt lgkmcnt(0)
	v_mov_b32_e32 v80, v85
	v_mov_b32_e32 v88, v84
	v_pk_mul_f32 v[80:81], v[36:37], v[80:81]
	v_mov_b32_e32 v84, v86
	v_pk_fma_f32 v[80:81], v[34:35], v[88:89], v[80:81]
	v_mov_b32_e32 v85, v82
	v_pk_fma_f32 v[80:81], v[38:39], v[84:85], v[80:81]
	v_mov_b32_e32 v82, v87
	v_pk_fma_f32 v[80:81], v[40:41], v[82:83], v[80:81]
	s_nop 0
	v_add_f32_e32 v79, v79, v80
	v_add_f32_e32 v79, v79, v81
	ds_read_b128 v[80:83], v47 offset:240
	s_waitcnt lgkmcnt(0)
	v_mul_f32_e32 v84, v42, v80
	v_pk_fma_f32 v[80:81], v[42:43], v[80:81], v[84:85] op_sel_hi:[1,1,0]
	v_mul_f32_e32 v47, v77, v82
	v_mov_b32_e32 v97, v81
	v_pk_add_f32 v[80:81], v[46:47], v[96:97]
	v_mov_b32_e32 v99, v83
	s_waitcnt vmcnt(0)
	v_pk_fma_f32 v[80:81], v[44:45], v[98:99], v[80:81]
	s_nop 0
	v_add_f32_e32 v44, v79, v81
	v_mul_f32_e32 v44, v80, v44
	v_cvt_pk_bf16_f32 v44, v44, s0
	global_store_short v[48:49], v44, off
	v_lshl_add_u64 v[48:49], v[48:49], 0, s[36:37]
	s_mov_b64 s[36:37], 0xf00
	v_lshl_add_u64 v[50:51], v[50:51], 0, s[36:37]
	s_cbranch_scc1 .LBB0_1129
	v_readlane_b32 s2, v208, 21
	s_add_i32 s8, s8, s66
	s_add_i32 s34, s34, s2
	s_cmp_lt_i32 s8, s6
	s_barrier
	s_cbranch_scc1 .LBB0_1125
	v_readlane_b32 s42, v208, 51
	v_readlane_b32 s54, v209, 14
	v_readlane_b32 s43, v208, 52
	v_readlane_b32 s55, v209, 15
	s_mov_b32 s56, 0x10000
	s_mov_b32 s57, 0x20000
	s_mov_b32 s58, 0x30000
	s_movk_i32 s59, 0x70
	s_movk_i32 s53, 0x2000
	s_mov_b32 s52, 0xb000

.LBB0_1186:
	s_ashr_i32 s5, s4, 31
	s_lshr_b32 s5, s5, 29
	s_add_i32 s5, s4, s5
	s_ashr_i32 s34, s5, 3
	s_ashr_i32 s35, s34, 31
	v_readlane_b32 s36, v210, 50
	v_mov_b32_e32 v36, v133
	s_lshl_b64 s[6:7], s[34:35], 18
	v_readlane_b32 s38, v210, 52
	v_readlane_b32 s39, v210, 53
	v_ashrrev_i32_e32 v34, 3, v36
	s_add_u32 s6, s38, s6
	v_ashrrev_i32_e32 v35, 31, v34
	s_addc_u32 s7, s39, s7
	v_lshlrev_b64 v[2:3], 11, v[34:35]
	v_lshlrev_b32_e32 v0, 4, v36
	v_lshl_add_u64 v[2:3], s[6:7], 0, v[2:3]
	v_and_b32_e32 v0, 0x70, v0
	s_lshl_b32 s5, s34, 10
	v_lshl_add_u64 v[66:67], v[2:3], 0, v[0:1]
	v_subrev_u32_e32 v2, s5, v34
	v_add_u32_e32 v2, s3, v2
	v_ashrrev_i32_e32 v3, 31, v2
	v_lshlrev_b64 v[2:3], 11, v[2:3]
	v_lshl_add_u64 v[2:3], s[0:1], 0, v[2:3]
	v_add_co_u32_e32 v70, vcc, s10, v66
	v_lshl_add_u64 v[68:69], v[2:3], 0, v[0:1]
	s_nop 0
	v_addc_co_u32_e32 v71, vcc, 0, v67, vcc
	v_add_co_u32_e32 v72, vcc, s10, v68
	global_load_dwordx4 v[2:5], v[66:67], off
	global_load_dwordx4 v[6:9], v[68:69], off
	v_addc_co_u32_e32 v73, vcc, 0, v69, vcc
	v_add_co_u32_e32 v74, vcc, s63, v66
	global_load_dwordx4 v[10:13], v[70:71], off
	s_nop 0
	v_addc_co_u32_e32 v75, vcc, 0, v67, vcc
	v_add_co_u32_e32 v76, vcc, s63, v68
	global_load_dwordx4 v[14:17], v[72:73], off
	s_nop 0
	v_addc_co_u32_e32 v77, vcc, 0, v69, vcc
	global_load_dwordx4 v[18:21], v[74:75], off
	v_add_co_u32_e32 v78, vcc, s61, v66
	global_load_dwordx4 v[22:25], v[76:77], off
	s_nop 0
	v_addc_co_u32_e32 v79, vcc, 0, v67, vcc
	global_load_dwordx4 v[26:29], v[78:79], off
	v_add_co_u32_e32 v80, vcc, s61, v68
	v_lshlrev_b32_e32 v0, 7, v34
	s_nop 0
	v_addc_co_u32_e32 v81, vcc, 0, v69, vcc
	global_load_dwordx4 v[30:33], v[80:81], off
	global_load_dwordx4 v[94:97], v[66:67], off offset:128
	global_load_dwordx4 v[98:101], v[68:69], off offset:128
	global_load_dwordx4 v[102:105], v[70:71], off offset:128
	global_load_dwordx4 v[106:109], v[72:73], off offset:128
	global_load_dwordx4 v[110:113], v[74:75], off offset:128
	global_load_dwordx4 v[114:117], v[76:77], off offset:128
	global_load_dwordx4 v[118:121], v[78:79], off offset:128
	global_load_dwordx4 v[122:125], v[80:81], off offset:128
	v_lshrrev_b32_e32 v34, 1, v34
	v_xor_b32_e32 v34, v34, v36
	v_lshlrev_b32_e32 v34, 4, v34
	s_movk_i32 s6, 0x70
	v_and_or_b32 v0, v34, s6, v0
	s_waitcnt vmcnt(26)
	v_and_b32_e32 v82, 31, v36
	v_bfe_u32 v85, v36, 5, 1
	v_ashrrev_i32_e32 v84, 7, v36
	v_bfe_u32 v83, v36, 6, 1
	v_readlane_b32 s37, v210, 51
	v_readlane_b32 s40, v210, 54
	v_readlane_b32 s41, v210, 55
	v_readlane_b32 s42, v210, 56
	v_readlane_b32 s43, v210, 57
	v_readlane_b32 s44, v210, 58
	v_readlane_b32 s45, v210, 59
	v_readlane_b32 s46, v210, 60
	v_readlane_b32 s47, v210, 61
	v_readlane_b32 s48, v210, 62
	v_readlane_b32 s49, v210, 63
	v_readlane_b32 s50, v209, 0
	v_readlane_b32 s51, v209, 1
	s_waitcnt vmcnt(15)
	ds_write_b128 v0, v[2:5]
	s_waitcnt vmcnt(14)
	ds_write_b128 v0, v[6:9] offset:32768
	s_waitcnt vmcnt(13)
	ds_write_b128 v0, v[10:13] offset:4096
	s_waitcnt vmcnt(12)
	ds_write_b128 v0, v[14:17] offset:36864
	s_waitcnt vmcnt(11)
	ds_write_b128 v0, v[18:21] offset:8192
	s_waitcnt vmcnt(10)
	ds_write_b128 v0, v[22:25] offset:40960
	s_waitcnt vmcnt(9)
	ds_write_b128 v0, v[26:29] offset:12288
	s_waitcnt vmcnt(8)
	ds_write_b128 v0, v[30:33] offset:45056
	s_waitcnt lgkmcnt(0)
	s_barrier
	global_load_dwordx4 v[126:129], v[66:67], off offset:256
	global_load_dwordx4 v[134:137], v[68:69], off offset:256
	global_load_dwordx4 v[138:141], v[70:71], off offset:256
	global_load_dwordx4 v[142:145], v[72:73], off offset:256
	global_load_dwordx4 v[146:149], v[74:75], off offset:256
	global_load_dwordx4 v[150:153], v[76:77], off offset:256
	global_load_dwordx4 v[154:157], v[78:79], off offset:256
	global_load_dwordx4 v[158:161], v[80:81], off offset:256
	s_waitcnt vmcnt(15)
	ds_write_b128 v0, v[94:97] offset:16384
	s_waitcnt vmcnt(14)
	ds_write_b128 v0, v[98:101] offset:49152
	s_waitcnt vmcnt(13)
	ds_write_b128 v0, v[102:105] offset:20480
	s_waitcnt vmcnt(12)
	ds_write_b128 v0, v[106:109] offset:53248
	s_waitcnt vmcnt(11)
	ds_write_b128 v0, v[110:113] offset:24576
	s_waitcnt vmcnt(10)
	ds_write_b128 v0, v[114:117] offset:57344
	s_waitcnt vmcnt(9)
	ds_write_b128 v0, v[118:121] offset:28672
	s_waitcnt vmcnt(8)
	ds_write_b128 v0, v[122:125] offset:61440
	v_lshrrev_b32_e32 v4, 1, v36
	v_lshlrev_b32_e32 v2, 7, v82
	v_bitop3_b32 v4, v4, v85, 7 bitop3:0x6c
	v_lshl_or_b32 v3, v84, 13, v2
	v_bfe_u32 v5, v36, 1, 3
	v_lshlrev_b32_e32 v4, 4, v4
	v_lshl_or_b32 v2, v83, 13, v2
	v_or_b32_e32 v91, v3, v4
	v_or_b32_e32 v92, v2, v4
	v_bitop3_b32 v4, v85, v5, 2 bitop3:0x36
	v_lshlrev_b32_e32 v4, 4, v4
	v_or_b32_e32 v93, v3, v4
	v_or_b32_e32 v90, v2, v4
	v_bitop3_b32 v4, v85, v5, 4 bitop3:0x36
	v_lshlrev_b32_e32 v4, 4, v4
	v_or_b32_e32 v89, v3, v4
	v_or_b32_e32 v88, v2, v4
	v_bitop3_b32 v4, v85, v5, 6 bitop3:0x36
	v_lshlrev_b32_e32 v4, 4, v4
	v_or_b32_e32 v87, v3, v4
	v_or_b32_e32 v86, v2, v4
	ds_read_b128 v[2:5], v91
	ds_read_b128 v[6:9], v92 offset:32768
	ds_read_b128 v[10:13], v91 offset:4096
	ds_read_b128 v[14:17], v92 offset:36864
	ds_read_b128 v[162:165], v93
	ds_read_b128 v[166:169], v90 offset:32768
	ds_read_b128 v[182:185], v93 offset:4096
	ds_read_b128 v[186:189], v90 offset:36864
	s_waitcnt lgkmcnt(6)
	v_mfma_f32_32x32x16_bf16 v[50:65], v[2:5], v[6:9], 0
	s_waitcnt lgkmcnt(4)
	v_mfma_f32_32x32x16_bf16 v[18:33], v[2:5], v[14:17], 0
	v_mfma_f32_32x32x16_bf16 v[34:49], v[10:13], v[6:9], 0
	v_mfma_f32_32x32x16_bf16 v[2:17], v[10:13], v[14:17], 0
	ds_read_b128 v[190:193], v89
	ds_read_b128 v[194:197], v89 offset:4096
	ds_read_b128 v[198:201], v88 offset:32768
	ds_read_b128 v[202:205], v88 offset:36864
	s_waitcnt lgkmcnt(6)
	v_mfma_f32_32x32x16_bf16 v[50:65], v[162:165], v[166:169], v[50:65]
	s_waitcnt lgkmcnt(4)
	v_mfma_f32_32x32x16_bf16 v[18:33], v[162:165], v[186:189], v[18:33]
	v_mfma_f32_32x32x16_bf16 v[34:49], v[182:185], v[166:169], v[34:49]
	v_mfma_f32_32x32x16_bf16 v[2:17], v[182:185], v[186:189], v[2:17]
	ds_read_b128 v[162:165], v87
	ds_read_b128 v[166:169], v87 offset:4096
	ds_read_b128 v[182:185], v86 offset:32768
	ds_read_b128 v[186:189], v86 offset:36864
	s_waitcnt lgkmcnt(0)
	s_barrier
	global_load_dwordx4 v[94:97], v[66:67], off offset:384
	global_load_dwordx4 v[98:101], v[68:69], off offset:384
	global_load_dwordx4 v[102:105], v[70:71], off offset:384
	global_load_dwordx4 v[106:109], v[72:73], off offset:384
	global_load_dwordx4 v[110:113], v[74:75], off offset:384
	global_load_dwordx4 v[114:117], v[76:77], off offset:384
	global_load_dwordx4 v[118:121], v[78:79], off offset:384
	global_load_dwordx4 v[122:125], v[80:81], off offset:384
	s_waitcnt vmcnt(15)
	ds_write_b128 v0, v[126:129]
	s_waitcnt vmcnt(14)
	ds_write_b128 v0, v[134:137] offset:32768
	s_waitcnt vmcnt(13)
	ds_write_b128 v0, v[138:141] offset:4096
	s_waitcnt vmcnt(12)
	ds_write_b128 v0, v[142:145] offset:36864
	s_waitcnt vmcnt(11)
	ds_write_b128 v0, v[146:149] offset:8192
	s_waitcnt vmcnt(10)
	ds_write_b128 v0, v[150:153] offset:40960
	s_waitcnt vmcnt(9)
	ds_write_b128 v0, v[154:157] offset:12288
	s_waitcnt vmcnt(8)
	ds_write_b128 v0, v[158:161] offset:45056
	v_mfma_f32_32x32x16_bf16 v[50:65], v[190:193], v[198:201], v[50:65]
	v_mfma_f32_32x32x16_bf16 v[18:33], v[190:193], v[202:205], v[18:33]
	v_mfma_f32_32x32x16_bf16 v[34:49], v[194:197], v[198:201], v[34:49]
	v_mfma_f32_32x32x16_bf16 v[2:17], v[194:197], v[202:205], v[2:17]
	v_mfma_f32_32x32x16_bf16 v[50:65], v[162:165], v[182:185], v[50:65]
	v_mfma_f32_32x32x16_bf16 v[18:33], v[162:165], v[186:189], v[18:33]
	v_mfma_f32_32x32x16_bf16 v[34:49], v[166:169], v[182:185], v[34:49]
	v_mfma_f32_32x32x16_bf16 v[2:17], v[166:169], v[186:189], v[2:17]
	ds_read_b128 v[162:165], v91 offset:16384
	ds_read_b128 v[166:169], v92 offset:49152
	ds_read_b128 v[182:185], v91 offset:20480
	ds_read_b128 v[186:189], v92 offset:53248
	ds_read_b128 v[190:193], v93 offset:16384
	ds_read_b128 v[194:197], v90 offset:49152
	ds_read_b128 v[198:201], v93 offset:20480
	ds_read_b128 v[202:205], v90 offset:53248
	s_waitcnt lgkmcnt(6)
	v_mfma_f32_32x32x16_bf16 v[50:65], v[162:165], v[166:169], v[50:65]
	s_waitcnt lgkmcnt(4)
	v_mfma_f32_32x32x16_bf16 v[18:33], v[162:165], v[186:189], v[18:33]
	v_mfma_f32_32x32x16_bf16 v[34:49], v[182:185], v[166:169], v[34:49]
	v_mfma_f32_32x32x16_bf16 v[2:17], v[182:185], v[186:189], v[2:17]
	ds_read_b128 v[162:165], v89 offset:16384
	ds_read_b128 v[166:169], v89 offset:20480
	ds_read_b128 v[182:185], v88 offset:49152
	ds_read_b128 v[186:189], v88 offset:53248
	s_waitcnt lgkmcnt(6)
	v_mfma_f32_32x32x16_bf16 v[50:65], v[190:193], v[194:197], v[50:65]
	s_waitcnt lgkmcnt(4)
	v_mfma_f32_32x32x16_bf16 v[18:33], v[190:193], v[202:205], v[18:33]
	v_mfma_f32_32x32x16_bf16 v[34:49], v[198:201], v[194:197], v[34:49]
	v_mfma_f32_32x32x16_bf16 v[2:17], v[198:201], v[202:205], v[2:17]
	ds_read_b128 v[190:193], v87 offset:16384
	ds_read_b128 v[194:197], v87 offset:20480
	ds_read_b128 v[198:201], v86 offset:49152
	ds_read_b128 v[202:205], v86 offset:53248
	s_waitcnt lgkmcnt(0)
	s_barrier
	global_load_dwordx4 v[126:129], v[66:67], off offset:512
	global_load_dwordx4 v[134:137], v[68:69], off offset:512
	global_load_dwordx4 v[138:141], v[70:71], off offset:512
	global_load_dwordx4 v[142:145], v[72:73], off offset:512
	global_load_dwordx4 v[146:149], v[74:75], off offset:512
	global_load_dwordx4 v[150:153], v[76:77], off offset:512
	global_load_dwordx4 v[154:157], v[78:79], off offset:512
	global_load_dwordx4 v[158:161], v[80:81], off offset:512
	s_waitcnt vmcnt(15)
	ds_write_b128 v0, v[94:97] offset:16384
	s_waitcnt vmcnt(14)
	ds_write_b128 v0, v[98:101] offset:49152
	s_waitcnt vmcnt(13)
	ds_write_b128 v0, v[102:105] offset:20480
	s_waitcnt vmcnt(12)
	ds_write_b128 v0, v[106:109] offset:53248
	s_waitcnt vmcnt(11)
	ds_write_b128 v0, v[110:113] offset:24576
	s_waitcnt vmcnt(10)
	ds_write_b128 v0, v[114:117] offset:57344
	s_waitcnt vmcnt(9)
	ds_write_b128 v0, v[118:121] offset:28672
	s_waitcnt vmcnt(8)
	ds_write_b128 v0, v[122:125] offset:61440
	v_mfma_f32_32x32x16_bf16 v[50:65], v[162:165], v[182:185], v[50:65]
	v_mfma_f32_32x32x16_bf16 v[18:33], v[162:165], v[186:189], v[18:33]
	v_mfma_f32_32x32x16_bf16 v[34:49], v[166:169], v[182:185], v[34:49]
	v_mfma_f32_32x32x16_bf16 v[2:17], v[166:169], v[186:189], v[2:17]
	v_mfma_f32_32x32x16_bf16 v[50:65], v[190:193], v[198:201], v[50:65]
	v_mfma_f32_32x32x16_bf16 v[18:33], v[190:193], v[202:205], v[18:33]
	v_mfma_f32_32x32x16_bf16 v[34:49], v[194:197], v[198:201], v[34:49]
	v_mfma_f32_32x32x16_bf16 v[2:17], v[194:197], v[202:205], v[2:17]
	ds_read_b128 v[162:165], v91
	ds_read_b128 v[166:169], v92 offset:32768
	ds_read_b128 v[182:185], v91 offset:4096
	ds_read_b128 v[186:189], v92 offset:36864
	ds_read_b128 v[190:193], v93
	ds_read_b128 v[194:197], v90 offset:32768
	ds_read_b128 v[198:201], v93 offset:4096
	ds_read_b128 v[202:205], v90 offset:36864
	s_waitcnt lgkmcnt(6)
	v_mfma_f32_32x32x16_bf16 v[50:65], v[162:165], v[166:169], v[50:65]
	s_waitcnt lgkmcnt(4)
	v_mfma_f32_32x32x16_bf16 v[18:33], v[162:165], v[186:189], v[18:33]
	v_mfma_f32_32x32x16_bf16 v[34:49], v[182:185], v[166:169], v[34:49]
	v_mfma_f32_32x32x16_bf16 v[2:17], v[182:185], v[186:189], v[2:17]
	ds_read_b128 v[162:165], v89
	ds_read_b128 v[166:169], v89 offset:4096
	ds_read_b128 v[182:185], v88 offset:32768
	ds_read_b128 v[186:189], v88 offset:36864
	s_waitcnt lgkmcnt(6)
	v_mfma_f32_32x32x16_bf16 v[50:65], v[190:193], v[194:197], v[50:65]
	s_waitcnt lgkmcnt(4)
	v_mfma_f32_32x32x16_bf16 v[18:33], v[190:193], v[202:205], v[18:33]
	v_mfma_f32_32x32x16_bf16 v[34:49], v[198:201], v[194:197], v[34:49]
	v_mfma_f32_32x32x16_bf16 v[2:17], v[198:201], v[202:205], v[2:17]
	ds_read_b128 v[190:193], v87
	ds_read_b128 v[194:197], v87 offset:4096
	ds_read_b128 v[198:201], v86 offset:32768
	ds_read_b128 v[202:205], v86 offset:36864
	s_waitcnt lgkmcnt(0)
	s_barrier
	global_load_dwordx4 v[94:97], v[66:67], off offset:640
	global_load_dwordx4 v[98:101], v[68:69], off offset:640
	global_load_dwordx4 v[102:105], v[70:71], off offset:640
	global_load_dwordx4 v[106:109], v[72:73], off offset:640
	global_load_dwordx4 v[110:113], v[74:75], off offset:640
	global_load_dwordx4 v[114:117], v[76:77], off offset:640
	global_load_dwordx4 v[118:121], v[78:79], off offset:640
	global_load_dwordx4 v[122:125], v[80:81], off offset:640
	s_waitcnt vmcnt(15)
	ds_write_b128 v0, v[126:129]
	s_waitcnt vmcnt(14)
	ds_write_b128 v0, v[134:137] offset:32768
	s_waitcnt vmcnt(13)
	ds_write_b128 v0, v[138:141] offset:4096
	s_waitcnt vmcnt(12)
	ds_write_b128 v0, v[142:145] offset:36864
	s_waitcnt vmcnt(11)
	ds_write_b128 v0, v[146:149] offset:8192
	s_waitcnt vmcnt(10)
	ds_write_b128 v0, v[150:153] offset:40960
	s_waitcnt vmcnt(9)
	ds_write_b128 v0, v[154:157] offset:12288
	s_waitcnt vmcnt(8)
	ds_write_b128 v0, v[158:161] offset:45056
	v_mfma_f32_32x32x16_bf16 v[50:65], v[162:165], v[182:185], v[50:65]
	v_mfma_f32_32x32x16_bf16 v[18:33], v[162:165], v[186:189], v[18:33]
	v_mfma_f32_32x32x16_bf16 v[34:49], v[166:169], v[182:185], v[34:49]
	v_mfma_f32_32x32x16_bf16 v[2:17], v[166:169], v[186:189], v[2:17]
	v_mfma_f32_32x32x16_bf16 v[50:65], v[190:193], v[198:201], v[50:65]
	v_mfma_f32_32x32x16_bf16 v[18:33], v[190:193], v[202:205], v[18:33]
	v_mfma_f32_32x32x16_bf16 v[34:49], v[194:197], v[198:201], v[34:49]
	v_mfma_f32_32x32x16_bf16 v[2:17], v[194:197], v[202:205], v[2:17]
	ds_read_b128 v[162:165], v91 offset:16384
	ds_read_b128 v[166:169], v92 offset:49152
	ds_read_b128 v[182:185], v91 offset:20480
	ds_read_b128 v[186:189], v92 offset:53248
	ds_read_b128 v[190:193], v93 offset:16384
	ds_read_b128 v[194:197], v90 offset:49152
	ds_read_b128 v[198:201], v93 offset:20480
	ds_read_b128 v[202:205], v90 offset:53248
	s_waitcnt lgkmcnt(6)
	v_mfma_f32_32x32x16_bf16 v[50:65], v[162:165], v[166:169], v[50:65]
	s_waitcnt lgkmcnt(4)
	v_mfma_f32_32x32x16_bf16 v[18:33], v[162:165], v[186:189], v[18:33]
	v_mfma_f32_32x32x16_bf16 v[34:49], v[182:185], v[166:169], v[34:49]
	v_mfma_f32_32x32x16_bf16 v[2:17], v[182:185], v[186:189], v[2:17]
	ds_read_b128 v[162:165], v89 offset:16384
	ds_read_b128 v[166:169], v89 offset:20480
	ds_read_b128 v[182:185], v88 offset:49152
	ds_read_b128 v[186:189], v88 offset:53248
	s_waitcnt lgkmcnt(6)
	v_mfma_f32_32x32x16_bf16 v[50:65], v[190:193], v[194:197], v[50:65]
	s_waitcnt lgkmcnt(4)
	v_mfma_f32_32x32x16_bf16 v[18:33], v[190:193], v[202:205], v[18:33]
	v_mfma_f32_32x32x16_bf16 v[34:49], v[198:201], v[194:197], v[34:49]
	v_mfma_f32_32x32x16_bf16 v[2:17], v[198:201], v[202:205], v[2:17]
	ds_read_b128 v[190:193], v87 offset:16384
	ds_read_b128 v[194:197], v87 offset:20480
	ds_read_b128 v[198:201], v86 offset:49152
	ds_read_b128 v[202:205], v86 offset:53248
	s_waitcnt lgkmcnt(0)
	s_barrier
	global_load_dwordx4 v[126:129], v[66:67], off offset:768
	global_load_dwordx4 v[134:137], v[68:69], off offset:768
	global_load_dwordx4 v[138:141], v[70:71], off offset:768
	global_load_dwordx4 v[142:145], v[72:73], off offset:768
	global_load_dwordx4 v[146:149], v[74:75], off offset:768
	global_load_dwordx4 v[150:153], v[76:77], off offset:768
	global_load_dwordx4 v[154:157], v[78:79], off offset:768
	global_load_dwordx4 v[158:161], v[80:81], off offset:768
	s_waitcnt vmcnt(15)
	ds_write_b128 v0, v[94:97] offset:16384
	s_waitcnt vmcnt(14)
	ds_write_b128 v0, v[98:101] offset:49152
	s_waitcnt vmcnt(13)
	ds_write_b128 v0, v[102:105] offset:20480
	s_waitcnt vmcnt(12)
	ds_write_b128 v0, v[106:109] offset:53248
	s_waitcnt vmcnt(11)
	ds_write_b128 v0, v[110:113] offset:24576
	s_waitcnt vmcnt(10)
	ds_write_b128 v0, v[114:117] offset:57344
	s_waitcnt vmcnt(9)
	ds_write_b128 v0, v[118:121] offset:28672
	s_waitcnt vmcnt(8)
	ds_write_b128 v0, v[122:125] offset:61440
	v_mfma_f32_32x32x16_bf16 v[50:65], v[162:165], v[182:185], v[50:65]
	v_mfma_f32_32x32x16_bf16 v[18:33], v[162:165], v[186:189], v[18:33]
	v_mfma_f32_32x32x16_bf16 v[34:49], v[166:169], v[182:185], v[34:49]
	v_mfma_f32_32x32x16_bf16 v[2:17], v[166:169], v[186:189], v[2:17]
	v_mfma_f32_32x32x16_bf16 v[50:65], v[190:193], v[198:201], v[50:65]
	v_mfma_f32_32x32x16_bf16 v[18:33], v[190:193], v[202:205], v[18:33]
	v_mfma_f32_32x32x16_bf16 v[34:49], v[194:197], v[198:201], v[34:49]
	v_mfma_f32_32x32x16_bf16 v[2:17], v[194:197], v[202:205], v[2:17]
	ds_read_b128 v[162:165], v91
	ds_read_b128 v[166:169], v92 offset:32768
	ds_read_b128 v[182:185], v91 offset:4096
	ds_read_b128 v[186:189], v92 offset:36864
	ds_read_b128 v[190:193], v93
	ds_read_b128 v[194:197], v90 offset:32768
	ds_read_b128 v[198:201], v93 offset:4096
	ds_read_b128 v[202:205], v90 offset:36864
	s_waitcnt lgkmcnt(6)
	v_mfma_f32_32x32x16_bf16 v[50:65], v[162:165], v[166:169], v[50:65]
	s_waitcnt lgkmcnt(4)
	v_mfma_f32_32x32x16_bf16 v[18:33], v[162:165], v[186:189], v[18:33]
	v_mfma_f32_32x32x16_bf16 v[34:49], v[182:185], v[166:169], v[34:49]
	v_mfma_f32_32x32x16_bf16 v[2:17], v[182:185], v[186:189], v[2:17]
	ds_read_b128 v[162:165], v89
	ds_read_b128 v[166:169], v89 offset:4096
	ds_read_b128 v[182:185], v88 offset:32768
	ds_read_b128 v[186:189], v88 offset:36864
	s_waitcnt lgkmcnt(6)
	v_mfma_f32_32x32x16_bf16 v[50:65], v[190:193], v[194:197], v[50:65]
	s_waitcnt lgkmcnt(4)
	v_mfma_f32_32x32x16_bf16 v[18:33], v[190:193], v[202:205], v[18:33]
	v_mfma_f32_32x32x16_bf16 v[34:49], v[198:201], v[194:197], v[34:49]
	v_mfma_f32_32x32x16_bf16 v[2:17], v[198:201], v[202:205], v[2:17]
	ds_read_b128 v[190:193], v87
	ds_read_b128 v[194:197], v87 offset:4096
	ds_read_b128 v[198:201], v86 offset:32768
	ds_read_b128 v[202:205], v86 offset:36864
	s_waitcnt lgkmcnt(0)
	s_barrier
	global_load_dwordx4 v[94:97], v[66:67], off offset:896
	global_load_dwordx4 v[98:101], v[68:69], off offset:896
	global_load_dwordx4 v[102:105], v[70:71], off offset:896
	global_load_dwordx4 v[106:109], v[72:73], off offset:896
	global_load_dwordx4 v[110:113], v[74:75], off offset:896
	global_load_dwordx4 v[114:117], v[76:77], off offset:896
	global_load_dwordx4 v[118:121], v[78:79], off offset:896
	global_load_dwordx4 v[122:125], v[80:81], off offset:896
	s_waitcnt vmcnt(15)
	ds_write_b128 v0, v[126:129]
	s_waitcnt vmcnt(14)
	ds_write_b128 v0, v[134:137] offset:32768
	s_waitcnt vmcnt(13)
	ds_write_b128 v0, v[138:141] offset:4096
	s_waitcnt vmcnt(12)
	ds_write_b128 v0, v[142:145] offset:36864
	s_waitcnt vmcnt(11)
	ds_write_b128 v0, v[146:149] offset:8192
	s_waitcnt vmcnt(10)
	ds_write_b128 v0, v[150:153] offset:40960
	s_waitcnt vmcnt(9)
	ds_write_b128 v0, v[154:157] offset:12288
	s_waitcnt vmcnt(8)
	ds_write_b128 v0, v[158:161] offset:45056
	v_mfma_f32_32x32x16_bf16 v[50:65], v[162:165], v[182:185], v[50:65]
	v_mfma_f32_32x32x16_bf16 v[18:33], v[162:165], v[186:189], v[18:33]
	v_mfma_f32_32x32x16_bf16 v[34:49], v[166:169], v[182:185], v[34:49]
	v_mfma_f32_32x32x16_bf16 v[2:17], v[166:169], v[186:189], v[2:17]
	v_mfma_f32_32x32x16_bf16 v[50:65], v[190:193], v[198:201], v[50:65]
	v_mfma_f32_32x32x16_bf16 v[18:33], v[190:193], v[202:205], v[18:33]
	v_mfma_f32_32x32x16_bf16 v[34:49], v[194:197], v[198:201], v[34:49]
	v_mfma_f32_32x32x16_bf16 v[2:17], v[194:197], v[202:205], v[2:17]
	ds_read_b128 v[162:165], v91 offset:16384
	ds_read_b128 v[166:169], v92 offset:49152
	ds_read_b128 v[182:185], v91 offset:20480
	ds_read_b128 v[186:189], v92 offset:53248
	ds_read_b128 v[190:193], v93 offset:16384
	ds_read_b128 v[194:197], v90 offset:49152
	ds_read_b128 v[198:201], v93 offset:20480
	ds_read_b128 v[202:205], v90 offset:53248
	s_waitcnt lgkmcnt(6)
	v_mfma_f32_32x32x16_bf16 v[50:65], v[162:165], v[166:169], v[50:65]
	s_waitcnt lgkmcnt(4)
	v_mfma_f32_32x32x16_bf16 v[18:33], v[162:165], v[186:189], v[18:33]
	v_mfma_f32_32x32x16_bf16 v[34:49], v[182:185], v[166:169], v[34:49]
	v_mfma_f32_32x32x16_bf16 v[2:17], v[182:185], v[186:189], v[2:17]
	ds_read_b128 v[162:165], v89 offset:16384
	ds_read_b128 v[166:169], v89 offset:20480
	ds_read_b128 v[182:185], v88 offset:49152
	ds_read_b128 v[186:189], v88 offset:53248
	s_waitcnt lgkmcnt(6)
	v_mfma_f32_32x32x16_bf16 v[50:65], v[190:193], v[194:197], v[50:65]
	s_waitcnt lgkmcnt(4)
	v_mfma_f32_32x32x16_bf16 v[18:33], v[190:193], v[202:205], v[18:33]
	v_mfma_f32_32x32x16_bf16 v[34:49], v[198:201], v[194:197], v[34:49]
	v_mfma_f32_32x32x16_bf16 v[2:17], v[198:201], v[202:205], v[2:17]
	ds_read_b128 v[190:193], v87 offset:16384
	ds_read_b128 v[194:197], v87 offset:20480
	ds_read_b128 v[198:201], v86 offset:49152
	ds_read_b128 v[202:205], v86 offset:53248
	s_waitcnt lgkmcnt(0)
	s_barrier
	global_load_dwordx4 v[126:129], v[66:67], off offset:1024
	global_load_dwordx4 v[134:137], v[68:69], off offset:1024
	global_load_dwordx4 v[138:141], v[70:71], off offset:1024
	global_load_dwordx4 v[142:145], v[72:73], off offset:1024
	global_load_dwordx4 v[146:149], v[74:75], off offset:1024
	global_load_dwordx4 v[150:153], v[76:77], off offset:1024
	global_load_dwordx4 v[154:157], v[78:79], off offset:1024
	global_load_dwordx4 v[158:161], v[80:81], off offset:1024
	s_waitcnt vmcnt(15)
	ds_write_b128 v0, v[94:97] offset:16384
	s_waitcnt vmcnt(14)
	ds_write_b128 v0, v[98:101] offset:49152
	s_waitcnt vmcnt(13)
	ds_write_b128 v0, v[102:105] offset:20480
	s_waitcnt vmcnt(12)
	ds_write_b128 v0, v[106:109] offset:53248
	s_waitcnt vmcnt(11)
	ds_write_b128 v0, v[110:113] offset:24576
	s_waitcnt vmcnt(10)
	ds_write_b128 v0, v[114:117] offset:57344
	s_waitcnt vmcnt(9)
	ds_write_b128 v0, v[118:121] offset:28672
	s_waitcnt vmcnt(8)
	ds_write_b128 v0, v[122:125] offset:61440
	v_mfma_f32_32x32x16_bf16 v[50:65], v[162:165], v[182:185], v[50:65]
	v_mfma_f32_32x32x16_bf16 v[18:33], v[162:165], v[186:189], v[18:33]
	v_mfma_f32_32x32x16_bf16 v[34:49], v[166:169], v[182:185], v[34:49]
	v_mfma_f32_32x32x16_bf16 v[2:17], v[166:169], v[186:189], v[2:17]
	v_mfma_f32_32x32x16_bf16 v[50:65], v[190:193], v[198:201], v[50:65]
	v_mfma_f32_32x32x16_bf16 v[18:33], v[190:193], v[202:205], v[18:33]
	v_mfma_f32_32x32x16_bf16 v[34:49], v[194:197], v[198:201], v[34:49]
	v_mfma_f32_32x32x16_bf16 v[2:17], v[194:197], v[202:205], v[2:17]
	ds_read_b128 v[162:165], v91
	ds_read_b128 v[166:169], v92 offset:32768
	ds_read_b128 v[182:185], v91 offset:4096
	ds_read_b128 v[186:189], v92 offset:36864
	ds_read_b128 v[190:193], v93
	ds_read_b128 v[194:197], v90 offset:32768
	ds_read_b128 v[198:201], v93 offset:4096
	ds_read_b128 v[202:205], v90 offset:36864
	s_waitcnt lgkmcnt(6)
	v_mfma_f32_32x32x16_bf16 v[50:65], v[162:165], v[166:169], v[50:65]
	s_waitcnt lgkmcnt(4)
	v_mfma_f32_32x32x16_bf16 v[18:33], v[162:165], v[186:189], v[18:33]
	v_mfma_f32_32x32x16_bf16 v[34:49], v[182:185], v[166:169], v[34:49]
	v_mfma_f32_32x32x16_bf16 v[2:17], v[182:185], v[186:189], v[2:17]
	ds_read_b128 v[162:165], v89
	ds_read_b128 v[166:169], v89 offset:4096
	ds_read_b128 v[182:185], v88 offset:32768
	ds_read_b128 v[186:189], v88 offset:36864
	s_waitcnt lgkmcnt(6)
	v_mfma_f32_32x32x16_bf16 v[50:65], v[190:193], v[194:197], v[50:65]
	s_waitcnt lgkmcnt(4)
	v_mfma_f32_32x32x16_bf16 v[18:33], v[190:193], v[202:205], v[18:33]
	v_mfma_f32_32x32x16_bf16 v[34:49], v[198:201], v[194:197], v[34:49]
	v_mfma_f32_32x32x16_bf16 v[2:17], v[198:201], v[202:205], v[2:17]
	ds_read_b128 v[190:193], v87
	ds_read_b128 v[194:197], v87 offset:4096
	ds_read_b128 v[198:201], v86 offset:32768
	ds_read_b128 v[202:205], v86 offset:36864
	s_waitcnt lgkmcnt(0)
	s_barrier
	global_load_dwordx4 v[94:97], v[66:67], off offset:1152
	global_load_dwordx4 v[98:101], v[68:69], off offset:1152
	global_load_dwordx4 v[102:105], v[70:71], off offset:1152
	global_load_dwordx4 v[106:109], v[72:73], off offset:1152
	global_load_dwordx4 v[110:113], v[74:75], off offset:1152
	global_load_dwordx4 v[114:117], v[76:77], off offset:1152
	global_load_dwordx4 v[118:121], v[78:79], off offset:1152
	global_load_dwordx4 v[122:125], v[80:81], off offset:1152
	s_waitcnt vmcnt(15)
	ds_write_b128 v0, v[126:129]
	s_waitcnt vmcnt(14)
	ds_write_b128 v0, v[134:137] offset:32768
	s_waitcnt vmcnt(13)
	ds_write_b128 v0, v[138:141] offset:4096
	s_waitcnt vmcnt(12)
	ds_write_b128 v0, v[142:145] offset:36864
	s_waitcnt vmcnt(11)
	ds_write_b128 v0, v[146:149] offset:8192
	s_waitcnt vmcnt(10)
	ds_write_b128 v0, v[150:153] offset:40960
	s_waitcnt vmcnt(9)
	ds_write_b128 v0, v[154:157] offset:12288
	s_waitcnt vmcnt(8)
	ds_write_b128 v0, v[158:161] offset:45056
	v_mfma_f32_32x32x16_bf16 v[50:65], v[162:165], v[182:185], v[50:65]
	v_mfma_f32_32x32x16_bf16 v[18:33], v[162:165], v[186:189], v[18:33]
	v_mfma_f32_32x32x16_bf16 v[34:49], v[166:169], v[182:185], v[34:49]
	v_mfma_f32_32x32x16_bf16 v[2:17], v[166:169], v[186:189], v[2:17]
	v_mfma_f32_32x32x16_bf16 v[50:65], v[190:193], v[198:201], v[50:65]
	v_mfma_f32_32x32x16_bf16 v[18:33], v[190:193], v[202:205], v[18:33]
	v_mfma_f32_32x32x16_bf16 v[34:49], v[194:197], v[198:201], v[34:49]
	v_mfma_f32_32x32x16_bf16 v[2:17], v[194:197], v[202:205], v[2:17]
	ds_read_b128 v[162:165], v91 offset:16384
	ds_read_b128 v[166:169], v92 offset:49152
	ds_read_b128 v[182:185], v91 offset:20480
	ds_read_b128 v[186:189], v92 offset:53248
	ds_read_b128 v[190:193], v93 offset:16384
	ds_read_b128 v[194:197], v90 offset:49152
	ds_read_b128 v[198:201], v93 offset:20480
	ds_read_b128 v[202:205], v90 offset:53248
	s_waitcnt lgkmcnt(6)
	v_mfma_f32_32x32x16_bf16 v[50:65], v[162:165], v[166:169], v[50:65]
	s_waitcnt lgkmcnt(4)
	v_mfma_f32_32x32x16_bf16 v[18:33], v[162:165], v[186:189], v[18:33]
	v_mfma_f32_32x32x16_bf16 v[34:49], v[182:185], v[166:169], v[34:49]
	v_mfma_f32_32x32x16_bf16 v[2:17], v[182:185], v[186:189], v[2:17]
	ds_read_b128 v[162:165], v89 offset:16384
	ds_read_b128 v[166:169], v89 offset:20480
	ds_read_b128 v[182:185], v88 offset:49152
	ds_read_b128 v[186:189], v88 offset:53248
	s_waitcnt lgkmcnt(6)
	v_mfma_f32_32x32x16_bf16 v[50:65], v[190:193], v[194:197], v[50:65]
	s_waitcnt lgkmcnt(4)
	v_mfma_f32_32x32x16_bf16 v[18:33], v[190:193], v[202:205], v[18:33]
	v_mfma_f32_32x32x16_bf16 v[34:49], v[198:201], v[194:197], v[34:49]
	v_mfma_f32_32x32x16_bf16 v[2:17], v[198:201], v[202:205], v[2:17]
	ds_read_b128 v[190:193], v87 offset:16384
	ds_read_b128 v[194:197], v87 offset:20480
	ds_read_b128 v[198:201], v86 offset:49152
	ds_read_b128 v[202:205], v86 offset:53248
	s_waitcnt lgkmcnt(0)
	s_barrier
	global_load_dwordx4 v[126:129], v[66:67], off offset:1280
	global_load_dwordx4 v[134:137], v[68:69], off offset:1280
	global_load_dwordx4 v[138:141], v[70:71], off offset:1280
	global_load_dwordx4 v[142:145], v[72:73], off offset:1280
	global_load_dwordx4 v[146:149], v[74:75], off offset:1280
	global_load_dwordx4 v[150:153], v[76:77], off offset:1280
	global_load_dwordx4 v[154:157], v[78:79], off offset:1280
	global_load_dwordx4 v[158:161], v[80:81], off offset:1280
	s_waitcnt vmcnt(15)
	ds_write_b128 v0, v[94:97] offset:16384
	s_waitcnt vmcnt(14)
	ds_write_b128 v0, v[98:101] offset:49152
	s_waitcnt vmcnt(13)
	ds_write_b128 v0, v[102:105] offset:20480
	s_waitcnt vmcnt(12)
	ds_write_b128 v0, v[106:109] offset:53248
	s_waitcnt vmcnt(11)
	ds_write_b128 v0, v[110:113] offset:24576
	s_waitcnt vmcnt(10)
	ds_write_b128 v0, v[114:117] offset:57344
	s_waitcnt vmcnt(9)
	ds_write_b128 v0, v[118:121] offset:28672
	s_waitcnt vmcnt(8)
	ds_write_b128 v0, v[122:125] offset:61440
	v_mfma_f32_32x32x16_bf16 v[50:65], v[162:165], v[182:185], v[50:65]
	v_mfma_f32_32x32x16_bf16 v[18:33], v[162:165], v[186:189], v[18:33]
	v_mfma_f32_32x32x16_bf16 v[34:49], v[166:169], v[182:185], v[34:49]
	v_mfma_f32_32x32x16_bf16 v[2:17], v[166:169], v[186:189], v[2:17]
	v_mfma_f32_32x32x16_bf16 v[50:65], v[190:193], v[198:201], v[50:65]
	v_mfma_f32_32x32x16_bf16 v[18:33], v[190:193], v[202:205], v[18:33]
	v_mfma_f32_32x32x16_bf16 v[34:49], v[194:197], v[198:201], v[34:49]
	v_mfma_f32_32x32x16_bf16 v[2:17], v[194:197], v[202:205], v[2:17]
	ds_read_b128 v[162:165], v91
	ds_read_b128 v[166:169], v92 offset:32768
	ds_read_b128 v[182:185], v91 offset:4096
	ds_read_b128 v[186:189], v92 offset:36864
	ds_read_b128 v[190:193], v93
	ds_read_b128 v[194:197], v90 offset:32768
	ds_read_b128 v[198:201], v93 offset:4096
	ds_read_b128 v[202:205], v90 offset:36864
	s_waitcnt lgkmcnt(6)
	v_mfma_f32_32x32x16_bf16 v[50:65], v[162:165], v[166:169], v[50:65]
	s_waitcnt lgkmcnt(4)
	v_mfma_f32_32x32x16_bf16 v[18:33], v[162:165], v[186:189], v[18:33]
	v_mfma_f32_32x32x16_bf16 v[34:49], v[182:185], v[166:169], v[34:49]
	v_mfma_f32_32x32x16_bf16 v[2:17], v[182:185], v[186:189], v[2:17]
	ds_read_b128 v[162:165], v89
	ds_read_b128 v[166:169], v89 offset:4096
	ds_read_b128 v[182:185], v88 offset:32768
	ds_read_b128 v[186:189], v88 offset:36864
	s_waitcnt lgkmcnt(6)
	v_mfma_f32_32x32x16_bf16 v[50:65], v[190:193], v[194:197], v[50:65]
	s_waitcnt lgkmcnt(4)
	v_mfma_f32_32x32x16_bf16 v[18:33], v[190:193], v[202:205], v[18:33]
	v_mfma_f32_32x32x16_bf16 v[34:49], v[198:201], v[194:197], v[34:49]
	v_mfma_f32_32x32x16_bf16 v[2:17], v[198:201], v[202:205], v[2:17]
	ds_read_b128 v[190:193], v87
	ds_read_b128 v[194:197], v87 offset:4096
	ds_read_b128 v[198:201], v86 offset:32768
	ds_read_b128 v[202:205], v86 offset:36864
	s_waitcnt lgkmcnt(0)
	s_barrier
	global_load_dwordx4 v[94:97], v[66:67], off offset:1408
	global_load_dwordx4 v[98:101], v[68:69], off offset:1408
	global_load_dwordx4 v[102:105], v[70:71], off offset:1408
	global_load_dwordx4 v[106:109], v[72:73], off offset:1408
	global_load_dwordx4 v[110:113], v[74:75], off offset:1408
	global_load_dwordx4 v[114:117], v[76:77], off offset:1408
	global_load_dwordx4 v[118:121], v[78:79], off offset:1408
	global_load_dwordx4 v[122:125], v[80:81], off offset:1408
	s_waitcnt vmcnt(15)
	ds_write_b128 v0, v[126:129]
	s_waitcnt vmcnt(14)
	ds_write_b128 v0, v[134:137] offset:32768
	s_waitcnt vmcnt(13)
	ds_write_b128 v0, v[138:141] offset:4096
	s_waitcnt vmcnt(12)
	ds_write_b128 v0, v[142:145] offset:36864
	s_waitcnt vmcnt(11)
	ds_write_b128 v0, v[146:149] offset:8192
	s_waitcnt vmcnt(10)
	ds_write_b128 v0, v[150:153] offset:40960
	s_waitcnt vmcnt(9)
	ds_write_b128 v0, v[154:157] offset:12288
	s_waitcnt vmcnt(8)
	ds_write_b128 v0, v[158:161] offset:45056
	v_mfma_f32_32x32x16_bf16 v[50:65], v[162:165], v[182:185], v[50:65]
	v_mfma_f32_32x32x16_bf16 v[18:33], v[162:165], v[186:189], v[18:33]
	v_mfma_f32_32x32x16_bf16 v[34:49], v[166:169], v[182:185], v[34:49]
	v_mfma_f32_32x32x16_bf16 v[2:17], v[166:169], v[186:189], v[2:17]
	v_mfma_f32_32x32x16_bf16 v[50:65], v[190:193], v[198:201], v[50:65]
	v_mfma_f32_32x32x16_bf16 v[18:33], v[190:193], v[202:205], v[18:33]
	v_mfma_f32_32x32x16_bf16 v[34:49], v[194:197], v[198:201], v[34:49]
	v_mfma_f32_32x32x16_bf16 v[2:17], v[194:197], v[202:205], v[2:17]
	ds_read_b128 v[162:165], v91 offset:16384
	ds_read_b128 v[166:169], v92 offset:49152
	ds_read_b128 v[182:185], v91 offset:20480
	ds_read_b128 v[186:189], v92 offset:53248
	ds_read_b128 v[190:193], v93 offset:16384
	ds_read_b128 v[194:197], v90 offset:49152
	ds_read_b128 v[198:201], v93 offset:20480
	ds_read_b128 v[202:205], v90 offset:53248
	s_waitcnt lgkmcnt(6)
	v_mfma_f32_32x32x16_bf16 v[50:65], v[162:165], v[166:169], v[50:65]
	s_waitcnt lgkmcnt(4)
	v_mfma_f32_32x32x16_bf16 v[18:33], v[162:165], v[186:189], v[18:33]
	v_mfma_f32_32x32x16_bf16 v[34:49], v[182:185], v[166:169], v[34:49]
	v_mfma_f32_32x32x16_bf16 v[2:17], v[182:185], v[186:189], v[2:17]
	ds_read_b128 v[162:165], v89 offset:16384
	ds_read_b128 v[166:169], v89 offset:20480
	ds_read_b128 v[182:185], v88 offset:49152
	ds_read_b128 v[186:189], v88 offset:53248
	s_waitcnt lgkmcnt(6)
	v_mfma_f32_32x32x16_bf16 v[50:65], v[190:193], v[194:197], v[50:65]
	s_waitcnt lgkmcnt(4)
	v_mfma_f32_32x32x16_bf16 v[18:33], v[190:193], v[202:205], v[18:33]
	v_mfma_f32_32x32x16_bf16 v[34:49], v[198:201], v[194:197], v[34:49]
	v_mfma_f32_32x32x16_bf16 v[2:17], v[198:201], v[202:205], v[2:17]
	ds_read_b128 v[190:193], v87 offset:16384
	ds_read_b128 v[194:197], v87 offset:20480
	ds_read_b128 v[198:201], v86 offset:49152
	ds_read_b128 v[202:205], v86 offset:53248
	s_waitcnt lgkmcnt(0)
	s_barrier
	global_load_dwordx4 v[126:129], v[66:67], off offset:1536
	global_load_dwordx4 v[134:137], v[68:69], off offset:1536
	global_load_dwordx4 v[138:141], v[70:71], off offset:1536
	global_load_dwordx4 v[142:145], v[72:73], off offset:1536
	global_load_dwordx4 v[146:149], v[74:75], off offset:1536
	global_load_dwordx4 v[150:153], v[76:77], off offset:1536
	global_load_dwordx4 v[154:157], v[78:79], off offset:1536
	global_load_dwordx4 v[158:161], v[80:81], off offset:1536
	s_waitcnt vmcnt(15)
	ds_write_b128 v0, v[94:97] offset:16384
	s_waitcnt vmcnt(14)
	ds_write_b128 v0, v[98:101] offset:49152
	s_waitcnt vmcnt(13)
	ds_write_b128 v0, v[102:105] offset:20480
	s_waitcnt vmcnt(12)
	ds_write_b128 v0, v[106:109] offset:53248
	s_waitcnt vmcnt(11)
	ds_write_b128 v0, v[110:113] offset:24576
	s_waitcnt vmcnt(10)
	ds_write_b128 v0, v[114:117] offset:57344
	s_waitcnt vmcnt(9)
	ds_write_b128 v0, v[118:121] offset:28672
	s_waitcnt vmcnt(8)
	ds_write_b128 v0, v[122:125] offset:61440
	v_mfma_f32_32x32x16_bf16 v[50:65], v[162:165], v[182:185], v[50:65]
	v_mfma_f32_32x32x16_bf16 v[18:33], v[162:165], v[186:189], v[18:33]
	v_mfma_f32_32x32x16_bf16 v[34:49], v[166:169], v[182:185], v[34:49]
	v_mfma_f32_32x32x16_bf16 v[2:17], v[166:169], v[186:189], v[2:17]
	v_mfma_f32_32x32x16_bf16 v[50:65], v[190:193], v[198:201], v[50:65]
	v_mfma_f32_32x32x16_bf16 v[18:33], v[190:193], v[202:205], v[18:33]
	v_mfma_f32_32x32x16_bf16 v[34:49], v[194:197], v[198:201], v[34:49]
	v_mfma_f32_32x32x16_bf16 v[2:17], v[194:197], v[202:205], v[2:17]
	ds_read_b128 v[162:165], v91
	ds_read_b128 v[166:169], v92 offset:32768
	ds_read_b128 v[182:185], v91 offset:4096
	ds_read_b128 v[186:189], v92 offset:36864
	ds_read_b128 v[190:193], v93
	ds_read_b128 v[194:197], v90 offset:32768
	ds_read_b128 v[198:201], v93 offset:4096
	ds_read_b128 v[202:205], v90 offset:36864
	s_waitcnt lgkmcnt(6)
	v_mfma_f32_32x32x16_bf16 v[50:65], v[162:165], v[166:169], v[50:65]
	s_waitcnt lgkmcnt(4)
	v_mfma_f32_32x32x16_bf16 v[18:33], v[162:165], v[186:189], v[18:33]
	v_mfma_f32_32x32x16_bf16 v[34:49], v[182:185], v[166:169], v[34:49]
	v_mfma_f32_32x32x16_bf16 v[2:17], v[182:185], v[186:189], v[2:17]
	ds_read_b128 v[162:165], v89
	ds_read_b128 v[166:169], v89 offset:4096
	ds_read_b128 v[182:185], v88 offset:32768
	ds_read_b128 v[186:189], v88 offset:36864
	s_waitcnt lgkmcnt(6)
	v_mfma_f32_32x32x16_bf16 v[50:65], v[190:193], v[194:197], v[50:65]
	s_waitcnt lgkmcnt(4)
	v_mfma_f32_32x32x16_bf16 v[18:33], v[190:193], v[202:205], v[18:33]
	v_mfma_f32_32x32x16_bf16 v[34:49], v[198:201], v[194:197], v[34:49]
	v_mfma_f32_32x32x16_bf16 v[2:17], v[198:201], v[202:205], v[2:17]
	ds_read_b128 v[190:193], v87
	ds_read_b128 v[194:197], v87 offset:4096
	ds_read_b128 v[198:201], v86 offset:32768
	ds_read_b128 v[202:205], v86 offset:36864
	s_waitcnt lgkmcnt(0)
	s_barrier
	global_load_dwordx4 v[94:97], v[66:67], off offset:1664
	global_load_dwordx4 v[98:101], v[68:69], off offset:1664
	global_load_dwordx4 v[102:105], v[70:71], off offset:1664
	global_load_dwordx4 v[106:109], v[72:73], off offset:1664
	global_load_dwordx4 v[110:113], v[74:75], off offset:1664
	global_load_dwordx4 v[114:117], v[76:77], off offset:1664
	global_load_dwordx4 v[118:121], v[78:79], off offset:1664
	global_load_dwordx4 v[122:125], v[80:81], off offset:1664
	s_waitcnt vmcnt(15)
	ds_write_b128 v0, v[126:129]
	s_waitcnt vmcnt(14)
	ds_write_b128 v0, v[134:137] offset:32768
	s_waitcnt vmcnt(13)
	ds_write_b128 v0, v[138:141] offset:4096
	s_waitcnt vmcnt(12)
	ds_write_b128 v0, v[142:145] offset:36864
	s_waitcnt vmcnt(11)
	ds_write_b128 v0, v[146:149] offset:8192
	s_waitcnt vmcnt(10)
	ds_write_b128 v0, v[150:153] offset:40960
	s_waitcnt vmcnt(9)
	ds_write_b128 v0, v[154:157] offset:12288
	s_waitcnt vmcnt(8)
	ds_write_b128 v0, v[158:161] offset:45056
	v_mfma_f32_32x32x16_bf16 v[50:65], v[162:165], v[182:185], v[50:65]
	v_mfma_f32_32x32x16_bf16 v[18:33], v[162:165], v[186:189], v[18:33]
	v_mfma_f32_32x32x16_bf16 v[34:49], v[166:169], v[182:185], v[34:49]
	v_mfma_f32_32x32x16_bf16 v[2:17], v[166:169], v[186:189], v[2:17]
	v_mfma_f32_32x32x16_bf16 v[50:65], v[190:193], v[198:201], v[50:65]
	v_mfma_f32_32x32x16_bf16 v[18:33], v[190:193], v[202:205], v[18:33]
	v_mfma_f32_32x32x16_bf16 v[34:49], v[194:197], v[198:201], v[34:49]
	v_mfma_f32_32x32x16_bf16 v[2:17], v[194:197], v[202:205], v[2:17]
	ds_read_b128 v[162:165], v91 offset:16384
	ds_read_b128 v[166:169], v92 offset:49152
	ds_read_b128 v[182:185], v91 offset:20480
	ds_read_b128 v[186:189], v92 offset:53248
	ds_read_b128 v[190:193], v93 offset:16384
	ds_read_b128 v[194:197], v90 offset:49152
	ds_read_b128 v[198:201], v93 offset:20480
	ds_read_b128 v[202:205], v90 offset:53248
	s_waitcnt lgkmcnt(6)
	v_mfma_f32_32x32x16_bf16 v[50:65], v[162:165], v[166:169], v[50:65]
	s_waitcnt lgkmcnt(4)
	v_mfma_f32_32x32x16_bf16 v[18:33], v[162:165], v[186:189], v[18:33]
	v_mfma_f32_32x32x16_bf16 v[34:49], v[182:185], v[166:169], v[34:49]
	v_mfma_f32_32x32x16_bf16 v[2:17], v[182:185], v[186:189], v[2:17]
	ds_read_b128 v[162:165], v89 offset:16384
	ds_read_b128 v[166:169], v89 offset:20480
	ds_read_b128 v[182:185], v88 offset:49152
	ds_read_b128 v[186:189], v88 offset:53248
	s_waitcnt lgkmcnt(6)
	v_mfma_f32_32x32x16_bf16 v[50:65], v[190:193], v[194:197], v[50:65]
	s_waitcnt lgkmcnt(4)
	v_mfma_f32_32x32x16_bf16 v[18:33], v[190:193], v[202:205], v[18:33]
	v_mfma_f32_32x32x16_bf16 v[34:49], v[198:201], v[194:197], v[34:49]
	v_mfma_f32_32x32x16_bf16 v[2:17], v[198:201], v[202:205], v[2:17]
	ds_read_b128 v[190:193], v87 offset:16384
	ds_read_b128 v[194:197], v87 offset:20480
	ds_read_b128 v[198:201], v86 offset:49152
	ds_read_b128 v[202:205], v86 offset:53248
	s_waitcnt lgkmcnt(0)
	s_barrier
	global_load_dwordx4 v[126:129], v[66:67], off offset:1792
	global_load_dwordx4 v[134:137], v[68:69], off offset:1792
	global_load_dwordx4 v[138:141], v[70:71], off offset:1792
	global_load_dwordx4 v[142:145], v[72:73], off offset:1792
	global_load_dwordx4 v[146:149], v[74:75], off offset:1792
	global_load_dwordx4 v[150:153], v[76:77], off offset:1792
	global_load_dwordx4 v[154:157], v[78:79], off offset:1792
	global_load_dwordx4 v[158:161], v[80:81], off offset:1792
	s_waitcnt vmcnt(15)
	ds_write_b128 v0, v[94:97] offset:16384
	s_waitcnt vmcnt(14)
	ds_write_b128 v0, v[98:101] offset:49152
	s_waitcnt vmcnt(13)
	ds_write_b128 v0, v[102:105] offset:20480
	s_waitcnt vmcnt(12)
	ds_write_b128 v0, v[106:109] offset:53248
	s_waitcnt vmcnt(11)
	ds_write_b128 v0, v[110:113] offset:24576
	s_waitcnt vmcnt(10)
	ds_write_b128 v0, v[114:117] offset:57344
	s_waitcnt vmcnt(9)
	ds_write_b128 v0, v[118:121] offset:28672
	s_waitcnt vmcnt(8)
	ds_write_b128 v0, v[122:125] offset:61440
	v_mfma_f32_32x32x16_bf16 v[50:65], v[162:165], v[182:185], v[50:65]
	v_mfma_f32_32x32x16_bf16 v[18:33], v[162:165], v[186:189], v[18:33]
	v_mfma_f32_32x32x16_bf16 v[34:49], v[166:169], v[182:185], v[34:49]
	v_mfma_f32_32x32x16_bf16 v[2:17], v[166:169], v[186:189], v[2:17]
	v_mfma_f32_32x32x16_bf16 v[50:65], v[190:193], v[198:201], v[50:65]
	v_mfma_f32_32x32x16_bf16 v[18:33], v[190:193], v[202:205], v[18:33]
	v_mfma_f32_32x32x16_bf16 v[34:49], v[194:197], v[198:201], v[34:49]
	v_mfma_f32_32x32x16_bf16 v[2:17], v[194:197], v[202:205], v[2:17]
	ds_read_b128 v[162:165], v91
	ds_read_b128 v[166:169], v92 offset:32768
	ds_read_b128 v[182:185], v91 offset:4096
	ds_read_b128 v[186:189], v92 offset:36864
	ds_read_b128 v[190:193], v93
	ds_read_b128 v[194:197], v90 offset:32768
	ds_read_b128 v[198:201], v93 offset:4096
	ds_read_b128 v[202:205], v90 offset:36864
	s_waitcnt lgkmcnt(6)
	v_mfma_f32_32x32x16_bf16 v[50:65], v[162:165], v[166:169], v[50:65]
	s_waitcnt lgkmcnt(4)
	v_mfma_f32_32x32x16_bf16 v[18:33], v[162:165], v[186:189], v[18:33]
	v_mfma_f32_32x32x16_bf16 v[34:49], v[182:185], v[166:169], v[34:49]
	v_mfma_f32_32x32x16_bf16 v[2:17], v[182:185], v[186:189], v[2:17]
	ds_read_b128 v[162:165], v89
	ds_read_b128 v[166:169], v89 offset:4096
	ds_read_b128 v[182:185], v88 offset:32768
	ds_read_b128 v[186:189], v88 offset:36864
	s_waitcnt lgkmcnt(6)
	v_mfma_f32_32x32x16_bf16 v[50:65], v[190:193], v[194:197], v[50:65]
	s_waitcnt lgkmcnt(4)
	v_mfma_f32_32x32x16_bf16 v[18:33], v[190:193], v[202:205], v[18:33]
	v_mfma_f32_32x32x16_bf16 v[34:49], v[198:201], v[194:197], v[34:49]
	v_mfma_f32_32x32x16_bf16 v[2:17], v[198:201], v[202:205], v[2:17]
	ds_read_b128 v[190:193], v87
	ds_read_b128 v[194:197], v87 offset:4096
	ds_read_b128 v[198:201], v86 offset:32768
	ds_read_b128 v[202:205], v86 offset:36864
	s_waitcnt lgkmcnt(0)
	s_barrier
	global_load_dwordx4 v[94:97], v[66:67], off offset:1920
	s_nop 0
	global_load_dwordx4 v[66:69], v[68:69], off offset:1920
	s_nop 0
	global_load_dwordx4 v[98:101], v[70:71], off offset:1920
	s_nop 0
	global_load_dwordx4 v[70:73], v[72:73], off offset:1920
	s_nop 0
	global_load_dwordx4 v[102:105], v[74:75], off offset:1920
	s_nop 0
	global_load_dwordx4 v[74:77], v[76:77], off offset:1920
	s_nop 0
	global_load_dwordx4 v[106:109], v[78:79], off offset:1920
	s_nop 0
	global_load_dwordx4 v[78:81], v[80:81], off offset:1920
	s_waitcnt vmcnt(15)
	ds_write_b128 v0, v[126:129]
	s_waitcnt vmcnt(14)
	ds_write_b128 v0, v[134:137] offset:32768
	s_waitcnt vmcnt(13)
	ds_write_b128 v0, v[138:141] offset:4096
	s_waitcnt vmcnt(12)
	ds_write_b128 v0, v[142:145] offset:36864
	s_waitcnt vmcnt(11)
	ds_write_b128 v0, v[146:149] offset:8192
	s_waitcnt vmcnt(10)
	ds_write_b128 v0, v[150:153] offset:40960
	s_waitcnt vmcnt(9)
	ds_write_b128 v0, v[154:157] offset:12288
	s_waitcnt vmcnt(8)
	ds_write_b128 v0, v[158:161] offset:45056
	v_mfma_f32_32x32x16_bf16 v[50:65], v[162:165], v[182:185], v[50:65]
	v_mfma_f32_32x32x16_bf16 v[18:33], v[162:165], v[186:189], v[18:33]
	v_mfma_f32_32x32x16_bf16 v[34:49], v[166:169], v[182:185], v[34:49]
	v_mfma_f32_32x32x16_bf16 v[2:17], v[166:169], v[186:189], v[2:17]
	ds_read_b128 v[110:113], v91 offset:16384
	ds_read_b128 v[114:117], v91 offset:20480
	ds_read_b128 v[118:121], v92 offset:49152
	ds_read_b128 v[122:125], v92 offset:53248
	ds_read_b128 v[162:165], v93 offset:16384
	ds_read_b128 v[166:169], v93 offset:20480
	ds_read_b128 v[182:185], v90 offset:49152
	ds_read_b128 v[186:189], v90 offset:53248
	v_mfma_f32_32x32x16_bf16 v[50:65], v[190:193], v[198:201], v[50:65]
	v_mfma_f32_32x32x16_bf16 v[18:33], v[190:193], v[202:205], v[18:33]
	v_mfma_f32_32x32x16_bf16 v[34:49], v[194:197], v[198:201], v[34:49]
	v_mfma_f32_32x32x16_bf16 v[2:17], v[194:197], v[202:205], v[2:17]
	s_waitcnt lgkmcnt(5)
	v_mfma_f32_32x32x16_bf16 v[50:65], v[110:113], v[118:121], v[50:65]
	s_waitcnt lgkmcnt(4)
	v_mfma_f32_32x32x16_bf16 v[18:33], v[110:113], v[122:125], v[18:33]
	v_mfma_f32_32x32x16_bf16 v[34:49], v[114:117], v[118:121], v[34:49]
	v_mfma_f32_32x32x16_bf16 v[2:17], v[114:117], v[122:125], v[2:17]
	ds_read_b128 v[110:113], v89 offset:16384
	ds_read_b128 v[114:117], v89 offset:20480
	ds_read_b128 v[118:121], v88 offset:49152
	ds_read_b128 v[122:125], v88 offset:53248
	s_waitcnt lgkmcnt(5)
	v_mfma_f32_32x32x16_bf16 v[50:65], v[162:165], v[182:185], v[50:65]
	s_waitcnt lgkmcnt(4)
	v_mfma_f32_32x32x16_bf16 v[18:33], v[162:165], v[186:189], v[18:33]
	v_mfma_f32_32x32x16_bf16 v[34:49], v[166:169], v[182:185], v[34:49]
	v_mfma_f32_32x32x16_bf16 v[2:17], v[166:169], v[186:189], v[2:17]
	ds_read_b128 v[162:165], v87 offset:16384
	ds_read_b128 v[166:169], v87 offset:20480
	ds_read_b128 v[182:185], v86 offset:49152
	ds_read_b128 v[186:189], v86 offset:53248
	s_waitcnt lgkmcnt(5)
	v_mfma_f32_32x32x16_bf16 v[50:65], v[110:113], v[118:121], v[50:65]
	s_waitcnt lgkmcnt(0)
	s_barrier
	s_waitcnt vmcnt(7)
	ds_write_b128 v0, v[94:97] offset:16384
	s_waitcnt vmcnt(6)
	ds_write_b128 v0, v[66:69] offset:49152
	s_waitcnt vmcnt(5)
	ds_write_b128 v0, v[98:101] offset:20480
	s_waitcnt vmcnt(4)
	ds_write_b128 v0, v[70:73] offset:53248
	s_waitcnt vmcnt(3)
	ds_write_b128 v0, v[102:105] offset:24576
	s_waitcnt vmcnt(2)
	ds_write_b128 v0, v[74:77] offset:57344
	s_waitcnt vmcnt(1)
	ds_write_b128 v0, v[106:109] offset:28672
	s_waitcnt vmcnt(0)
	ds_write_b128 v0, v[78:81] offset:61440
	v_mfma_f32_32x32x16_bf16 v[18:33], v[110:113], v[122:125], v[18:33]
	v_mfma_f32_32x32x16_bf16 v[34:49], v[114:117], v[118:121], v[34:49]
	v_mfma_f32_32x32x16_bf16 v[2:17], v[114:117], v[122:125], v[2:17]
	ds_read_b128 v[110:113], v91
	ds_read_b128 v[114:117], v91 offset:4096
	ds_read_b128 v[118:121], v92 offset:32768
	ds_read_b128 v[122:125], v92 offset:36864
	ds_read_b128 v[126:129], v93
	ds_read_b128 v[134:137], v93 offset:4096
	ds_read_b128 v[138:141], v90 offset:32768
	ds_read_b128 v[142:145], v90 offset:36864
	v_mfma_f32_32x32x16_bf16 v[50:65], v[162:165], v[182:185], v[50:65]
	v_mfma_f32_32x32x16_bf16 v[18:33], v[162:165], v[186:189], v[18:33]
	v_mfma_f32_32x32x16_bf16 v[34:49], v[166:169], v[182:185], v[34:49]
	v_mfma_f32_32x32x16_bf16 v[2:17], v[166:169], v[186:189], v[2:17]
	s_waitcnt lgkmcnt(5)
	v_mfma_f32_32x32x16_bf16 v[50:65], v[110:113], v[118:121], v[50:65]
	s_waitcnt lgkmcnt(4)
	v_mfma_f32_32x32x16_bf16 v[18:33], v[110:113], v[122:125], v[18:33]
	v_mfma_f32_32x32x16_bf16 v[34:49], v[114:117], v[118:121], v[34:49]
	v_mfma_f32_32x32x16_bf16 v[2:17], v[114:117], v[122:125], v[2:17]
	ds_read_b128 v[110:113], v89
	ds_read_b128 v[114:117], v89 offset:4096
	ds_read_b128 v[118:121], v88 offset:32768
	ds_read_b128 v[122:125], v88 offset:36864
	s_waitcnt lgkmcnt(5)
	v_mfma_f32_32x32x16_bf16 v[50:65], v[126:129], v[138:141], v[50:65]
	s_waitcnt lgkmcnt(4)
	v_mfma_f32_32x32x16_bf16 v[18:33], v[126:129], v[142:145], v[18:33]
	v_mfma_f32_32x32x16_bf16 v[34:49], v[134:137], v[138:141], v[34:49]
	v_mfma_f32_32x32x16_bf16 v[2:17], v[134:137], v[142:145], v[2:17]
	ds_read_b128 v[126:129], v87
	ds_read_b128 v[134:137], v87 offset:4096
	ds_read_b128 v[138:141], v86 offset:32768
	ds_read_b128 v[142:145], v86 offset:36864
	s_waitcnt lgkmcnt(0)
	s_barrier
	ds_read_b128 v[66:69], v91 offset:16384
	ds_read_b128 v[70:73], v91 offset:20480
	ds_read_b128 v[74:77], v92 offset:49152
	ds_read_b128 v[78:81], v92 offset:53248
	ds_read_b128 v[94:97], v93 offset:16384
	ds_read_b128 v[98:101], v93 offset:20480
	ds_read_b128 v[102:105], v90 offset:49152
	ds_read_b128 v[90:93], v90 offset:53248
	v_mfma_f32_32x32x16_bf16 v[50:65], v[110:113], v[118:121], v[50:65]
	v_mfma_f32_32x32x16_bf16 v[18:33], v[110:113], v[122:125], v[18:33]
	v_mfma_f32_32x32x16_bf16 v[34:49], v[114:117], v[118:121], v[34:49]
	v_mfma_f32_32x32x16_bf16 v[2:17], v[114:117], v[122:125], v[2:17]
	v_mfma_f32_32x32x16_bf16 v[50:65], v[126:129], v[138:141], v[50:65]
	v_mfma_f32_32x32x16_bf16 v[18:33], v[126:129], v[142:145], v[18:33]
	v_mfma_f32_32x32x16_bf16 v[34:49], v[134:137], v[138:141], v[34:49]
	v_mfma_f32_32x32x16_bf16 v[2:17], v[134:137], v[142:145], v[2:17]
	s_waitcnt lgkmcnt(5)
	v_mfma_f32_32x32x16_bf16 v[50:65], v[66:69], v[74:77], v[50:65]
	s_waitcnt lgkmcnt(4)
	v_mfma_f32_32x32x16_bf16 v[18:33], v[66:69], v[78:81], v[18:33]
	v_mfma_f32_32x32x16_bf16 v[34:49], v[70:73], v[74:77], v[34:49]
	v_mfma_f32_32x32x16_bf16 v[2:17], v[70:73], v[78:81], v[2:17]
	ds_read_b128 v[66:69], v89 offset:16384
	ds_read_b128 v[70:73], v89 offset:20480
	ds_read_b128 v[74:77], v88 offset:49152
	ds_read_b128 v[78:81], v88 offset:53248
	s_waitcnt lgkmcnt(5)
	v_mfma_f32_32x32x16_bf16 v[50:65], v[94:97], v[102:105], v[50:65]
	s_waitcnt lgkmcnt(4)
	v_mfma_f32_32x32x16_bf16 v[18:33], v[94:97], v[90:93], v[18:33]
	v_mfma_f32_32x32x16_bf16 v[34:49], v[98:101], v[102:105], v[34:49]
	v_mfma_f32_32x32x16_bf16 v[2:17], v[98:101], v[90:93], v[2:17]
	ds_read_b128 v[88:91], v87 offset:16384
	ds_read_b128 v[92:95], v87 offset:20480
	ds_read_b128 v[96:99], v86 offset:49152
	ds_read_b128 v[100:103], v86 offset:53248
	s_lshl_b32 s6, s34, 7
	v_lshl_add_u32 v0, v84, 6, s6
	s_min_i32 s7, s6, 0x4000
	v_lshl_or_b32 v0, v85, 2, v0
	s_movk_i32 s6, 0x4000
	s_waitcnt lgkmcnt(5)
	v_mfma_f32_32x32x16_bf16 v[50:65], v[66:69], v[74:77], v[50:65]
	v_cmp_gt_i32_e32 vcc, s6, v0
	v_readlane_b32 s36, v210, 2
	v_readlane_b32 s40, v210, 6
	s_ashr_i32 s7, s7, 12
	s_add_i32 s7, s7, s70
	s_mul_hi_i32 s8, s7, 0x6000
	s_mulk_i32 s7, 0x6000
	s_waitcnt lgkmcnt(4)
	v_mfma_f32_32x32x16_bf16 v[18:33], v[66:69], v[78:81], v[18:33]
	v_add_u32_e32 v66, 0xffffc000, v0
	v_ashrrev_i32_e32 v67, 31, v0
	v_cndmask_b32_e32 v66, v66, v0, vcc
	v_mov_b32_e32 v0, s95
	v_mov_b32_e32 v68, s89
	v_cndmask_b32_e32 v69, v0, v68, vcc
	v_mov_b32_e32 v0, s94
	v_mov_b32_e32 v68, s88
	v_mfma_f32_32x32x16_bf16 v[34:49], v[70:73], v[74:77], v[34:49]
	v_cndmask_b32_e32 v67, 0, v67, vcc
	v_cndmask_b32_e32 v68, v0, v68, vcc
	v_mov_b32_e32 v0, s40
	v_lshlrev_b64 v[66:67], 12, v[66:67]
	v_lshl_add_u64 v[134:135], v[68:69], 0, v[66:67]
	v_readlane_b32 s37, v210, 3
	v_readlane_b32 s41, v210, 7
	v_mfma_f32_32x32x16_bf16 v[2:17], v[70:73], v[78:81], v[2:17]
	v_mov_b32_e32 v70, s36
	v_cndmask_b32_e32 v0, v0, v70, vcc
	v_cndmask_b32_e64 v68, v68, v0, s[52:53]
	v_lshl_or_b32 v0, v83, 6, v82
	s_add_u32 s7, s90, s7
	v_mov_b32_e32 v70, s41
	v_mov_b32_e32 v71, s37
	v_subrev_u32_e32 v0, s5, v0
	s_addc_u32 s8, s91, s8
	v_cndmask_b32_e32 v70, v70, v71, vcc
	v_add_u32_e32 v168, s3, v0
	s_add_u32 s34, s7, 0x2000
	v_cndmask_b32_e64 v69, v69, v70, s[52:53]
	v_ashrrev_i32_e32 v169, 31, v168
	s_addc_u32 s35, s8, 0
	v_lshl_add_u64 v[66:67], v[68:69], 0, v[66:67]
	v_lshlrev_b64 v[136:137], 2, v[168:169]
	v_lshl_add_u64 v[68:69], s[34:35], 0, v[136:137]
	v_lshl_add_u64 v[66:67], v[66:67], 0, v[136:137]
	s_movk_i32 s8, 0x1000
	s_waitcnt lgkmcnt(0)
	s_barrier
	global_load_dword v0, v[68:69], off
	v_add_co_u32_e32 v68, vcc, s8, v66
	s_movk_i32 s6, 0x2000
	s_nop 0
	v_addc_co_u32_e32 v69, vcc, 0, v67, vcc
	global_load_dword v138, v[66:67], off
	v_add_co_u32_e32 v70, vcc, s6, v66
	v_readlane_b32 s38, v210, 4
	s_nop 0
	v_addc_co_u32_e32 v71, vcc, 0, v67, vcc
	global_load_dword v139, v[70:71], off offset:-4096
	global_load_dword v140, v[70:71], off
	s_movk_i32 s38, 0x3000
	v_add_co_u32_e32 v72, vcc, s38, v66
	s_mov_b32 s7, 0x8000
	s_nop 0
	v_addc_co_u32_e32 v73, vcc, 0, v67, vcc
	global_load_dword v141, v[72:73], off
	v_add_co_u32_e32 v74, vcc, s7, v66
	s_mov_b32 s36, 0x9000
	s_nop 0
	v_addc_co_u32_e32 v75, vcc, 0, v67, vcc
	v_add_co_u32_e32 v76, vcc, s36, v66
	s_mov_b32 s37, 0xa000
	s_nop 0
	v_addc_co_u32_e32 v77, vcc, 0, v67, vcc
	v_add_co_u32_e32 v78, vcc, s37, v66
	s_mov_b32 s5, 0xb000
	s_nop 0
	v_addc_co_u32_e32 v79, vcc, 0, v67, vcc
	global_load_dword v142, v[76:77], off offset:-4096
	global_load_dword v143, v[76:77], off
	v_add_co_u32_e32 v80, vcc, s5, v66
	v_readlane_b32 s39, v210, 5
	s_nop 0
	v_addc_co_u32_e32 v81, vcc, 0, v67, vcc
	v_add_co_u32_e32 v82, vcc, s10, v66
	s_mov_b32 s39, 0x11000
	s_nop 0
	v_addc_co_u32_e32 v83, vcc, 0, v67, vcc
	global_load_dword v144, v[80:81], off offset:-4096
	global_load_dword v145, v[80:81], off
	v_add_co_u32_e32 v84, vcc, s39, v66
	v_mfma_f32_32x32x16_bf16 v[50:65], v[88:91], v[96:99], v[50:65]
	s_nop 0
	v_addc_co_u32_e32 v85, vcc, 0, v67, vcc
	v_add_co_u32_e32 v86, vcc, s62, v66
	global_load_dword v146, v[84:85], off offset:-4096
	global_load_dword v147, v[84:85], off
	v_addc_co_u32_e32 v87, vcc, 0, v67, vcc
	v_mfma_f32_32x32x16_bf16 v[18:33], v[88:91], v[100:103], v[18:33]
	v_add_co_u32_e32 v88, vcc, s57, v66
	v_lshl_add_u64 v[134:135], v[134:135], 0, v[136:137]
	s_nop 0
	v_addc_co_u32_e32 v89, vcc, 0, v67, vcc
	v_add_co_u32_e32 v90, vcc, s54, v66
	v_mfma_f32_32x32x16_bf16 v[34:49], v[92:95], v[96:99], v[34:49]
	s_nop 0
	v_addc_co_u32_e32 v91, vcc, 0, v67, vcc
	global_load_dword v148, v[88:89], off offset:-4096
	global_load_dword v149, v[88:89], off
	s_add_i32 s4, s4, s66
	s_add_i32 s3, s3, s2
	s_cmp_lt_i32 s4, s59
	v_readlane_b32 s42, v210, 8
	v_mfma_f32_32x32x16_bf16 v[2:17], v[92:95], v[100:103], v[2:17]
	v_add_co_u32_e32 v92, vcc, s55, v66
	v_readlane_b32 s43, v210, 9
	s_nop 0
	v_addc_co_u32_e32 v93, vcc, 0, v67, vcc
	v_add_co_u32_e32 v94, vcc, s72, v66
	global_load_dword v150, v[92:93], off offset:-4096
	global_load_dword v151, v[92:93], off
	v_addc_co_u32_e32 v95, vcc, 0, v67, vcc
	v_add_co_u32_e32 v96, vcc, s73, v66
	s_waitcnt vmcnt(13)
	v_fmac_f32_e32 v138, v50, v0
	v_addc_co_u32_e32 v97, vcc, 0, v67, vcc
	v_add_co_u32_e32 v98, vcc, s63, v66
	global_load_dword v152, v[96:97], off offset:-4096
	global_load_dword v153, v[96:97], off
	v_addc_co_u32_e32 v99, vcc, 0, v67, vcc
	v_add_co_u32_e32 v100, vcc, s74, v66
	s_waitcnt vmcnt(14)
	v_fmac_f32_e32 v139, v51, v0
	v_addc_co_u32_e32 v101, vcc, 0, v67, vcc
	v_add_co_u32_e32 v102, vcc, s75, v66
	global_load_dword v154, v[100:101], off offset:-4096
	global_load_dword v155, v[100:101], off
	v_addc_co_u32_e32 v103, vcc, 0, v67, vcc
	v_add_co_u32_e32 v104, vcc, s76, v66
	s_waitcnt vmcnt(15)
	v_fmac_f32_e32 v140, v52, v0
	v_addc_co_u32_e32 v105, vcc, 0, v67, vcc
	v_add_co_u32_e32 v106, vcc, s77, v66
	global_load_dword v156, v[104:105], off offset:-4096
	global_load_dword v157, v[104:105], off
	v_addc_co_u32_e32 v107, vcc, 0, v67, vcc
	v_add_co_u32_e32 v108, vcc, s78, v66
	s_waitcnt vmcnt(16)
	v_fmac_f32_e32 v141, v53, v0
	v_addc_co_u32_e32 v109, vcc, 0, v67, vcc
	v_add_co_u32_e32 v110, vcc, s79, v66
	global_load_dword v158, v[108:109], off offset:-4096
	global_load_dword v159, v[108:109], off
	v_addc_co_u32_e32 v111, vcc, 0, v67, vcc
	v_add_co_u32_e32 v112, vcc, s58, v66
	s_waitcnt vmcnt(17)
	v_fmac_f32_e32 v142, v54, v0
	v_addc_co_u32_e32 v113, vcc, 0, v67, vcc
	v_add_co_u32_e32 v114, vcc, s61, v66
	global_load_dword v160, v[112:113], off offset:-4096
	global_load_dword v161, v[112:113], off
	v_addc_co_u32_e32 v115, vcc, 0, v67, vcc
	v_add_co_u32_e32 v116, vcc, s56, v66
	s_waitcnt vmcnt(18)
	v_fmac_f32_e32 v143, v55, v0
	v_addc_co_u32_e32 v117, vcc, 0, v67, vcc
	v_add_co_u32_e32 v118, vcc, s97, v66
	global_load_dword v162, v[116:117], off offset:-4096
	global_load_dword v163, v[116:117], off
	v_addc_co_u32_e32 v119, vcc, 0, v67, vcc
	v_add_co_u32_e32 v120, vcc, s9, v66
	s_waitcnt vmcnt(19)
	v_fmac_f32_e32 v144, v56, v0
	v_addc_co_u32_e32 v121, vcc, 0, v67, vcc
	v_add_co_u32_e32 v122, vcc, s69, v66
	global_load_dword v164, v[120:121], off offset:-4096
	global_load_dword v165, v[120:121], off
	v_addc_co_u32_e32 v123, vcc, 0, v67, vcc
	v_add_co_u32_e32 v124, vcc, s67, v66
	s_waitcnt vmcnt(20)
	v_fmac_f32_e32 v145, v57, v0
	v_addc_co_u32_e32 v125, vcc, 0, v67, vcc
	v_add_co_u32_e32 v126, vcc, s60, v66
	global_load_dword v166, v[124:125], off offset:-4096
	global_load_dword v167, v[124:125], off
	v_addc_co_u32_e32 v127, vcc, 0, v67, vcc
	v_add_co_u32_e32 v128, vcc, s33, v66
	s_waitcnt vmcnt(21)
	v_fmac_f32_e32 v146, v58, v0
	v_addc_co_u32_e32 v129, vcc, 0, v67, vcc
	global_load_dword v169, v[128:129], off offset:-4096
	global_load_dword v181, v[128:129], off
	v_add_co_u32_e32 v50, vcc, s8, v134
	global_store_dword v[134:135], v138, off
	s_nop 0
	v_addc_co_u32_e32 v51, vcc, 0, v135, vcc
	v_add_co_u32_e32 v136, vcc, s6, v134
	s_waitcnt vmcnt(23)
	v_fmac_f32_e32 v147, v59, v0
	v_addc_co_u32_e32 v137, vcc, 0, v135, vcc
	v_add_co_u32_e32 v52, vcc, s38, v134
	global_store_dword v[136:137], v139, off offset:-4096
	s_nop 0
	v_addc_co_u32_e32 v53, vcc, 0, v135, vcc
	v_add_co_u32_e32 v138, vcc, s7, v134
	global_store_dword v[136:137], v140, off
	s_nop 0
	v_addc_co_u32_e32 v139, vcc, 0, v135, vcc
	v_add_co_u32_e32 v140, vcc, s36, v134
	global_store_dword v[52:53], v141, off
	s_nop 0
	v_addc_co_u32_e32 v141, vcc, 0, v135, vcc
	v_add_co_u32_e32 v54, vcc, s37, v134
	global_store_dword v[140:141], v142, off offset:-4096
	s_nop 0
	v_addc_co_u32_e32 v55, vcc, 0, v135, vcc
	v_add_co_u32_e32 v142, vcc, s5, v134
	global_store_dword v[140:141], v143, off
	s_nop 0
	v_addc_co_u32_e32 v143, vcc, 0, v135, vcc
	v_add_co_u32_e32 v56, vcc, s10, v134
	global_store_dword v[142:143], v144, off offset:-4096
	s_nop 0
	v_addc_co_u32_e32 v57, vcc, 0, v135, vcc
	v_add_co_u32_e32 v144, vcc, s39, v134
	global_store_dword v[142:143], v145, off
	s_nop 0
	v_addc_co_u32_e32 v145, vcc, 0, v135, vcc
	v_add_co_u32_e32 v58, vcc, s62, v134
	global_store_dword v[144:145], v146, off offset:-4096
	s_nop 0
	v_addc_co_u32_e32 v59, vcc, 0, v135, vcc
	v_add_co_u32_e32 v146, vcc, s57, v134
	global_store_dword v[144:145], v147, off
	s_nop 0
	v_addc_co_u32_e32 v147, vcc, 0, v135, vcc
	s_waitcnt vmcnt(31)
	v_fmac_f32_e32 v148, v60, v0
	v_add_co_u32_e32 v60, vcc, s54, v134
	s_waitcnt vmcnt(30)
	v_fmac_f32_e32 v149, v61, v0
	v_addc_co_u32_e32 v61, vcc, 0, v135, vcc
	global_store_dword v[146:147], v148, off offset:-4096
	v_add_co_u32_e32 v148, vcc, s55, v134
	global_store_dword v[146:147], v149, off
	s_nop 0
	v_addc_co_u32_e32 v149, vcc, 0, v135, vcc
	s_waitcnt vmcnt(31)
	v_fmac_f32_e32 v150, v62, v0
	v_add_co_u32_e32 v62, vcc, s72, v134
	s_waitcnt vmcnt(30)
	v_fmac_f32_e32 v151, v63, v0
	v_addc_co_u32_e32 v63, vcc, 0, v135, vcc
	global_store_dword v[148:149], v150, off offset:-4096
	v_add_co_u32_e32 v150, vcc, s73, v134
	global_store_dword v[148:149], v151, off
	s_nop 0
	v_addc_co_u32_e32 v151, vcc, 0, v135, vcc
	s_waitcnt vmcnt(31)
	v_fmac_f32_e32 v152, v64, v0
	v_add_co_u32_e32 v64, vcc, s63, v134
	s_waitcnt vmcnt(30)
	v_fmac_f32_e32 v153, v65, v0
	v_addc_co_u32_e32 v65, vcc, 0, v135, vcc
	global_store_dword v[150:151], v152, off offset:-4096
	v_add_co_u32_e32 v152, vcc, s74, v134
	global_store_dword v[150:151], v153, off
	s_nop 0
	v_addc_co_u32_e32 v153, vcc, 0, v135, vcc
	s_waitcnt vmcnt(31)
	v_fmac_f32_e32 v154, v34, v0
	v_add_co_u32_e32 v34, vcc, s75, v134
	s_waitcnt vmcnt(30)
	v_fmac_f32_e32 v155, v35, v0
	v_addc_co_u32_e32 v35, vcc, 0, v135, vcc
	global_store_dword v[152:153], v154, off offset:-4096
	v_add_co_u32_e32 v154, vcc, s76, v134
	global_store_dword v[152:153], v155, off
	s_nop 0
	v_addc_co_u32_e32 v155, vcc, 0, v135, vcc
	s_waitcnt vmcnt(31)
	v_fmac_f32_e32 v156, v36, v0
	v_add_co_u32_e32 v36, vcc, s77, v134
	s_waitcnt vmcnt(30)
	v_fmac_f32_e32 v157, v37, v0
	v_addc_co_u32_e32 v37, vcc, 0, v135, vcc
	global_store_dword v[154:155], v156, off offset:-4096
	v_add_co_u32_e32 v156, vcc, s78, v134
	global_store_dword v[154:155], v157, off
	s_nop 0
	v_addc_co_u32_e32 v157, vcc, 0, v135, vcc
	s_waitcnt vmcnt(31)
	v_fmac_f32_e32 v158, v38, v0
	v_add_co_u32_e32 v38, vcc, s79, v134
	s_waitcnt vmcnt(30)
	v_fmac_f32_e32 v159, v39, v0
	v_addc_co_u32_e32 v39, vcc, 0, v135, vcc
	global_store_dword v[156:157], v158, off offset:-4096
	v_add_co_u32_e32 v158, vcc, s58, v134
	global_store_dword v[156:157], v159, off
	s_nop 0
	v_addc_co_u32_e32 v159, vcc, 0, v135, vcc
	s_waitcnt vmcnt(31)
	v_fmac_f32_e32 v160, v40, v0
	v_add_co_u32_e32 v40, vcc, s61, v134
	s_waitcnt vmcnt(30)
	v_fmac_f32_e32 v161, v41, v0
	v_addc_co_u32_e32 v41, vcc, 0, v135, vcc
	global_store_dword v[158:159], v160, off offset:-4096
	v_add_co_u32_e32 v160, vcc, s56, v134
	global_store_dword v[158:159], v161, off
	s_nop 0
	v_addc_co_u32_e32 v161, vcc, 0, v135, vcc
	s_waitcnt vmcnt(31)
	v_fmac_f32_e32 v162, v42, v0
	v_add_co_u32_e32 v42, vcc, s97, v134
	s_waitcnt vmcnt(30)
	v_fmac_f32_e32 v163, v43, v0
	v_addc_co_u32_e32 v43, vcc, 0, v135, vcc
	global_store_dword v[160:161], v162, off offset:-4096
	v_add_co_u32_e32 v162, vcc, s9, v134
	global_store_dword v[160:161], v163, off
	s_nop 0
	v_addc_co_u32_e32 v163, vcc, 0, v135, vcc
	s_waitcnt vmcnt(31)
	v_fmac_f32_e32 v164, v44, v0
	v_add_co_u32_e32 v44, vcc, s69, v134
	s_waitcnt vmcnt(30)
	v_fmac_f32_e32 v165, v45, v0
	v_addc_co_u32_e32 v45, vcc, 0, v135, vcc
	global_store_dword v[162:163], v164, off offset:-4096
	v_add_co_u32_e32 v164, vcc, s67, v134
	global_store_dword v[162:163], v165, off
	s_nop 0
	v_addc_co_u32_e32 v165, vcc, 0, v135, vcc
	s_waitcnt vmcnt(31)
	v_fmac_f32_e32 v166, v46, v0
	v_add_co_u32_e32 v46, vcc, s60, v134
	s_waitcnt vmcnt(30)
	v_fmac_f32_e32 v167, v47, v0
	v_addc_co_u32_e32 v47, vcc, 0, v135, vcc
	global_store_dword v[164:165], v166, off offset:-4096
	s_waitcnt vmcnt(30)
	v_fmac_f32_e32 v169, v48, v0
	v_add_co_u32_e32 v166, vcc, s33, v134
	v_add_u32_e32 v48, 32, v168
	global_store_dword v[164:165], v167, off
	v_addc_co_u32_e32 v167, vcc, 0, v135, vcc
	s_waitcnt vmcnt(30)
	v_fmac_f32_e32 v181, v49, v0
	v_ashrrev_i32_e32 v49, 31, v48
	global_store_dword v[166:167], v169, off offset:-4096
	global_store_dword v[166:167], v181, off
	v_lshl_add_u64 v[48:49], v[48:49], 2, s[34:35]
	global_load_dword v0, v[48:49], off
	s_nop 0
	global_load_dword v48, v[66:67], off offset:128
	global_load_dword v49, v[68:69], off offset:128
	s_nop 0
	global_load_dword v66, v[70:71], off offset:128
	global_load_dword v67, v[72:73], off offset:128
	global_load_dword v68, v[74:75], off offset:128
	global_load_dword v69, v[76:77], off offset:128
	s_nop 0
	global_load_dword v70, v[78:79], off offset:128
	global_load_dword v71, v[80:81], off offset:128
	global_load_dword v72, v[82:83], off offset:128
	global_load_dword v73, v[84:85], off offset:128
	global_load_dword v74, v[86:87], off offset:128
	global_load_dword v75, v[88:89], off offset:128
	global_load_dword v76, v[90:91], off offset:128
	global_load_dword v77, v[92:93], off offset:128
	global_load_dword v78, v[94:95], off offset:128
	global_load_dword v79, v[96:97], off offset:128
	global_load_dword v80, v[98:99], off offset:128
	global_load_dword v81, v[100:101], off offset:128
	global_load_dword v82, v[102:103], off offset:128
	global_load_dword v83, v[104:105], off offset:128
	global_load_dword v84, v[106:107], off offset:128
	global_load_dword v85, v[108:109], off offset:128
	global_load_dword v86, v[110:111], off offset:128
	global_load_dword v87, v[112:113], off offset:128
	global_load_dword v88, v[114:115], off offset:128
	global_load_dword v89, v[116:117], off offset:128
	global_load_dword v90, v[118:119], off offset:128
	global_load_dword v91, v[120:121], off offset:128
	global_load_dword v92, v[122:123], off offset:128
	global_load_dword v93, v[124:125], off offset:128
	global_load_dword v94, v[126:127], off offset:128
	global_load_dword v95, v[128:129], off offset:128
	v_readlane_b32 s44, v210, 10
	v_readlane_b32 s45, v210, 11
	v_readlane_b32 s46, v210, 12
	v_readlane_b32 s47, v210, 13
	v_readlane_b32 s48, v210, 14
	v_readlane_b32 s49, v210, 15
	v_readlane_b32 s50, v210, 16
	v_readlane_b32 s51, v210, 17
	s_waitcnt vmcnt(31)
	v_fmac_f32_e32 v48, v18, v0
	s_waitcnt vmcnt(30)
	v_fmac_f32_e32 v49, v19, v0
	s_waitcnt vmcnt(29)
	v_fmac_f32_e32 v66, v20, v0
	s_waitcnt vmcnt(28)
	v_fmac_f32_e32 v67, v21, v0
	s_waitcnt vmcnt(27)
	v_fmac_f32_e32 v68, v22, v0
	s_waitcnt vmcnt(26)
	v_fmac_f32_e32 v69, v23, v0
	s_waitcnt vmcnt(25)
	v_fmac_f32_e32 v70, v24, v0
	s_waitcnt vmcnt(24)
	v_fmac_f32_e32 v71, v25, v0
	s_waitcnt vmcnt(23)
	v_fmac_f32_e32 v72, v26, v0
	s_waitcnt vmcnt(22)
	v_fmac_f32_e32 v73, v27, v0
	s_waitcnt vmcnt(21)
	v_fmac_f32_e32 v74, v28, v0
	s_waitcnt vmcnt(20)
	v_fmac_f32_e32 v75, v29, v0
	s_waitcnt vmcnt(19)
	v_fmac_f32_e32 v76, v30, v0
	s_waitcnt vmcnt(18)
	v_fmac_f32_e32 v77, v31, v0
	s_waitcnt vmcnt(17)
	v_fmac_f32_e32 v78, v32, v0
	s_waitcnt vmcnt(16)
	v_fmac_f32_e32 v79, v33, v0
	s_waitcnt vmcnt(15)
	v_fmac_f32_e32 v80, v2, v0
	s_waitcnt vmcnt(14)
	v_fmac_f32_e32 v81, v3, v0
	s_waitcnt vmcnt(13)
	v_fmac_f32_e32 v82, v4, v0
	s_waitcnt vmcnt(12)
	v_fmac_f32_e32 v83, v5, v0
	s_waitcnt vmcnt(11)
	v_fmac_f32_e32 v84, v6, v0
	s_waitcnt vmcnt(10)
	v_fmac_f32_e32 v85, v7, v0
	s_waitcnt vmcnt(9)
	v_fmac_f32_e32 v86, v8, v0
	s_waitcnt vmcnt(8)
	v_fmac_f32_e32 v87, v9, v0
	s_waitcnt vmcnt(7)
	v_fmac_f32_e32 v88, v10, v0
	s_waitcnt vmcnt(6)
	v_fmac_f32_e32 v89, v11, v0
	s_waitcnt vmcnt(5)
	v_fmac_f32_e32 v90, v12, v0
	s_waitcnt vmcnt(4)
	v_fmac_f32_e32 v91, v13, v0
	s_waitcnt vmcnt(3)
	v_fmac_f32_e32 v92, v14, v0
	s_waitcnt vmcnt(2)
	v_fmac_f32_e32 v93, v15, v0
	s_waitcnt vmcnt(1)
	v_fmac_f32_e32 v94, v16, v0
	s_waitcnt vmcnt(0)
	v_fmac_f32_e32 v95, v17, v0
	global_store_dword v[134:135], v48, off offset:128
	global_store_dword v[50:51], v49, off offset:128
	global_store_dword v[136:137], v66, off offset:128
	global_store_dword v[52:53], v67, off offset:128
	global_store_dword v[138:139], v68, off offset:128
	global_store_dword v[140:141], v69, off offset:128
	global_store_dword v[54:55], v70, off offset:128
	global_store_dword v[142:143], v71, off offset:128
	global_store_dword v[56:57], v72, off offset:128
	global_store_dword v[144:145], v73, off offset:128
	global_store_dword v[58:59], v74, off offset:128
	global_store_dword v[146:147], v75, off offset:128
	global_store_dword v[60:61], v76, off offset:128
	global_store_dword v[148:149], v77, off offset:128
	global_store_dword v[62:63], v78, off offset:128
	global_store_dword v[150:151], v79, off offset:128
	global_store_dword v[64:65], v80, off offset:128
	global_store_dword v[152:153], v81, off offset:128
	global_store_dword v[34:35], v82, off offset:128
	global_store_dword v[154:155], v83, off offset:128
	global_store_dword v[36:37], v84, off offset:128
	global_store_dword v[156:157], v85, off offset:128
	global_store_dword v[38:39], v86, off offset:128
	global_store_dword v[158:159], v87, off offset:128
	global_store_dword v[40:41], v88, off offset:128
	global_store_dword v[160:161], v89, off offset:128
	global_store_dword v[42:43], v90, off offset:128
	global_store_dword v[162:163], v91, off offset:128
	global_store_dword v[44:45], v92, off offset:128
	global_store_dword v[164:165], v93, off offset:128
	global_store_dword v[46:47], v94, off offset:128
	global_store_dword v[166:167], v95, off offset:128
	s_cbranch_scc1 .LBB0_1186
	v_readlane_b32 s72, v208, 43
	v_readlane_b32 s42, v208, 51
	v_readlane_b32 s54, v209, 14
	s_mov_b32 s62, 0x3b000
	v_readlane_b32 s73, v208, 44
	v_readlane_b32 s74, v208, 45
	v_readlane_b32 s75, v208, 46
	v_readlane_b32 s76, v208, 47
	v_readlane_b32 s77, v208, 48
	v_readlane_b32 s78, v208, 49
	v_readlane_b32 s79, v208, 50
	v_readlane_b32 s43, v208, 52
	v_readlane_b32 s55, v209, 15
	s_mov_b32 s67, 0x3a000
	v_readlane_b32 s97, v209, 2
	v_readlane_b32 s60, v208, 63
	s_mov_b32 s56, 0x10000
	s_mov_b32 s57, 0x20000
	s_mov_b32 s58, 0x30000
	s_movk_i32 s59, 0x70
	s_movk_i32 s53, 0x2000
	s_mov_b32 s52, 0xb000

.LBB0_1298:
	s_ashr_i32 s6, s5, 31
	s_lshr_b32 s6, s6, 27
	s_add_i32 s6, s5, s6
	s_ashr_i32 s34, s6, 5
	s_ashr_i32 s35, s34, 31
	v_mov_b32_e32 v36, v133
	s_lshl_b64 s[6:7], s[34:35], 18
	s_add_u32 s6, s38, s6
	v_ashrrev_i32_e32 v34, 3, v36
	v_ashrrev_i32_e32 v35, 31, v34
	s_addc_u32 s7, s39, s7
	v_lshlrev_b64 v[2:3], 11, v[34:35]
	v_lshlrev_b32_e32 v0, 4, v36
	v_lshl_add_u64 v[2:3], s[6:7], 0, v[2:3]
	v_and_b32_e32 v0, 0x70, v0
	s_lshl_b32 s6, s34, 12
	v_lshl_add_u64 v[66:67], v[2:3], 0, v[0:1]
	v_subrev_u32_e32 v2, s6, v34
	v_add_u32_e32 v2, s4, v2
	v_ashrrev_i32_e32 v3, 31, v2
	v_lshlrev_b64 v[2:3], 11, v[2:3]
	v_lshl_add_u64 v[2:3], s[0:1], 0, v[2:3]
	v_add_co_u32_e32 v70, vcc, s56, v66
	v_lshl_add_u64 v[68:69], v[2:3], 0, v[0:1]
	s_nop 0
	v_addc_co_u32_e32 v71, vcc, 0, v67, vcc
	v_add_co_u32_e32 v72, vcc, s56, v68
	global_load_dwordx4 v[2:5], v[66:67], off
	global_load_dwordx4 v[6:9], v[68:69], off
	v_addc_co_u32_e32 v73, vcc, 0, v69, vcc
	v_add_co_u32_e32 v74, vcc, s57, v66
	global_load_dwordx4 v[10:13], v[70:71], off
	s_nop 0
	v_addc_co_u32_e32 v75, vcc, 0, v67, vcc
	v_add_co_u32_e32 v76, vcc, s57, v68
	global_load_dwordx4 v[14:17], v[72:73], off
	s_nop 0
	v_addc_co_u32_e32 v77, vcc, 0, v69, vcc
	global_load_dwordx4 v[18:21], v[74:75], off
	v_add_co_u32_e32 v78, vcc, s58, v66
	global_load_dwordx4 v[22:25], v[76:77], off
	s_nop 0
	v_addc_co_u32_e32 v79, vcc, 0, v67, vcc
	global_load_dwordx4 v[26:29], v[78:79], off
	v_add_co_u32_e32 v80, vcc, s58, v68
	v_lshlrev_b32_e32 v0, 7, v34
	s_nop 0
	v_addc_co_u32_e32 v81, vcc, 0, v69, vcc
	global_load_dwordx4 v[30:33], v[80:81], off
	global_load_dwordx4 v[94:97], v[66:67], off offset:128
	global_load_dwordx4 v[98:101], v[68:69], off offset:128
	global_load_dwordx4 v[102:105], v[70:71], off offset:128
	global_load_dwordx4 v[106:109], v[72:73], off offset:128
	global_load_dwordx4 v[110:113], v[74:75], off offset:128
	global_load_dwordx4 v[114:117], v[76:77], off offset:128
	global_load_dwordx4 v[118:121], v[78:79], off offset:128
	global_load_dwordx4 v[122:125], v[80:81], off offset:128
	v_lshrrev_b32_e32 v34, 1, v34
	v_xor_b32_e32 v34, v34, v36
	v_lshlrev_b32_e32 v34, 4, v34
	v_and_or_b32 v0, v34, s59, v0
	s_waitcnt vmcnt(26)
	v_and_b32_e32 v82, 31, v36
	v_bfe_u32 v83, v36, 5, 1
	v_ashrrev_i32_e32 v84, 7, v36
	v_bfe_u32 v85, v36, 6, 1
	s_waitcnt vmcnt(15)
	ds_write_b128 v0, v[2:5]
	s_waitcnt vmcnt(14)
	ds_write_b128 v0, v[6:9] offset:32768
	s_waitcnt vmcnt(13)
	ds_write_b128 v0, v[10:13] offset:4096
	s_waitcnt vmcnt(12)
	ds_write_b128 v0, v[14:17] offset:36864
	s_waitcnt vmcnt(11)
	ds_write_b128 v0, v[18:21] offset:8192
	s_waitcnt vmcnt(10)
	ds_write_b128 v0, v[22:25] offset:40960
	s_waitcnt vmcnt(9)
	ds_write_b128 v0, v[26:29] offset:12288
	s_waitcnt vmcnt(8)
	ds_write_b128 v0, v[30:33] offset:45056
	s_waitcnt lgkmcnt(0)
	s_barrier
	global_load_dwordx4 v[126:129], v[66:67], off offset:256
	global_load_dwordx4 v[134:137], v[68:69], off offset:256
	global_load_dwordx4 v[138:141], v[70:71], off offset:256
	global_load_dwordx4 v[142:145], v[72:73], off offset:256
	global_load_dwordx4 v[146:149], v[74:75], off offset:256
	global_load_dwordx4 v[150:153], v[76:77], off offset:256
	global_load_dwordx4 v[154:157], v[78:79], off offset:256
	global_load_dwordx4 v[158:161], v[80:81], off offset:256
	s_waitcnt vmcnt(15)
	ds_write_b128 v0, v[94:97] offset:16384
	s_waitcnt vmcnt(14)
	ds_write_b128 v0, v[98:101] offset:49152
	s_waitcnt vmcnt(13)
	ds_write_b128 v0, v[102:105] offset:20480
	s_waitcnt vmcnt(12)
	ds_write_b128 v0, v[106:109] offset:53248
	s_waitcnt vmcnt(11)
	ds_write_b128 v0, v[110:113] offset:24576
	s_waitcnt vmcnt(10)
	ds_write_b128 v0, v[114:117] offset:57344
	s_waitcnt vmcnt(9)
	ds_write_b128 v0, v[118:121] offset:28672
	s_waitcnt vmcnt(8)
	ds_write_b128 v0, v[122:125] offset:61440
	v_lshrrev_b32_e32 v4, 1, v36
	v_lshlrev_b32_e32 v2, 7, v82
	v_bitop3_b32 v4, v4, v83, 7 bitop3:0x6c
	v_lshl_or_b32 v3, v84, 13, v2
	v_bfe_u32 v5, v36, 1, 3
	v_lshlrev_b32_e32 v4, 4, v4
	v_lshl_or_b32 v2, v85, 13, v2
	v_or_b32_e32 v91, v3, v4
	v_or_b32_e32 v92, v2, v4
	v_bitop3_b32 v4, v83, v5, 2 bitop3:0x36
	v_lshlrev_b32_e32 v4, 4, v4
	v_or_b32_e32 v93, v3, v4
	v_or_b32_e32 v90, v2, v4
	v_bitop3_b32 v4, v83, v5, 4 bitop3:0x36
	v_lshlrev_b32_e32 v4, 4, v4
	v_or_b32_e32 v89, v3, v4
	v_or_b32_e32 v88, v2, v4
	v_bitop3_b32 v4, v83, v5, 6 bitop3:0x36
	v_lshlrev_b32_e32 v4, 4, v4
	v_or_b32_e32 v87, v3, v4
	v_or_b32_e32 v86, v2, v4
	ds_read_b128 v[2:5], v91
	ds_read_b128 v[6:9], v92 offset:32768
	ds_read_b128 v[10:13], v91 offset:4096
	ds_read_b128 v[14:17], v92 offset:36864
	ds_read_b128 v[162:165], v93
	ds_read_b128 v[166:169], v90 offset:32768
	ds_read_b128 v[182:185], v93 offset:4096
	ds_read_b128 v[186:189], v90 offset:36864
	s_waitcnt lgkmcnt(6)
	v_mfma_f32_32x32x16_bf16 v[50:65], v[2:5], v[6:9], 0
	s_waitcnt lgkmcnt(4)
	v_mfma_f32_32x32x16_bf16 v[34:49], v[2:5], v[14:17], 0
	v_mfma_f32_32x32x16_bf16 v[18:33], v[10:13], v[6:9], 0
	v_mfma_f32_32x32x16_bf16 v[2:17], v[10:13], v[14:17], 0
	ds_read_b128 v[190:193], v89
	ds_read_b128 v[194:197], v89 offset:4096
	ds_read_b128 v[198:201], v88 offset:32768
	ds_read_b128 v[202:205], v88 offset:36864
	s_waitcnt lgkmcnt(6)
	v_mfma_f32_32x32x16_bf16 v[50:65], v[162:165], v[166:169], v[50:65]
	s_waitcnt lgkmcnt(4)
	v_mfma_f32_32x32x16_bf16 v[34:49], v[162:165], v[186:189], v[34:49]
	v_mfma_f32_32x32x16_bf16 v[18:33], v[182:185], v[166:169], v[18:33]
	v_mfma_f32_32x32x16_bf16 v[2:17], v[182:185], v[186:189], v[2:17]
	ds_read_b128 v[162:165], v87
	ds_read_b128 v[166:169], v87 offset:4096
	ds_read_b128 v[182:185], v86 offset:32768
	ds_read_b128 v[186:189], v86 offset:36864
	s_waitcnt lgkmcnt(0)
	s_barrier
	global_load_dwordx4 v[94:97], v[66:67], off offset:384
	global_load_dwordx4 v[98:101], v[68:69], off offset:384
	global_load_dwordx4 v[102:105], v[70:71], off offset:384
	global_load_dwordx4 v[106:109], v[72:73], off offset:384
	global_load_dwordx4 v[110:113], v[74:75], off offset:384
	global_load_dwordx4 v[114:117], v[76:77], off offset:384
	global_load_dwordx4 v[118:121], v[78:79], off offset:384
	global_load_dwordx4 v[122:125], v[80:81], off offset:384
	s_waitcnt vmcnt(15)
	ds_write_b128 v0, v[126:129]
	s_waitcnt vmcnt(14)
	ds_write_b128 v0, v[134:137] offset:32768
	s_waitcnt vmcnt(13)
	ds_write_b128 v0, v[138:141] offset:4096
	s_waitcnt vmcnt(12)
	ds_write_b128 v0, v[142:145] offset:36864
	s_waitcnt vmcnt(11)
	ds_write_b128 v0, v[146:149] offset:8192
	s_waitcnt vmcnt(10)
	ds_write_b128 v0, v[150:153] offset:40960
	s_waitcnt vmcnt(9)
	ds_write_b128 v0, v[154:157] offset:12288
	s_waitcnt vmcnt(8)
	ds_write_b128 v0, v[158:161] offset:45056
	v_mfma_f32_32x32x16_bf16 v[50:65], v[190:193], v[198:201], v[50:65]
	v_mfma_f32_32x32x16_bf16 v[34:49], v[190:193], v[202:205], v[34:49]
	v_mfma_f32_32x32x16_bf16 v[18:33], v[194:197], v[198:201], v[18:33]
	v_mfma_f32_32x32x16_bf16 v[2:17], v[194:197], v[202:205], v[2:17]
	v_mfma_f32_32x32x16_bf16 v[50:65], v[162:165], v[182:185], v[50:65]
	v_mfma_f32_32x32x16_bf16 v[34:49], v[162:165], v[186:189], v[34:49]
	v_mfma_f32_32x32x16_bf16 v[18:33], v[166:169], v[182:185], v[18:33]
	v_mfma_f32_32x32x16_bf16 v[2:17], v[166:169], v[186:189], v[2:17]
	ds_read_b128 v[162:165], v91 offset:16384
	ds_read_b128 v[166:169], v92 offset:49152
	ds_read_b128 v[182:185], v91 offset:20480
	ds_read_b128 v[186:189], v92 offset:53248
	ds_read_b128 v[190:193], v93 offset:16384
	ds_read_b128 v[194:197], v90 offset:49152
	ds_read_b128 v[198:201], v93 offset:20480
	ds_read_b128 v[202:205], v90 offset:53248
	s_waitcnt lgkmcnt(6)
	v_mfma_f32_32x32x16_bf16 v[50:65], v[162:165], v[166:169], v[50:65]
	s_waitcnt lgkmcnt(4)
	v_mfma_f32_32x32x16_bf16 v[34:49], v[162:165], v[186:189], v[34:49]
	v_mfma_f32_32x32x16_bf16 v[18:33], v[182:185], v[166:169], v[18:33]
	v_mfma_f32_32x32x16_bf16 v[2:17], v[182:185], v[186:189], v[2:17]
	ds_read_b128 v[162:165], v89 offset:16384
	ds_read_b128 v[166:169], v89 offset:20480
	ds_read_b128 v[182:185], v88 offset:49152
	ds_read_b128 v[186:189], v88 offset:53248
	s_waitcnt lgkmcnt(6)
	v_mfma_f32_32x32x16_bf16 v[50:65], v[190:193], v[194:197], v[50:65]
	s_waitcnt lgkmcnt(4)
	v_mfma_f32_32x32x16_bf16 v[34:49], v[190:193], v[202:205], v[34:49]
	v_mfma_f32_32x32x16_bf16 v[18:33], v[198:201], v[194:197], v[18:33]
	v_mfma_f32_32x32x16_bf16 v[2:17], v[198:201], v[202:205], v[2:17]
	ds_read_b128 v[190:193], v87 offset:16384
	ds_read_b128 v[194:197], v87 offset:20480
	ds_read_b128 v[198:201], v86 offset:49152
	ds_read_b128 v[202:205], v86 offset:53248
	s_waitcnt lgkmcnt(0)
	s_barrier
	global_load_dwordx4 v[126:129], v[66:67], off offset:512
	global_load_dwordx4 v[134:137], v[68:69], off offset:512
	global_load_dwordx4 v[138:141], v[70:71], off offset:512
	global_load_dwordx4 v[142:145], v[72:73], off offset:512
	global_load_dwordx4 v[146:149], v[74:75], off offset:512
	global_load_dwordx4 v[150:153], v[76:77], off offset:512
	global_load_dwordx4 v[154:157], v[78:79], off offset:512
	global_load_dwordx4 v[158:161], v[80:81], off offset:512
	s_waitcnt vmcnt(15)
	ds_write_b128 v0, v[94:97] offset:16384
	s_waitcnt vmcnt(14)
	ds_write_b128 v0, v[98:101] offset:49152
	s_waitcnt vmcnt(13)
	ds_write_b128 v0, v[102:105] offset:20480
	s_waitcnt vmcnt(12)
	ds_write_b128 v0, v[106:109] offset:53248
	s_waitcnt vmcnt(11)
	ds_write_b128 v0, v[110:113] offset:24576
	s_waitcnt vmcnt(10)
	ds_write_b128 v0, v[114:117] offset:57344
	s_waitcnt vmcnt(9)
	ds_write_b128 v0, v[118:121] offset:28672
	s_waitcnt vmcnt(8)
	ds_write_b128 v0, v[122:125] offset:61440
	v_mfma_f32_32x32x16_bf16 v[50:65], v[162:165], v[182:185], v[50:65]
	v_mfma_f32_32x32x16_bf16 v[34:49], v[162:165], v[186:189], v[34:49]
	v_mfma_f32_32x32x16_bf16 v[18:33], v[166:169], v[182:185], v[18:33]
	v_mfma_f32_32x32x16_bf16 v[2:17], v[166:169], v[186:189], v[2:17]
	v_mfma_f32_32x32x16_bf16 v[50:65], v[190:193], v[198:201], v[50:65]
	v_mfma_f32_32x32x16_bf16 v[34:49], v[190:193], v[202:205], v[34:49]
	v_mfma_f32_32x32x16_bf16 v[18:33], v[194:197], v[198:201], v[18:33]
	v_mfma_f32_32x32x16_bf16 v[2:17], v[194:197], v[202:205], v[2:17]
	ds_read_b128 v[162:165], v91
	ds_read_b128 v[166:169], v92 offset:32768
	ds_read_b128 v[182:185], v91 offset:4096
	ds_read_b128 v[186:189], v92 offset:36864
	ds_read_b128 v[190:193], v93
	ds_read_b128 v[194:197], v90 offset:32768
	ds_read_b128 v[198:201], v93 offset:4096
	ds_read_b128 v[202:205], v90 offset:36864
	s_waitcnt lgkmcnt(6)
	v_mfma_f32_32x32x16_bf16 v[50:65], v[162:165], v[166:169], v[50:65]
	s_waitcnt lgkmcnt(4)
	v_mfma_f32_32x32x16_bf16 v[34:49], v[162:165], v[186:189], v[34:49]
	v_mfma_f32_32x32x16_bf16 v[18:33], v[182:185], v[166:169], v[18:33]
	v_mfma_f32_32x32x16_bf16 v[2:17], v[182:185], v[186:189], v[2:17]
	ds_read_b128 v[162:165], v89
	ds_read_b128 v[166:169], v89 offset:4096
	ds_read_b128 v[182:185], v88 offset:32768
	ds_read_b128 v[186:189], v88 offset:36864
	s_waitcnt lgkmcnt(6)
	v_mfma_f32_32x32x16_bf16 v[50:65], v[190:193], v[194:197], v[50:65]
	s_waitcnt lgkmcnt(4)
	v_mfma_f32_32x32x16_bf16 v[34:49], v[190:193], v[202:205], v[34:49]
	v_mfma_f32_32x32x16_bf16 v[18:33], v[198:201], v[194:197], v[18:33]
	v_mfma_f32_32x32x16_bf16 v[2:17], v[198:201], v[202:205], v[2:17]
	ds_read_b128 v[190:193], v87
	ds_read_b128 v[194:197], v87 offset:4096
	ds_read_b128 v[198:201], v86 offset:32768
	ds_read_b128 v[202:205], v86 offset:36864
	s_waitcnt lgkmcnt(0)
	s_barrier
	global_load_dwordx4 v[94:97], v[66:67], off offset:640
	global_load_dwordx4 v[98:101], v[68:69], off offset:640
	global_load_dwordx4 v[102:105], v[70:71], off offset:640
	global_load_dwordx4 v[106:109], v[72:73], off offset:640
	global_load_dwordx4 v[110:113], v[74:75], off offset:640
	global_load_dwordx4 v[114:117], v[76:77], off offset:640
	global_load_dwordx4 v[118:121], v[78:79], off offset:640
	global_load_dwordx4 v[122:125], v[80:81], off offset:640
	s_waitcnt vmcnt(15)
	ds_write_b128 v0, v[126:129]
	s_waitcnt vmcnt(14)
	ds_write_b128 v0, v[134:137] offset:32768
	s_waitcnt vmcnt(13)
	ds_write_b128 v0, v[138:141] offset:4096
	s_waitcnt vmcnt(12)
	ds_write_b128 v0, v[142:145] offset:36864
	s_waitcnt vmcnt(11)
	ds_write_b128 v0, v[146:149] offset:8192
	s_waitcnt vmcnt(10)
	ds_write_b128 v0, v[150:153] offset:40960
	s_waitcnt vmcnt(9)
	ds_write_b128 v0, v[154:157] offset:12288
	s_waitcnt vmcnt(8)
	ds_write_b128 v0, v[158:161] offset:45056
	v_mfma_f32_32x32x16_bf16 v[50:65], v[162:165], v[182:185], v[50:65]
	v_mfma_f32_32x32x16_bf16 v[34:49], v[162:165], v[186:189], v[34:49]
	v_mfma_f32_32x32x16_bf16 v[18:33], v[166:169], v[182:185], v[18:33]
	v_mfma_f32_32x32x16_bf16 v[2:17], v[166:169], v[186:189], v[2:17]
	v_mfma_f32_32x32x16_bf16 v[50:65], v[190:193], v[198:201], v[50:65]
	v_mfma_f32_32x32x16_bf16 v[34:49], v[190:193], v[202:205], v[34:49]
	v_mfma_f32_32x32x16_bf16 v[18:33], v[194:197], v[198:201], v[18:33]
	v_mfma_f32_32x32x16_bf16 v[2:17], v[194:197], v[202:205], v[2:17]
	ds_read_b128 v[162:165], v91 offset:16384
	ds_read_b128 v[166:169], v92 offset:49152
	ds_read_b128 v[182:185], v91 offset:20480
	ds_read_b128 v[186:189], v92 offset:53248
	ds_read_b128 v[190:193], v93 offset:16384
	ds_read_b128 v[194:197], v90 offset:49152
	ds_read_b128 v[198:201], v93 offset:20480
	ds_read_b128 v[202:205], v90 offset:53248
	s_waitcnt lgkmcnt(6)
	v_mfma_f32_32x32x16_bf16 v[50:65], v[162:165], v[166:169], v[50:65]
	s_waitcnt lgkmcnt(4)
	v_mfma_f32_32x32x16_bf16 v[34:49], v[162:165], v[186:189], v[34:49]
	v_mfma_f32_32x32x16_bf16 v[18:33], v[182:185], v[166:169], v[18:33]
	v_mfma_f32_32x32x16_bf16 v[2:17], v[182:185], v[186:189], v[2:17]
	ds_read_b128 v[162:165], v89 offset:16384
	ds_read_b128 v[166:169], v89 offset:20480
	ds_read_b128 v[182:185], v88 offset:49152
	ds_read_b128 v[186:189], v88 offset:53248
	s_waitcnt lgkmcnt(6)
	v_mfma_f32_32x32x16_bf16 v[50:65], v[190:193], v[194:197], v[50:65]
	s_waitcnt lgkmcnt(4)
	v_mfma_f32_32x32x16_bf16 v[34:49], v[190:193], v[202:205], v[34:49]
	v_mfma_f32_32x32x16_bf16 v[18:33], v[198:201], v[194:197], v[18:33]
	v_mfma_f32_32x32x16_bf16 v[2:17], v[198:201], v[202:205], v[2:17]
	ds_read_b128 v[190:193], v87 offset:16384
	ds_read_b128 v[194:197], v87 offset:20480
	ds_read_b128 v[198:201], v86 offset:49152
	ds_read_b128 v[202:205], v86 offset:53248
	s_waitcnt lgkmcnt(0)
	s_barrier
	global_load_dwordx4 v[126:129], v[66:67], off offset:768
	global_load_dwordx4 v[134:137], v[68:69], off offset:768
	global_load_dwordx4 v[138:141], v[70:71], off offset:768
	global_load_dwordx4 v[142:145], v[72:73], off offset:768
	global_load_dwordx4 v[146:149], v[74:75], off offset:768
	global_load_dwordx4 v[150:153], v[76:77], off offset:768
	global_load_dwordx4 v[154:157], v[78:79], off offset:768
	global_load_dwordx4 v[158:161], v[80:81], off offset:768
	s_waitcnt vmcnt(15)
	ds_write_b128 v0, v[94:97] offset:16384
	s_waitcnt vmcnt(14)
	ds_write_b128 v0, v[98:101] offset:49152
	s_waitcnt vmcnt(13)
	ds_write_b128 v0, v[102:105] offset:20480
	s_waitcnt vmcnt(12)
	ds_write_b128 v0, v[106:109] offset:53248
	s_waitcnt vmcnt(11)
	ds_write_b128 v0, v[110:113] offset:24576
	s_waitcnt vmcnt(10)
	ds_write_b128 v0, v[114:117] offset:57344
	s_waitcnt vmcnt(9)
	ds_write_b128 v0, v[118:121] offset:28672
	s_waitcnt vmcnt(8)
	ds_write_b128 v0, v[122:125] offset:61440
	v_mfma_f32_32x32x16_bf16 v[50:65], v[162:165], v[182:185], v[50:65]
	v_mfma_f32_32x32x16_bf16 v[34:49], v[162:165], v[186:189], v[34:49]
	v_mfma_f32_32x32x16_bf16 v[18:33], v[166:169], v[182:185], v[18:33]
	v_mfma_f32_32x32x16_bf16 v[2:17], v[166:169], v[186:189], v[2:17]
	v_mfma_f32_32x32x16_bf16 v[50:65], v[190:193], v[198:201], v[50:65]
	v_mfma_f32_32x32x16_bf16 v[34:49], v[190:193], v[202:205], v[34:49]
	v_mfma_f32_32x32x16_bf16 v[18:33], v[194:197], v[198:201], v[18:33]
	v_mfma_f32_32x32x16_bf16 v[2:17], v[194:197], v[202:205], v[2:17]
	ds_read_b128 v[162:165], v91
	ds_read_b128 v[166:169], v92 offset:32768
	ds_read_b128 v[182:185], v91 offset:4096
	ds_read_b128 v[186:189], v92 offset:36864
	ds_read_b128 v[190:193], v93
	ds_read_b128 v[194:197], v90 offset:32768
	ds_read_b128 v[198:201], v93 offset:4096
	ds_read_b128 v[202:205], v90 offset:36864
	s_waitcnt lgkmcnt(6)
	v_mfma_f32_32x32x16_bf16 v[50:65], v[162:165], v[166:169], v[50:65]
	s_waitcnt lgkmcnt(4)
	v_mfma_f32_32x32x16_bf16 v[34:49], v[162:165], v[186:189], v[34:49]
	v_mfma_f32_32x32x16_bf16 v[18:33], v[182:185], v[166:169], v[18:33]
	v_mfma_f32_32x32x16_bf16 v[2:17], v[182:185], v[186:189], v[2:17]
	ds_read_b128 v[162:165], v89
	ds_read_b128 v[166:169], v89 offset:4096
	ds_read_b128 v[182:185], v88 offset:32768
	ds_read_b128 v[186:189], v88 offset:36864
	s_waitcnt lgkmcnt(6)
	v_mfma_f32_32x32x16_bf16 v[50:65], v[190:193], v[194:197], v[50:65]
	s_waitcnt lgkmcnt(4)
	v_mfma_f32_32x32x16_bf16 v[34:49], v[190:193], v[202:205], v[34:49]
	v_mfma_f32_32x32x16_bf16 v[18:33], v[198:201], v[194:197], v[18:33]
	v_mfma_f32_32x32x16_bf16 v[2:17], v[198:201], v[202:205], v[2:17]
	ds_read_b128 v[190:193], v87
	ds_read_b128 v[194:197], v87 offset:4096
	ds_read_b128 v[198:201], v86 offset:32768
	ds_read_b128 v[202:205], v86 offset:36864
	s_waitcnt lgkmcnt(0)
	s_barrier
	global_load_dwordx4 v[94:97], v[66:67], off offset:896
	global_load_dwordx4 v[98:101], v[68:69], off offset:896
	global_load_dwordx4 v[102:105], v[70:71], off offset:896
	global_load_dwordx4 v[106:109], v[72:73], off offset:896
	global_load_dwordx4 v[110:113], v[74:75], off offset:896
	global_load_dwordx4 v[114:117], v[76:77], off offset:896
	global_load_dwordx4 v[118:121], v[78:79], off offset:896
	global_load_dwordx4 v[122:125], v[80:81], off offset:896
	s_waitcnt vmcnt(15)
	ds_write_b128 v0, v[126:129]
	s_waitcnt vmcnt(14)
	ds_write_b128 v0, v[134:137] offset:32768
	s_waitcnt vmcnt(13)
	ds_write_b128 v0, v[138:141] offset:4096
	s_waitcnt vmcnt(12)
	ds_write_b128 v0, v[142:145] offset:36864
	s_waitcnt vmcnt(11)
	ds_write_b128 v0, v[146:149] offset:8192
	s_waitcnt vmcnt(10)
	ds_write_b128 v0, v[150:153] offset:40960
	s_waitcnt vmcnt(9)
	ds_write_b128 v0, v[154:157] offset:12288
	s_waitcnt vmcnt(8)
	ds_write_b128 v0, v[158:161] offset:45056
	v_mfma_f32_32x32x16_bf16 v[50:65], v[162:165], v[182:185], v[50:65]
	v_mfma_f32_32x32x16_bf16 v[34:49], v[162:165], v[186:189], v[34:49]
	v_mfma_f32_32x32x16_bf16 v[18:33], v[166:169], v[182:185], v[18:33]
	v_mfma_f32_32x32x16_bf16 v[2:17], v[166:169], v[186:189], v[2:17]
	v_mfma_f32_32x32x16_bf16 v[50:65], v[190:193], v[198:201], v[50:65]
	v_mfma_f32_32x32x16_bf16 v[34:49], v[190:193], v[202:205], v[34:49]
	v_mfma_f32_32x32x16_bf16 v[18:33], v[194:197], v[198:201], v[18:33]
	v_mfma_f32_32x32x16_bf16 v[2:17], v[194:197], v[202:205], v[2:17]
	ds_read_b128 v[162:165], v91 offset:16384
	ds_read_b128 v[166:169], v92 offset:49152
	ds_read_b128 v[182:185], v91 offset:20480
	ds_read_b128 v[186:189], v92 offset:53248
	ds_read_b128 v[190:193], v93 offset:16384
	ds_read_b128 v[194:197], v90 offset:49152
	ds_read_b128 v[198:201], v93 offset:20480
	ds_read_b128 v[202:205], v90 offset:53248
	s_waitcnt lgkmcnt(6)
	v_mfma_f32_32x32x16_bf16 v[50:65], v[162:165], v[166:169], v[50:65]
	s_waitcnt lgkmcnt(4)
	v_mfma_f32_32x32x16_bf16 v[34:49], v[162:165], v[186:189], v[34:49]
	v_mfma_f32_32x32x16_bf16 v[18:33], v[182:185], v[166:169], v[18:33]
	v_mfma_f32_32x32x16_bf16 v[2:17], v[182:185], v[186:189], v[2:17]
	ds_read_b128 v[162:165], v89 offset:16384
	ds_read_b128 v[166:169], v89 offset:20480
	ds_read_b128 v[182:185], v88 offset:49152
	ds_read_b128 v[186:189], v88 offset:53248
	s_waitcnt lgkmcnt(6)
	v_mfma_f32_32x32x16_bf16 v[50:65], v[190:193], v[194:197], v[50:65]
	s_waitcnt lgkmcnt(4)
	v_mfma_f32_32x32x16_bf16 v[34:49], v[190:193], v[202:205], v[34:49]
	v_mfma_f32_32x32x16_bf16 v[18:33], v[198:201], v[194:197], v[18:33]
	v_mfma_f32_32x32x16_bf16 v[2:17], v[198:201], v[202:205], v[2:17]
	ds_read_b128 v[190:193], v87 offset:16384
	ds_read_b128 v[194:197], v87 offset:20480
	ds_read_b128 v[198:201], v86 offset:49152
	ds_read_b128 v[202:205], v86 offset:53248
	s_waitcnt lgkmcnt(0)
	s_barrier
	global_load_dwordx4 v[126:129], v[66:67], off offset:1024
	global_load_dwordx4 v[134:137], v[68:69], off offset:1024
	global_load_dwordx4 v[138:141], v[70:71], off offset:1024
	global_load_dwordx4 v[142:145], v[72:73], off offset:1024
	global_load_dwordx4 v[146:149], v[74:75], off offset:1024
	global_load_dwordx4 v[150:153], v[76:77], off offset:1024
	global_load_dwordx4 v[154:157], v[78:79], off offset:1024
	global_load_dwordx4 v[158:161], v[80:81], off offset:1024
	s_waitcnt vmcnt(15)
	ds_write_b128 v0, v[94:97] offset:16384
	s_waitcnt vmcnt(14)
	ds_write_b128 v0, v[98:101] offset:49152
	s_waitcnt vmcnt(13)
	ds_write_b128 v0, v[102:105] offset:20480
	s_waitcnt vmcnt(12)
	ds_write_b128 v0, v[106:109] offset:53248
	s_waitcnt vmcnt(11)
	ds_write_b128 v0, v[110:113] offset:24576
	s_waitcnt vmcnt(10)
	ds_write_b128 v0, v[114:117] offset:57344
	s_waitcnt vmcnt(9)
	ds_write_b128 v0, v[118:121] offset:28672
	s_waitcnt vmcnt(8)
	ds_write_b128 v0, v[122:125] offset:61440
	v_mfma_f32_32x32x16_bf16 v[50:65], v[162:165], v[182:185], v[50:65]
	v_mfma_f32_32x32x16_bf16 v[34:49], v[162:165], v[186:189], v[34:49]
	v_mfma_f32_32x32x16_bf16 v[18:33], v[166:169], v[182:185], v[18:33]
	v_mfma_f32_32x32x16_bf16 v[2:17], v[166:169], v[186:189], v[2:17]
	v_mfma_f32_32x32x16_bf16 v[50:65], v[190:193], v[198:201], v[50:65]
	v_mfma_f32_32x32x16_bf16 v[34:49], v[190:193], v[202:205], v[34:49]
	v_mfma_f32_32x32x16_bf16 v[18:33], v[194:197], v[198:201], v[18:33]
	v_mfma_f32_32x32x16_bf16 v[2:17], v[194:197], v[202:205], v[2:17]
	ds_read_b128 v[162:165], v91
	ds_read_b128 v[166:169], v92 offset:32768
	ds_read_b128 v[182:185], v91 offset:4096
	ds_read_b128 v[186:189], v92 offset:36864
	ds_read_b128 v[190:193], v93
	ds_read_b128 v[194:197], v90 offset:32768
	ds_read_b128 v[198:201], v93 offset:4096
	ds_read_b128 v[202:205], v90 offset:36864
	s_waitcnt lgkmcnt(6)
	v_mfma_f32_32x32x16_bf16 v[50:65], v[162:165], v[166:169], v[50:65]
	s_waitcnt lgkmcnt(4)
	v_mfma_f32_32x32x16_bf16 v[34:49], v[162:165], v[186:189], v[34:49]
	v_mfma_f32_32x32x16_bf16 v[18:33], v[182:185], v[166:169], v[18:33]
	v_mfma_f32_32x32x16_bf16 v[2:17], v[182:185], v[186:189], v[2:17]
	ds_read_b128 v[162:165], v89
	ds_read_b128 v[166:169], v89 offset:4096
	ds_read_b128 v[182:185], v88 offset:32768
	ds_read_b128 v[186:189], v88 offset:36864
	s_waitcnt lgkmcnt(6)
	v_mfma_f32_32x32x16_bf16 v[50:65], v[190:193], v[194:197], v[50:65]
	s_waitcnt lgkmcnt(4)
	v_mfma_f32_32x32x16_bf16 v[34:49], v[190:193], v[202:205], v[34:49]
	v_mfma_f32_32x32x16_bf16 v[18:33], v[198:201], v[194:197], v[18:33]
	v_mfma_f32_32x32x16_bf16 v[2:17], v[198:201], v[202:205], v[2:17]
	ds_read_b128 v[190:193], v87
	ds_read_b128 v[194:197], v87 offset:4096
	ds_read_b128 v[198:201], v86 offset:32768
	ds_read_b128 v[202:205], v86 offset:36864
	s_waitcnt lgkmcnt(0)
	s_barrier
	global_load_dwordx4 v[94:97], v[66:67], off offset:1152
	global_load_dwordx4 v[98:101], v[68:69], off offset:1152
	global_load_dwordx4 v[102:105], v[70:71], off offset:1152
	global_load_dwordx4 v[106:109], v[72:73], off offset:1152
	global_load_dwordx4 v[110:113], v[74:75], off offset:1152
	global_load_dwordx4 v[114:117], v[76:77], off offset:1152
	global_load_dwordx4 v[118:121], v[78:79], off offset:1152
	global_load_dwordx4 v[122:125], v[80:81], off offset:1152
	s_waitcnt vmcnt(15)
	ds_write_b128 v0, v[126:129]
	s_waitcnt vmcnt(14)
	ds_write_b128 v0, v[134:137] offset:32768
	s_waitcnt vmcnt(13)
	ds_write_b128 v0, v[138:141] offset:4096
	s_waitcnt vmcnt(12)
	ds_write_b128 v0, v[142:145] offset:36864
	s_waitcnt vmcnt(11)
	ds_write_b128 v0, v[146:149] offset:8192
	s_waitcnt vmcnt(10)
	ds_write_b128 v0, v[150:153] offset:40960
	s_waitcnt vmcnt(9)
	ds_write_b128 v0, v[154:157] offset:12288
	s_waitcnt vmcnt(8)
	ds_write_b128 v0, v[158:161] offset:45056
	v_mfma_f32_32x32x16_bf16 v[50:65], v[162:165], v[182:185], v[50:65]
	v_mfma_f32_32x32x16_bf16 v[34:49], v[162:165], v[186:189], v[34:49]
	v_mfma_f32_32x32x16_bf16 v[18:33], v[166:169], v[182:185], v[18:33]
	v_mfma_f32_32x32x16_bf16 v[2:17], v[166:169], v[186:189], v[2:17]
	v_mfma_f32_32x32x16_bf16 v[50:65], v[190:193], v[198:201], v[50:65]
	v_mfma_f32_32x32x16_bf16 v[34:49], v[190:193], v[202:205], v[34:49]
	v_mfma_f32_32x32x16_bf16 v[18:33], v[194:197], v[198:201], v[18:33]
	v_mfma_f32_32x32x16_bf16 v[2:17], v[194:197], v[202:205], v[2:17]
	ds_read_b128 v[162:165], v91 offset:16384
	ds_read_b128 v[166:169], v92 offset:49152
	ds_read_b128 v[182:185], v91 offset:20480
	ds_read_b128 v[186:189], v92 offset:53248
	ds_read_b128 v[190:193], v93 offset:16384
	ds_read_b128 v[194:197], v90 offset:49152
	ds_read_b128 v[198:201], v93 offset:20480
	ds_read_b128 v[202:205], v90 offset:53248
	s_waitcnt lgkmcnt(6)
	v_mfma_f32_32x32x16_bf16 v[50:65], v[162:165], v[166:169], v[50:65]
	s_waitcnt lgkmcnt(4)
	v_mfma_f32_32x32x16_bf16 v[34:49], v[162:165], v[186:189], v[34:49]
	v_mfma_f32_32x32x16_bf16 v[18:33], v[182:185], v[166:169], v[18:33]
	v_mfma_f32_32x32x16_bf16 v[2:17], v[182:185], v[186:189], v[2:17]
	ds_read_b128 v[162:165], v89 offset:16384
	ds_read_b128 v[166:169], v89 offset:20480
	ds_read_b128 v[182:185], v88 offset:49152
	ds_read_b128 v[186:189], v88 offset:53248
	s_waitcnt lgkmcnt(6)
	v_mfma_f32_32x32x16_bf16 v[50:65], v[190:193], v[194:197], v[50:65]
	s_waitcnt lgkmcnt(4)
	v_mfma_f32_32x32x16_bf16 v[34:49], v[190:193], v[202:205], v[34:49]
	v_mfma_f32_32x32x16_bf16 v[18:33], v[198:201], v[194:197], v[18:33]
	v_mfma_f32_32x32x16_bf16 v[2:17], v[198:201], v[202:205], v[2:17]
	ds_read_b128 v[190:193], v87 offset:16384
	ds_read_b128 v[194:197], v87 offset:20480
	ds_read_b128 v[198:201], v86 offset:49152
	ds_read_b128 v[202:205], v86 offset:53248
	s_waitcnt lgkmcnt(0)
	s_barrier
	global_load_dwordx4 v[126:129], v[66:67], off offset:1280
	global_load_dwordx4 v[134:137], v[68:69], off offset:1280
	global_load_dwordx4 v[138:141], v[70:71], off offset:1280
	global_load_dwordx4 v[142:145], v[72:73], off offset:1280
	global_load_dwordx4 v[146:149], v[74:75], off offset:1280
	global_load_dwordx4 v[150:153], v[76:77], off offset:1280
	global_load_dwordx4 v[154:157], v[78:79], off offset:1280
	global_load_dwordx4 v[158:161], v[80:81], off offset:1280
	s_waitcnt vmcnt(15)
	ds_write_b128 v0, v[94:97] offset:16384
	s_waitcnt vmcnt(14)
	ds_write_b128 v0, v[98:101] offset:49152
	s_waitcnt vmcnt(13)
	ds_write_b128 v0, v[102:105] offset:20480
	s_waitcnt vmcnt(12)
	ds_write_b128 v0, v[106:109] offset:53248
	s_waitcnt vmcnt(11)
	ds_write_b128 v0, v[110:113] offset:24576
	s_waitcnt vmcnt(10)
	ds_write_b128 v0, v[114:117] offset:57344
	s_waitcnt vmcnt(9)
	ds_write_b128 v0, v[118:121] offset:28672
	s_waitcnt vmcnt(8)
	ds_write_b128 v0, v[122:125] offset:61440
	v_mfma_f32_32x32x16_bf16 v[50:65], v[162:165], v[182:185], v[50:65]
	v_mfma_f32_32x32x16_bf16 v[34:49], v[162:165], v[186:189], v[34:49]
	v_mfma_f32_32x32x16_bf16 v[18:33], v[166:169], v[182:185], v[18:33]
	v_mfma_f32_32x32x16_bf16 v[2:17], v[166:169], v[186:189], v[2:17]
	v_mfma_f32_32x32x16_bf16 v[50:65], v[190:193], v[198:201], v[50:65]
	v_mfma_f32_32x32x16_bf16 v[34:49], v[190:193], v[202:205], v[34:49]
	v_mfma_f32_32x32x16_bf16 v[18:33], v[194:197], v[198:201], v[18:33]
	v_mfma_f32_32x32x16_bf16 v[2:17], v[194:197], v[202:205], v[2:17]
	ds_read_b128 v[162:165], v91
	ds_read_b128 v[166:169], v92 offset:32768
	ds_read_b128 v[182:185], v91 offset:4096
	ds_read_b128 v[186:189], v92 offset:36864
	ds_read_b128 v[190:193], v93
	ds_read_b128 v[194:197], v90 offset:32768
	ds_read_b128 v[198:201], v93 offset:4096
	ds_read_b128 v[202:205], v90 offset:36864
	s_waitcnt lgkmcnt(6)
	v_mfma_f32_32x32x16_bf16 v[50:65], v[162:165], v[166:169], v[50:65]
	s_waitcnt lgkmcnt(4)
	v_mfma_f32_32x32x16_bf16 v[34:49], v[162:165], v[186:189], v[34:49]
	v_mfma_f32_32x32x16_bf16 v[18:33], v[182:185], v[166:169], v[18:33]
	v_mfma_f32_32x32x16_bf16 v[2:17], v[182:185], v[186:189], v[2:17]
	ds_read_b128 v[162:165], v89
	ds_read_b128 v[166:169], v89 offset:4096
	ds_read_b128 v[182:185], v88 offset:32768
	ds_read_b128 v[186:189], v88 offset:36864
	s_waitcnt lgkmcnt(6)
	v_mfma_f32_32x32x16_bf16 v[50:65], v[190:193], v[194:197], v[50:65]
	s_waitcnt lgkmcnt(4)
	v_mfma_f32_32x32x16_bf16 v[34:49], v[190:193], v[202:205], v[34:49]
	v_mfma_f32_32x32x16_bf16 v[18:33], v[198:201], v[194:197], v[18:33]
	v_mfma_f32_32x32x16_bf16 v[2:17], v[198:201], v[202:205], v[2:17]
	ds_read_b128 v[190:193], v87
	ds_read_b128 v[194:197], v87 offset:4096
	ds_read_b128 v[198:201], v86 offset:32768
	ds_read_b128 v[202:205], v86 offset:36864
	s_waitcnt lgkmcnt(0)
	s_barrier
	global_load_dwordx4 v[94:97], v[66:67], off offset:1408
	global_load_dwordx4 v[98:101], v[68:69], off offset:1408
	global_load_dwordx4 v[102:105], v[70:71], off offset:1408
	global_load_dwordx4 v[106:109], v[72:73], off offset:1408
	global_load_dwordx4 v[110:113], v[74:75], off offset:1408
	global_load_dwordx4 v[114:117], v[76:77], off offset:1408
	global_load_dwordx4 v[118:121], v[78:79], off offset:1408
	global_load_dwordx4 v[122:125], v[80:81], off offset:1408
	s_waitcnt vmcnt(15)
	ds_write_b128 v0, v[126:129]
	s_waitcnt vmcnt(14)
	ds_write_b128 v0, v[134:137] offset:32768
	s_waitcnt vmcnt(13)
	ds_write_b128 v0, v[138:141] offset:4096
	s_waitcnt vmcnt(12)
	ds_write_b128 v0, v[142:145] offset:36864
	s_waitcnt vmcnt(11)
	ds_write_b128 v0, v[146:149] offset:8192
	s_waitcnt vmcnt(10)
	ds_write_b128 v0, v[150:153] offset:40960
	s_waitcnt vmcnt(9)
	ds_write_b128 v0, v[154:157] offset:12288
	s_waitcnt vmcnt(8)
	ds_write_b128 v0, v[158:161] offset:45056
	v_mfma_f32_32x32x16_bf16 v[50:65], v[162:165], v[182:185], v[50:65]
	v_mfma_f32_32x32x16_bf16 v[34:49], v[162:165], v[186:189], v[34:49]
	v_mfma_f32_32x32x16_bf16 v[18:33], v[166:169], v[182:185], v[18:33]
	v_mfma_f32_32x32x16_bf16 v[2:17], v[166:169], v[186:189], v[2:17]
	v_mfma_f32_32x32x16_bf16 v[50:65], v[190:193], v[198:201], v[50:65]
	v_mfma_f32_32x32x16_bf16 v[34:49], v[190:193], v[202:205], v[34:49]
	v_mfma_f32_32x32x16_bf16 v[18:33], v[194:197], v[198:201], v[18:33]
	v_mfma_f32_32x32x16_bf16 v[2:17], v[194:197], v[202:205], v[2:17]
	ds_read_b128 v[162:165], v91 offset:16384
	ds_read_b128 v[166:169], v92 offset:49152
	ds_read_b128 v[182:185], v91 offset:20480
	ds_read_b128 v[186:189], v92 offset:53248
	ds_read_b128 v[190:193], v93 offset:16384
	ds_read_b128 v[194:197], v90 offset:49152
	ds_read_b128 v[198:201], v93 offset:20480
	ds_read_b128 v[202:205], v90 offset:53248
	s_waitcnt lgkmcnt(6)
	v_mfma_f32_32x32x16_bf16 v[50:65], v[162:165], v[166:169], v[50:65]
	s_waitcnt lgkmcnt(4)
	v_mfma_f32_32x32x16_bf16 v[34:49], v[162:165], v[186:189], v[34:49]
	v_mfma_f32_32x32x16_bf16 v[18:33], v[182:185], v[166:169], v[18:33]
	v_mfma_f32_32x32x16_bf16 v[2:17], v[182:185], v[186:189], v[2:17]
	ds_read_b128 v[162:165], v89 offset:16384
	ds_read_b128 v[166:169], v89 offset:20480
	ds_read_b128 v[182:185], v88 offset:49152
	ds_read_b128 v[186:189], v88 offset:53248
	s_waitcnt lgkmcnt(6)
	v_mfma_f32_32x32x16_bf16 v[50:65], v[190:193], v[194:197], v[50:65]
	s_waitcnt lgkmcnt(4)
	v_mfma_f32_32x32x16_bf16 v[34:49], v[190:193], v[202:205], v[34:49]
	v_mfma_f32_32x32x16_bf16 v[18:33], v[198:201], v[194:197], v[18:33]
	v_mfma_f32_32x32x16_bf16 v[2:17], v[198:201], v[202:205], v[2:17]
	ds_read_b128 v[190:193], v87 offset:16384
	ds_read_b128 v[194:197], v87 offset:20480
	ds_read_b128 v[198:201], v86 offset:49152
	ds_read_b128 v[202:205], v86 offset:53248
	s_waitcnt lgkmcnt(0)
	s_barrier
	global_load_dwordx4 v[126:129], v[66:67], off offset:1536
	global_load_dwordx4 v[134:137], v[68:69], off offset:1536
	global_load_dwordx4 v[138:141], v[70:71], off offset:1536
	global_load_dwordx4 v[142:145], v[72:73], off offset:1536
	global_load_dwordx4 v[146:149], v[74:75], off offset:1536
	global_load_dwordx4 v[150:153], v[76:77], off offset:1536
	global_load_dwordx4 v[154:157], v[78:79], off offset:1536
	global_load_dwordx4 v[158:161], v[80:81], off offset:1536
	s_waitcnt vmcnt(15)
	ds_write_b128 v0, v[94:97] offset:16384
	s_waitcnt vmcnt(14)
	ds_write_b128 v0, v[98:101] offset:49152
	s_waitcnt vmcnt(13)
	ds_write_b128 v0, v[102:105] offset:20480
	s_waitcnt vmcnt(12)
	ds_write_b128 v0, v[106:109] offset:53248
	s_waitcnt vmcnt(11)
	ds_write_b128 v0, v[110:113] offset:24576
	s_waitcnt vmcnt(10)
	ds_write_b128 v0, v[114:117] offset:57344
	s_waitcnt vmcnt(9)
	ds_write_b128 v0, v[118:121] offset:28672
	s_waitcnt vmcnt(8)
	ds_write_b128 v0, v[122:125] offset:61440
	v_mfma_f32_32x32x16_bf16 v[50:65], v[162:165], v[182:185], v[50:65]
	v_mfma_f32_32x32x16_bf16 v[34:49], v[162:165], v[186:189], v[34:49]
	v_mfma_f32_32x32x16_bf16 v[18:33], v[166:169], v[182:185], v[18:33]
	v_mfma_f32_32x32x16_bf16 v[2:17], v[166:169], v[186:189], v[2:17]
	v_mfma_f32_32x32x16_bf16 v[50:65], v[190:193], v[198:201], v[50:65]
	v_mfma_f32_32x32x16_bf16 v[34:49], v[190:193], v[202:205], v[34:49]
	v_mfma_f32_32x32x16_bf16 v[18:33], v[194:197], v[198:201], v[18:33]
	v_mfma_f32_32x32x16_bf16 v[2:17], v[194:197], v[202:205], v[2:17]
	ds_read_b128 v[162:165], v91
	ds_read_b128 v[166:169], v92 offset:32768
	ds_read_b128 v[182:185], v91 offset:4096
	ds_read_b128 v[186:189], v92 offset:36864
	ds_read_b128 v[190:193], v93
	ds_read_b128 v[194:197], v90 offset:32768
	ds_read_b128 v[198:201], v93 offset:4096
	ds_read_b128 v[202:205], v90 offset:36864
	s_waitcnt lgkmcnt(6)
	v_mfma_f32_32x32x16_bf16 v[50:65], v[162:165], v[166:169], v[50:65]
	s_waitcnt lgkmcnt(4)
	v_mfma_f32_32x32x16_bf16 v[34:49], v[162:165], v[186:189], v[34:49]
	v_mfma_f32_32x32x16_bf16 v[18:33], v[182:185], v[166:169], v[18:33]
	v_mfma_f32_32x32x16_bf16 v[2:17], v[182:185], v[186:189], v[2:17]
	ds_read_b128 v[162:165], v89
	ds_read_b128 v[166:169], v89 offset:4096
	ds_read_b128 v[182:185], v88 offset:32768
	ds_read_b128 v[186:189], v88 offset:36864
	s_waitcnt lgkmcnt(6)
	v_mfma_f32_32x32x16_bf16 v[50:65], v[190:193], v[194:197], v[50:65]
	s_waitcnt lgkmcnt(4)
	v_mfma_f32_32x32x16_bf16 v[34:49], v[190:193], v[202:205], v[34:49]
	v_mfma_f32_32x32x16_bf16 v[18:33], v[198:201], v[194:197], v[18:33]
	v_mfma_f32_32x32x16_bf16 v[2:17], v[198:201], v[202:205], v[2:17]
	ds_read_b128 v[190:193], v87
	ds_read_b128 v[194:197], v87 offset:4096
	ds_read_b128 v[198:201], v86 offset:32768
	ds_read_b128 v[202:205], v86 offset:36864
	s_waitcnt lgkmcnt(0)
	s_barrier
	global_load_dwordx4 v[94:97], v[66:67], off offset:1664
	global_load_dwordx4 v[98:101], v[68:69], off offset:1664
	global_load_dwordx4 v[102:105], v[70:71], off offset:1664
	global_load_dwordx4 v[106:109], v[72:73], off offset:1664
	global_load_dwordx4 v[110:113], v[74:75], off offset:1664
	global_load_dwordx4 v[114:117], v[76:77], off offset:1664
	global_load_dwordx4 v[118:121], v[78:79], off offset:1664
	global_load_dwordx4 v[122:125], v[80:81], off offset:1664
	s_waitcnt vmcnt(15)
	ds_write_b128 v0, v[126:129]
	s_waitcnt vmcnt(14)
	ds_write_b128 v0, v[134:137] offset:32768
	s_waitcnt vmcnt(13)
	ds_write_b128 v0, v[138:141] offset:4096
	s_waitcnt vmcnt(12)
	ds_write_b128 v0, v[142:145] offset:36864
	s_waitcnt vmcnt(11)
	ds_write_b128 v0, v[146:149] offset:8192
	s_waitcnt vmcnt(10)
	ds_write_b128 v0, v[150:153] offset:40960
	s_waitcnt vmcnt(9)
	ds_write_b128 v0, v[154:157] offset:12288
	s_waitcnt vmcnt(8)
	ds_write_b128 v0, v[158:161] offset:45056
	v_mfma_f32_32x32x16_bf16 v[50:65], v[162:165], v[182:185], v[50:65]
	v_mfma_f32_32x32x16_bf16 v[34:49], v[162:165], v[186:189], v[34:49]
	v_mfma_f32_32x32x16_bf16 v[18:33], v[166:169], v[182:185], v[18:33]
	v_mfma_f32_32x32x16_bf16 v[2:17], v[166:169], v[186:189], v[2:17]
	v_mfma_f32_32x32x16_bf16 v[50:65], v[190:193], v[198:201], v[50:65]
	v_mfma_f32_32x32x16_bf16 v[34:49], v[190:193], v[202:205], v[34:49]
	v_mfma_f32_32x32x16_bf16 v[18:33], v[194:197], v[198:201], v[18:33]
	v_mfma_f32_32x32x16_bf16 v[2:17], v[194:197], v[202:205], v[2:17]
	ds_read_b128 v[162:165], v91 offset:16384
	ds_read_b128 v[166:169], v92 offset:49152
	ds_read_b128 v[182:185], v91 offset:20480
	ds_read_b128 v[186:189], v92 offset:53248
	ds_read_b128 v[190:193], v93 offset:16384
	ds_read_b128 v[194:197], v90 offset:49152
	ds_read_b128 v[198:201], v93 offset:20480
	ds_read_b128 v[202:205], v90 offset:53248
	s_waitcnt lgkmcnt(6)
	v_mfma_f32_32x32x16_bf16 v[50:65], v[162:165], v[166:169], v[50:65]
	s_waitcnt lgkmcnt(4)
	v_mfma_f32_32x32x16_bf16 v[34:49], v[162:165], v[186:189], v[34:49]
	v_mfma_f32_32x32x16_bf16 v[18:33], v[182:185], v[166:169], v[18:33]
	v_mfma_f32_32x32x16_bf16 v[2:17], v[182:185], v[186:189], v[2:17]
	ds_read_b128 v[162:165], v89 offset:16384
	ds_read_b128 v[166:169], v89 offset:20480
	ds_read_b128 v[182:185], v88 offset:49152
	ds_read_b128 v[186:189], v88 offset:53248
	s_waitcnt lgkmcnt(6)
	v_mfma_f32_32x32x16_bf16 v[50:65], v[190:193], v[194:197], v[50:65]
	s_waitcnt lgkmcnt(4)
	v_mfma_f32_32x32x16_bf16 v[34:49], v[190:193], v[202:205], v[34:49]
	v_mfma_f32_32x32x16_bf16 v[18:33], v[198:201], v[194:197], v[18:33]
	v_mfma_f32_32x32x16_bf16 v[2:17], v[198:201], v[202:205], v[2:17]
	ds_read_b128 v[190:193], v87 offset:16384
	ds_read_b128 v[194:197], v87 offset:20480
	ds_read_b128 v[198:201], v86 offset:49152
	ds_read_b128 v[202:205], v86 offset:53248
	s_waitcnt lgkmcnt(0)
	s_barrier
	global_load_dwordx4 v[126:129], v[66:67], off offset:1792
	global_load_dwordx4 v[134:137], v[68:69], off offset:1792
	global_load_dwordx4 v[138:141], v[70:71], off offset:1792
	global_load_dwordx4 v[142:145], v[72:73], off offset:1792
	global_load_dwordx4 v[146:149], v[74:75], off offset:1792
	global_load_dwordx4 v[150:153], v[76:77], off offset:1792
	global_load_dwordx4 v[154:157], v[78:79], off offset:1792
	global_load_dwordx4 v[158:161], v[80:81], off offset:1792
	s_waitcnt vmcnt(15)
	ds_write_b128 v0, v[94:97] offset:16384
	s_waitcnt vmcnt(14)
	ds_write_b128 v0, v[98:101] offset:49152
	s_waitcnt vmcnt(13)
	ds_write_b128 v0, v[102:105] offset:20480
	s_waitcnt vmcnt(12)
	ds_write_b128 v0, v[106:109] offset:53248
	s_waitcnt vmcnt(11)
	ds_write_b128 v0, v[110:113] offset:24576
	s_waitcnt vmcnt(10)
	ds_write_b128 v0, v[114:117] offset:57344
	s_waitcnt vmcnt(9)
	ds_write_b128 v0, v[118:121] offset:28672
	s_waitcnt vmcnt(8)
	ds_write_b128 v0, v[122:125] offset:61440
	v_mfma_f32_32x32x16_bf16 v[50:65], v[162:165], v[182:185], v[50:65]
	v_mfma_f32_32x32x16_bf16 v[34:49], v[162:165], v[186:189], v[34:49]
	v_mfma_f32_32x32x16_bf16 v[18:33], v[166:169], v[182:185], v[18:33]
	v_mfma_f32_32x32x16_bf16 v[2:17], v[166:169], v[186:189], v[2:17]
	v_mfma_f32_32x32x16_bf16 v[50:65], v[190:193], v[198:201], v[50:65]
	v_mfma_f32_32x32x16_bf16 v[34:49], v[190:193], v[202:205], v[34:49]
	v_mfma_f32_32x32x16_bf16 v[18:33], v[194:197], v[198:201], v[18:33]
	v_mfma_f32_32x32x16_bf16 v[2:17], v[194:197], v[202:205], v[2:17]
	ds_read_b128 v[162:165], v91
	ds_read_b128 v[166:169], v92 offset:32768
	ds_read_b128 v[182:185], v91 offset:4096
	ds_read_b128 v[186:189], v92 offset:36864
	ds_read_b128 v[190:193], v93
	ds_read_b128 v[194:197], v90 offset:32768
	ds_read_b128 v[198:201], v93 offset:4096
	ds_read_b128 v[202:205], v90 offset:36864
	s_waitcnt lgkmcnt(6)
	v_mfma_f32_32x32x16_bf16 v[50:65], v[162:165], v[166:169], v[50:65]
	s_waitcnt lgkmcnt(4)
	v_mfma_f32_32x32x16_bf16 v[34:49], v[162:165], v[186:189], v[34:49]
	v_mfma_f32_32x32x16_bf16 v[18:33], v[182:185], v[166:169], v[18:33]
	v_mfma_f32_32x32x16_bf16 v[2:17], v[182:185], v[186:189], v[2:17]
	ds_read_b128 v[162:165], v89
	ds_read_b128 v[166:169], v89 offset:4096
	ds_read_b128 v[182:185], v88 offset:32768
	ds_read_b128 v[186:189], v88 offset:36864
	s_waitcnt lgkmcnt(6)
	v_mfma_f32_32x32x16_bf16 v[50:65], v[190:193], v[194:197], v[50:65]
	s_waitcnt lgkmcnt(4)
	v_mfma_f32_32x32x16_bf16 v[34:49], v[190:193], v[202:205], v[34:49]
	v_mfma_f32_32x32x16_bf16 v[18:33], v[198:201], v[194:197], v[18:33]
	v_mfma_f32_32x32x16_bf16 v[2:17], v[198:201], v[202:205], v[2:17]
	ds_read_b128 v[190:193], v87
	ds_read_b128 v[194:197], v87 offset:4096
	ds_read_b128 v[198:201], v86 offset:32768
	ds_read_b128 v[202:205], v86 offset:36864
	s_waitcnt lgkmcnt(0)
	s_barrier
	global_load_dwordx4 v[94:97], v[66:67], off offset:1920
	s_nop 0
	global_load_dwordx4 v[66:69], v[68:69], off offset:1920
	s_nop 0
	global_load_dwordx4 v[98:101], v[70:71], off offset:1920
	s_nop 0
	global_load_dwordx4 v[70:73], v[72:73], off offset:1920
	s_nop 0
	global_load_dwordx4 v[102:105], v[74:75], off offset:1920
	s_nop 0
	global_load_dwordx4 v[74:77], v[76:77], off offset:1920
	s_nop 0
	global_load_dwordx4 v[106:109], v[78:79], off offset:1920
	s_nop 0
	global_load_dwordx4 v[78:81], v[80:81], off offset:1920
	s_waitcnt vmcnt(15)
	ds_write_b128 v0, v[126:129]
	s_waitcnt vmcnt(14)
	ds_write_b128 v0, v[134:137] offset:32768
	s_waitcnt vmcnt(13)
	ds_write_b128 v0, v[138:141] offset:4096
	s_waitcnt vmcnt(12)
	ds_write_b128 v0, v[142:145] offset:36864
	s_waitcnt vmcnt(11)
	ds_write_b128 v0, v[146:149] offset:8192
	s_waitcnt vmcnt(10)
	ds_write_b128 v0, v[150:153] offset:40960
	s_waitcnt vmcnt(9)
	ds_write_b128 v0, v[154:157] offset:12288
	s_waitcnt vmcnt(8)
	ds_write_b128 v0, v[158:161] offset:45056
	v_mfma_f32_32x32x16_bf16 v[50:65], v[162:165], v[182:185], v[50:65]
	v_mfma_f32_32x32x16_bf16 v[34:49], v[162:165], v[186:189], v[34:49]
	v_mfma_f32_32x32x16_bf16 v[18:33], v[166:169], v[182:185], v[18:33]
	v_mfma_f32_32x32x16_bf16 v[2:17], v[166:169], v[186:189], v[2:17]
	ds_read_b128 v[110:113], v91 offset:16384
	ds_read_b128 v[114:117], v91 offset:20480
	ds_read_b128 v[118:121], v92 offset:49152
	ds_read_b128 v[122:125], v92 offset:53248
	ds_read_b128 v[162:165], v93 offset:16384
	ds_read_b128 v[166:169], v93 offset:20480
	ds_read_b128 v[182:185], v90 offset:49152
	ds_read_b128 v[186:189], v90 offset:53248
	v_mfma_f32_32x32x16_bf16 v[50:65], v[190:193], v[198:201], v[50:65]
	v_mfma_f32_32x32x16_bf16 v[34:49], v[190:193], v[202:205], v[34:49]
	v_mfma_f32_32x32x16_bf16 v[18:33], v[194:197], v[198:201], v[18:33]
	v_mfma_f32_32x32x16_bf16 v[2:17], v[194:197], v[202:205], v[2:17]
	s_waitcnt lgkmcnt(5)
	v_mfma_f32_32x32x16_bf16 v[50:65], v[110:113], v[118:121], v[50:65]
	s_waitcnt lgkmcnt(4)
	v_mfma_f32_32x32x16_bf16 v[34:49], v[110:113], v[122:125], v[34:49]
	v_mfma_f32_32x32x16_bf16 v[18:33], v[114:117], v[118:121], v[18:33]
	v_mfma_f32_32x32x16_bf16 v[2:17], v[114:117], v[122:125], v[2:17]
	ds_read_b128 v[110:113], v89 offset:16384
	ds_read_b128 v[114:117], v89 offset:20480
	ds_read_b128 v[118:121], v88 offset:49152
	ds_read_b128 v[122:125], v88 offset:53248
	s_waitcnt lgkmcnt(5)
	v_mfma_f32_32x32x16_bf16 v[50:65], v[162:165], v[182:185], v[50:65]
	s_waitcnt lgkmcnt(4)
	v_mfma_f32_32x32x16_bf16 v[34:49], v[162:165], v[186:189], v[34:49]
	v_mfma_f32_32x32x16_bf16 v[18:33], v[166:169], v[182:185], v[18:33]
	v_mfma_f32_32x32x16_bf16 v[2:17], v[166:169], v[186:189], v[2:17]
	ds_read_b128 v[162:165], v87 offset:16384
	ds_read_b128 v[166:169], v87 offset:20480
	ds_read_b128 v[182:185], v86 offset:49152
	ds_read_b128 v[186:189], v86 offset:53248
	s_waitcnt lgkmcnt(5)
	v_mfma_f32_32x32x16_bf16 v[50:65], v[110:113], v[118:121], v[50:65]
	s_waitcnt lgkmcnt(0)
	s_barrier
	s_waitcnt vmcnt(7)
	ds_write_b128 v0, v[94:97] offset:16384
	s_waitcnt vmcnt(6)
	ds_write_b128 v0, v[66:69] offset:49152
	s_waitcnt vmcnt(5)
	ds_write_b128 v0, v[98:101] offset:20480
	s_waitcnt vmcnt(4)
	ds_write_b128 v0, v[70:73] offset:53248
	s_waitcnt vmcnt(3)
	ds_write_b128 v0, v[102:105] offset:24576
	s_waitcnt vmcnt(2)
	ds_write_b128 v0, v[74:77] offset:57344
	s_waitcnt vmcnt(1)
	ds_write_b128 v0, v[106:109] offset:28672
	s_waitcnt vmcnt(0)
	ds_write_b128 v0, v[78:81] offset:61440
	v_mfma_f32_32x32x16_bf16 v[34:49], v[110:113], v[122:125], v[34:49]
	v_mfma_f32_32x32x16_bf16 v[18:33], v[114:117], v[118:121], v[18:33]
	v_mfma_f32_32x32x16_bf16 v[2:17], v[114:117], v[122:125], v[2:17]
	ds_read_b128 v[110:113], v91
	ds_read_b128 v[114:117], v91 offset:4096
	ds_read_b128 v[118:121], v92 offset:32768
	ds_read_b128 v[122:125], v92 offset:36864
	ds_read_b128 v[126:129], v93
	ds_read_b128 v[134:137], v93 offset:4096
	ds_read_b128 v[138:141], v90 offset:32768
	ds_read_b128 v[142:145], v90 offset:36864
	v_mfma_f32_32x32x16_bf16 v[50:65], v[162:165], v[182:185], v[50:65]
	v_mfma_f32_32x32x16_bf16 v[34:49], v[162:165], v[186:189], v[34:49]
	v_mfma_f32_32x32x16_bf16 v[18:33], v[166:169], v[182:185], v[18:33]
	v_mfma_f32_32x32x16_bf16 v[2:17], v[166:169], v[186:189], v[2:17]
	s_waitcnt lgkmcnt(5)
	v_mfma_f32_32x32x16_bf16 v[50:65], v[110:113], v[118:121], v[50:65]
	s_waitcnt lgkmcnt(4)
	v_mfma_f32_32x32x16_bf16 v[34:49], v[110:113], v[122:125], v[34:49]
	v_mfma_f32_32x32x16_bf16 v[18:33], v[114:117], v[118:121], v[18:33]
	v_mfma_f32_32x32x16_bf16 v[2:17], v[114:117], v[122:125], v[2:17]
	ds_read_b128 v[110:113], v89
	ds_read_b128 v[114:117], v89 offset:4096
	ds_read_b128 v[118:121], v88 offset:32768
	ds_read_b128 v[122:125], v88 offset:36864
	s_waitcnt lgkmcnt(5)
	v_mfma_f32_32x32x16_bf16 v[50:65], v[126:129], v[138:141], v[50:65]
	s_waitcnt lgkmcnt(4)
	v_mfma_f32_32x32x16_bf16 v[34:49], v[126:129], v[142:145], v[34:49]
	v_mfma_f32_32x32x16_bf16 v[18:33], v[134:137], v[138:141], v[18:33]
	v_mfma_f32_32x32x16_bf16 v[2:17], v[134:137], v[142:145], v[2:17]
	ds_read_b128 v[126:129], v87
	ds_read_b128 v[134:137], v87 offset:4096
	ds_read_b128 v[138:141], v86 offset:32768
	ds_read_b128 v[142:145], v86 offset:36864
	s_waitcnt lgkmcnt(0)
	s_barrier
	ds_read_b128 v[66:69], v91 offset:16384
	ds_read_b128 v[70:73], v91 offset:20480
	ds_read_b128 v[74:77], v92 offset:49152
	ds_read_b128 v[78:81], v92 offset:53248
	ds_read_b128 v[94:97], v93 offset:16384
	ds_read_b128 v[98:101], v93 offset:20480
	ds_read_b128 v[102:105], v90 offset:49152
	ds_read_b128 v[90:93], v90 offset:53248
	v_mfma_f32_32x32x16_bf16 v[50:65], v[110:113], v[118:121], v[50:65]
	v_mfma_f32_32x32x16_bf16 v[34:49], v[110:113], v[122:125], v[34:49]
	v_mfma_f32_32x32x16_bf16 v[18:33], v[114:117], v[118:121], v[18:33]
	v_mfma_f32_32x32x16_bf16 v[2:17], v[114:117], v[122:125], v[2:17]
	v_mfma_f32_32x32x16_bf16 v[50:65], v[126:129], v[138:141], v[50:65]
	v_mfma_f32_32x32x16_bf16 v[34:49], v[126:129], v[142:145], v[34:49]
	v_mfma_f32_32x32x16_bf16 v[18:33], v[134:137], v[138:141], v[18:33]
	v_mfma_f32_32x32x16_bf16 v[2:17], v[134:137], v[142:145], v[2:17]
	s_waitcnt lgkmcnt(5)
	v_mfma_f32_32x32x16_bf16 v[50:65], v[66:69], v[74:77], v[50:65]
	s_waitcnt lgkmcnt(4)
	v_mfma_f32_32x32x16_bf16 v[34:49], v[66:69], v[78:81], v[34:49]
	v_mfma_f32_32x32x16_bf16 v[18:33], v[70:73], v[74:77], v[18:33]
	v_mfma_f32_32x32x16_bf16 v[2:17], v[70:73], v[78:81], v[2:17]
	ds_read_b128 v[66:69], v89 offset:16384
	ds_read_b128 v[70:73], v89 offset:20480
	ds_read_b128 v[74:77], v88 offset:49152
	ds_read_b128 v[78:81], v88 offset:53248
	s_waitcnt lgkmcnt(5)
	v_mfma_f32_32x32x16_bf16 v[50:65], v[94:97], v[102:105], v[50:65]
	s_waitcnt lgkmcnt(4)
	v_mfma_f32_32x32x16_bf16 v[34:49], v[94:97], v[90:93], v[34:49]
	v_mfma_f32_32x32x16_bf16 v[18:33], v[98:101], v[102:105], v[18:33]
	v_mfma_f32_32x32x16_bf16 v[2:17], v[98:101], v[90:93], v[2:17]
	ds_read_b128 v[88:91], v87 offset:16384
	ds_read_b128 v[92:95], v87 offset:20480
	ds_read_b128 v[96:99], v86 offset:49152
	ds_read_b128 v[100:103], v86 offset:53248
	s_waitcnt lgkmcnt(5)
	v_mfma_f32_32x32x16_bf16 v[50:65], v[66:69], v[74:77], v[50:65]
	v_lshlrev_b32_e32 v0, 6, v85
	v_lshlrev_b32_e32 v84, 6, v84
	v_subrev_u32_e32 v0, s6, v0
	v_add_u32_e32 v0, s4, v0
	v_ashrrev_i32_e32 v0, 6, v0
	v_lshlrev_b32_e32 v85, 2, v83
	s_waitcnt lgkmcnt(0)
	v_mfma_f32_32x32x16_bf16 v[50:65], v[88:91], v[96:99], v[50:65]
	s_barrier
	v_or_b32_e32 v83, 2, v84
	v_or_b32_e32 v86, 3, v84
	v_or_b32_e32 v87, 8, v85
	s_add_i32 s5, s5, s66
	s_add_i32 s4, s4, s3
	v_mfma_f32_32x32x16_bf16 v[34:49], v[66:69], v[78:81], v[34:49]
	v_lshl_add_u32 v66, s34, 7, v84
	v_ashrrev_i32_e32 v66, 1, v66
	v_and_b32_e32 v66, 0xffffffc0, v66
	v_add_u32_e32 v66, v66, v0
	v_ashrrev_i32_e32 v67, 31, v66
	v_lshlrev_b64 v[66:67], 14, v[66:67]
	v_lshl_add_u64 v[66:67], s[50:51], 0, v[66:67]
	v_lshlrev_b32_e32 v0, 1, v82
	v_lshl_add_u64 v[66:67], v[66:67], 0, v[0:1]
	v_max_f32_e32 v0, v50, v50
	v_max_f32_e32 v0, 0, v0
	v_or_b32_e32 v68, v85, v84
	v_mul_f32_e32 v0, v0, v0
	v_cvt_pk_bf16_f32 v50, v0, s0
	v_lshlrev_b32_e32 v0, 7, v68
	v_and_b32_e32 v0, 0x2200, v0
	v_lshl_add_u64 v[68:69], v[66:67], 0, v[0:1]
	v_or_b32_e32 v82, 1, v84
	global_store_short v[68:69], v50, off
	v_or_b32_e32 v0, v85, v82
	v_max_f32_e32 v50, v51, v51
	v_max_f32_e32 v50, 0, v50
	v_lshlrev_b32_e32 v0, 7, v0
	v_mul_f32_e32 v50, v50, v50
	v_and_b32_e32 v0, 0x2280, v0
	v_mfma_f32_32x32x16_bf16 v[18:33], v[70:73], v[74:77], v[18:33]
	v_max_f32_e32 v52, v52, v52
	v_max_f32_e32 v52, 0, v52
	v_mul_f32_e32 v52, v52, v52
	v_cvt_pk_bf16_f32 v52, v52, s0
	v_max_f32_e32 v54, v54, v54
	v_max_f32_e32 v54, 0, v54
	v_mul_f32_e32 v54, v54, v54
	v_mfma_f32_32x32x16_bf16 v[2:17], v[70:73], v[78:81], v[2:17]
	v_cvt_pk_bf16_f32 v70, v50, s0
	v_lshl_add_u64 v[50:51], v[66:67], 0, v[0:1]
	v_or_b32_e32 v0, v85, v83
	v_lshlrev_b32_e32 v0, 7, v0
	v_and_b32_e32 v0, 0x2300, v0
	global_store_short v[50:51], v70, off
	v_lshl_add_u64 v[70:71], v[66:67], 0, v[0:1]
	global_store_short v[70:71], v52, off
	v_or_b32_e32 v0, v85, v86
	v_max_f32_e32 v52, v53, v53
	v_max_f32_e32 v52, 0, v52
	v_lshlrev_b32_e32 v0, 7, v0
	v_mul_f32_e32 v52, v52, v52
	v_and_b32_e32 v0, 0x2380, v0
	v_cvt_pk_bf16_f32 v72, v52, s0
	v_lshl_add_u64 v[52:53], v[66:67], 0, v[0:1]
	v_or_b32_e32 v0, v87, v84
	v_lshlrev_b32_e32 v0, 7, v0
	v_and_b32_e32 v0, 0x2600, v0
	global_store_short v[52:53], v72, off
	v_cvt_pk_bf16_f32 v54, v54, s0
	v_lshl_add_u64 v[72:73], v[66:67], 0, v[0:1]
	global_store_short v[72:73], v54, off
	v_or_b32_e32 v0, v87, v82
	v_max_f32_e32 v54, v55, v55
	v_max_f32_e32 v54, 0, v54
	v_lshlrev_b32_e32 v0, 7, v0
	v_mul_f32_e32 v54, v54, v54
	v_and_b32_e32 v0, 0x2680, v0
	v_cvt_pk_bf16_f32 v74, v54, s0
	v_lshl_add_u64 v[54:55], v[66:67], 0, v[0:1]
	v_or_b32_e32 v0, v87, v83
	v_max_f32_e32 v56, v56, v56
	v_max_f32_e32 v56, 0, v56
	v_lshlrev_b32_e32 v0, 7, v0
	v_mul_f32_e32 v56, v56, v56
	v_and_b32_e32 v0, 0x2700, v0
	global_store_short v[54:55], v74, off
	v_cvt_pk_bf16_f32 v56, v56, s0
	v_lshl_add_u64 v[74:75], v[66:67], 0, v[0:1]
	global_store_short v[74:75], v56, off
	v_or_b32_e32 v0, v87, v86
	v_max_f32_e32 v56, v57, v57
	v_max_f32_e32 v56, 0, v56
	v_lshlrev_b32_e32 v0, 7, v0
	v_mfma_f32_32x32x16_bf16 v[34:49], v[88:91], v[100:103], v[34:49]
	v_mul_f32_e32 v56, v56, v56
	v_and_b32_e32 v0, 0x2780, v0
	v_or_b32_e32 v88, 16, v85
	v_cvt_pk_bf16_f32 v76, v56, s0
	v_lshl_add_u64 v[56:57], v[66:67], 0, v[0:1]
	v_or_b32_e32 v0, v88, v84
	v_max_f32_e32 v58, v58, v58
	v_max_f32_e32 v58, 0, v58
	v_lshlrev_b32_e32 v0, 7, v0
	v_mul_f32_e32 v58, v58, v58
	v_and_b32_e32 v0, 0x2a00, v0
	global_store_short v[56:57], v76, off
	v_cvt_pk_bf16_f32 v58, v58, s0
	v_lshl_add_u64 v[76:77], v[66:67], 0, v[0:1]
	global_store_short v[76:77], v58, off
	v_or_b32_e32 v0, v88, v82
	v_max_f32_e32 v58, v59, v59
	v_max_f32_e32 v58, 0, v58
	v_lshlrev_b32_e32 v0, 7, v0
	v_mul_f32_e32 v58, v58, v58
	v_and_b32_e32 v0, 0x2a80, v0
	v_cvt_pk_bf16_f32 v78, v58, s0
	v_lshl_add_u64 v[58:59], v[66:67], 0, v[0:1]
	v_or_b32_e32 v0, v88, v83
	v_max_f32_e32 v60, v60, v60
	v_max_f32_e32 v60, 0, v60
	v_lshlrev_b32_e32 v0, 7, v0
	v_mul_f32_e32 v60, v60, v60
	v_and_b32_e32 v0, 0x2b00, v0
	global_store_short v[58:59], v78, off
	v_cvt_pk_bf16_f32 v60, v60, s0
	v_lshl_add_u64 v[78:79], v[66:67], 0, v[0:1]
	global_store_short v[78:79], v60, off
	v_or_b32_e32 v0, v88, v86
	v_max_f32_e32 v60, v61, v61
	v_max_f32_e32 v60, 0, v60
	v_lshlrev_b32_e32 v0, 7, v0
	v_mul_f32_e32 v60, v60, v60
	v_and_b32_e32 v0, 0x2b80, v0
	v_or_b32_e32 v89, 24, v85
	v_cvt_pk_bf16_f32 v80, v60, s0
	v_lshl_add_u64 v[60:61], v[66:67], 0, v[0:1]
	v_or_b32_e32 v0, v89, v84
	v_max_f32_e32 v62, v62, v62
	v_max_f32_e32 v62, 0, v62
	v_lshlrev_b32_e32 v0, 7, v0
	v_mul_f32_e32 v62, v62, v62
	v_and_b32_e32 v0, 0x2e00, v0
	global_store_short v[60:61], v80, off
	v_cvt_pk_bf16_f32 v62, v62, s0
	v_lshl_add_u64 v[80:81], v[66:67], 0, v[0:1]
	global_store_short v[80:81], v62, off
	v_or_b32_e32 v0, v89, v82
	v_max_f32_e32 v62, v63, v63
	v_max_f32_e32 v62, 0, v62
	v_lshlrev_b32_e32 v0, 7, v0
	v_mul_f32_e32 v62, v62, v62
	v_and_b32_e32 v0, 0x2e80, v0
	v_cvt_pk_bf16_f32 v82, v62, s0
	v_lshl_add_u64 v[62:63], v[66:67], 0, v[0:1]
	v_or_b32_e32 v0, v89, v83
	v_max_f32_e32 v64, v64, v64
	v_max_f32_e32 v64, 0, v64
	v_lshlrev_b32_e32 v0, 7, v0
	v_mul_f32_e32 v64, v64, v64
	v_and_b32_e32 v0, 0x2f00, v0
	global_store_short v[62:63], v82, off
	v_cvt_pk_bf16_f32 v64, v64, s0
	v_lshl_add_u64 v[82:83], v[66:67], 0, v[0:1]
	global_store_short v[82:83], v64, off
	v_or_b32_e32 v0, v89, v86
	v_max_f32_e32 v64, v65, v65
	v_max_f32_e32 v64, 0, v64
	v_lshlrev_b32_e32 v0, 7, v0
	v_mul_f32_e32 v64, v64, v64
	v_and_b32_e32 v0, 0x2f80, v0
	v_cvt_pk_bf16_f32 v86, v64, s0
	v_lshl_add_u64 v[64:65], v[66:67], 0, v[0:1]
	v_max_f32_e32 v0, v34, v34
	v_max_f32_e32 v0, 0, v0
	v_mul_f32_e32 v0, v0, v0
	v_cvt_pk_bf16_f32 v0, v0, s0
	global_store_short v[64:65], v86, off
	global_store_short v[68:69], v0, off offset:64
	v_max_f32_e32 v0, v35, v35
	v_max_f32_e32 v0, 0, v0
	v_mul_f32_e32 v0, v0, v0
	v_cvt_pk_bf16_f32 v0, v0, s0
	global_store_short v[50:51], v0, off offset:64
	v_max_f32_e32 v0, v36, v36
	v_max_f32_e32 v0, 0, v0
	v_mul_f32_e32 v0, v0, v0
	v_cvt_pk_bf16_f32 v0, v0, s0
	global_store_short v[70:71], v0, off offset:64
	v_max_f32_e32 v0, v37, v37
	v_max_f32_e32 v0, 0, v0
	v_mul_f32_e32 v0, v0, v0
	v_cvt_pk_bf16_f32 v0, v0, s0
	global_store_short v[52:53], v0, off offset:64
	v_max_f32_e32 v0, v38, v38
	v_max_f32_e32 v0, 0, v0
	v_mul_f32_e32 v0, v0, v0
	v_cvt_pk_bf16_f32 v0, v0, s0
	global_store_short v[72:73], v0, off offset:64
	v_max_f32_e32 v0, v39, v39
	v_max_f32_e32 v0, 0, v0
	v_mul_f32_e32 v0, v0, v0
	v_cvt_pk_bf16_f32 v0, v0, s0
	global_store_short v[54:55], v0, off offset:64
	v_max_f32_e32 v0, v40, v40
	v_max_f32_e32 v0, 0, v0
	v_mul_f32_e32 v0, v0, v0
	v_cvt_pk_bf16_f32 v0, v0, s0
	global_store_short v[74:75], v0, off offset:64
	v_max_f32_e32 v0, v41, v41
	v_max_f32_e32 v0, 0, v0
	v_mul_f32_e32 v0, v0, v0
	v_cvt_pk_bf16_f32 v0, v0, s0
	global_store_short v[56:57], v0, off offset:64
	v_max_f32_e32 v0, v42, v42
	v_max_f32_e32 v0, 0, v0
	v_mul_f32_e32 v0, v0, v0
	v_cvt_pk_bf16_f32 v0, v0, s0
	global_store_short v[76:77], v0, off offset:64
	v_max_f32_e32 v0, v43, v43
	v_max_f32_e32 v0, 0, v0
	v_mul_f32_e32 v0, v0, v0
	v_cvt_pk_bf16_f32 v0, v0, s0
	global_store_short v[58:59], v0, off offset:64
	v_max_f32_e32 v0, v44, v44
	v_max_f32_e32 v0, 0, v0
	v_mul_f32_e32 v0, v0, v0
	v_cvt_pk_bf16_f32 v0, v0, s0
	global_store_short v[78:79], v0, off offset:64
	v_max_f32_e32 v0, v45, v45
	v_max_f32_e32 v0, 0, v0
	v_mul_f32_e32 v0, v0, v0
	v_cvt_pk_bf16_f32 v0, v0, s0
	global_store_short v[60:61], v0, off offset:64
	v_max_f32_e32 v0, v46, v46
	v_max_f32_e32 v0, 0, v0
	v_mul_f32_e32 v0, v0, v0
	v_cvt_pk_bf16_f32 v0, v0, s0
	global_store_short v[80:81], v0, off offset:64
	v_max_f32_e32 v0, v47, v47
	v_max_f32_e32 v0, 0, v0
	v_mul_f32_e32 v0, v0, v0
	v_cvt_pk_bf16_f32 v0, v0, s0
	v_mfma_f32_32x32x16_bf16 v[18:33], v[92:95], v[96:99], v[18:33]
	global_store_short v[62:63], v0, off offset:64
	v_max_f32_e32 v0, v48, v48
	v_max_f32_e32 v0, 0, v0
	v_mul_f32_e32 v0, v0, v0
	v_cvt_pk_bf16_f32 v0, v0, s0
	global_store_short v[82:83], v0, off offset:64
	v_max_f32_e32 v0, v49, v49
	v_max_f32_e32 v0, 0, v0
	v_mul_f32_e32 v0, v0, v0
	v_cvt_pk_bf16_f32 v0, v0, s0
	v_or_b32_e32 v46, 32, v84
	global_store_short v[64:65], v0, off offset:64
	v_or_b32_e32 v0, v85, v46
	v_max_f32_e32 v18, v18, v18
	v_max_f32_e32 v18, 0, v18
	v_lshlrev_b32_e32 v0, 7, v0
	v_mul_f32_e32 v18, v18, v18
	v_and_b32_e32 v0, 0x3200, v0
	v_cvt_pk_bf16_f32 v18, v18, s0
	v_lshl_add_u64 v[34:35], v[66:67], 0, v[0:1]
	v_or_b32_e32 v48, 33, v84
	global_store_short v[34:35], v18, off
	v_or_b32_e32 v0, v85, v48
	v_max_f32_e32 v18, v19, v19
	v_max_f32_e32 v18, 0, v18
	v_lshlrev_b32_e32 v0, 7, v0
	v_mul_f32_e32 v18, v18, v18
	v_and_b32_e32 v0, 0x3280, v0
	v_or_b32_e32 v49, 34, v84
	v_cvt_pk_bf16_f32 v36, v18, s0
	v_lshl_add_u64 v[18:19], v[66:67], 0, v[0:1]
	v_or_b32_e32 v0, v85, v49
	v_max_f32_e32 v20, v20, v20
	v_max_f32_e32 v20, 0, v20
	v_lshlrev_b32_e32 v0, 7, v0
	v_mul_f32_e32 v20, v20, v20
	v_and_b32_e32 v0, 0x3300, v0
	global_store_short v[18:19], v36, off
	v_cvt_pk_bf16_f32 v20, v20, s0
	v_lshl_add_u64 v[36:37], v[66:67], 0, v[0:1]
	v_or_b32_e32 v50, 35, v84
	global_store_short v[36:37], v20, off
	v_or_b32_e32 v0, v85, v50
	v_max_f32_e32 v20, v21, v21
	v_max_f32_e32 v20, 0, v20
	v_lshlrev_b32_e32 v0, 7, v0
	v_mul_f32_e32 v20, v20, v20
	v_and_b32_e32 v0, 0x3380, v0
	v_cvt_pk_bf16_f32 v38, v20, s0
	v_lshl_add_u64 v[20:21], v[66:67], 0, v[0:1]
	v_or_b32_e32 v0, v87, v46
	v_max_f32_e32 v22, v22, v22
	v_max_f32_e32 v22, 0, v22
	v_lshlrev_b32_e32 v0, 7, v0
	v_mul_f32_e32 v22, v22, v22
	v_and_b32_e32 v0, 0x3600, v0
	global_store_short v[20:21], v38, off
	v_cvt_pk_bf16_f32 v22, v22, s0
	v_lshl_add_u64 v[38:39], v[66:67], 0, v[0:1]
	global_store_short v[38:39], v22, off
	v_or_b32_e32 v0, v87, v48
	v_max_f32_e32 v22, v23, v23
	v_max_f32_e32 v22, 0, v22
	v_lshlrev_b32_e32 v0, 7, v0
	v_mul_f32_e32 v22, v22, v22
	v_and_b32_e32 v0, 0x3680, v0
	v_cvt_pk_bf16_f32 v40, v22, s0
	v_lshl_add_u64 v[22:23], v[66:67], 0, v[0:1]
	v_or_b32_e32 v0, v87, v49
	v_max_f32_e32 v24, v24, v24
	v_max_f32_e32 v24, 0, v24
	v_lshlrev_b32_e32 v0, 7, v0
	v_mul_f32_e32 v24, v24, v24
	v_and_b32_e32 v0, 0x3700, v0
	global_store_short v[22:23], v40, off
	v_cvt_pk_bf16_f32 v24, v24, s0
	v_lshl_add_u64 v[40:41], v[66:67], 0, v[0:1]
	global_store_short v[40:41], v24, off
	v_or_b32_e32 v0, v87, v50
	v_max_f32_e32 v24, v25, v25
	v_max_f32_e32 v24, 0, v24
	v_lshlrev_b32_e32 v0, 7, v0
	v_mul_f32_e32 v24, v24, v24
	v_and_b32_e32 v0, 0x3780, v0
	v_cvt_pk_bf16_f32 v42, v24, s0
	v_lshl_add_u64 v[24:25], v[66:67], 0, v[0:1]
	v_or_b32_e32 v0, v88, v46
	v_max_f32_e32 v26, v26, v26
	v_max_f32_e32 v26, 0, v26
	v_lshlrev_b32_e32 v0, 7, v0
	v_mul_f32_e32 v26, v26, v26
	v_and_b32_e32 v0, 0x3a00, v0
	global_store_short v[24:25], v42, off
	v_cvt_pk_bf16_f32 v26, v26, s0
	v_lshl_add_u64 v[42:43], v[66:67], 0, v[0:1]
	global_store_short v[42:43], v26, off
	v_or_b32_e32 v0, v88, v48
	v_max_f32_e32 v26, v27, v27
	v_max_f32_e32 v26, 0, v26
	v_lshlrev_b32_e32 v0, 7, v0
	v_mul_f32_e32 v26, v26, v26
	v_and_b32_e32 v0, 0x3a80, v0
	v_cvt_pk_bf16_f32 v44, v26, s0
	v_lshl_add_u64 v[26:27], v[66:67], 0, v[0:1]
	v_or_b32_e32 v0, v88, v49
	v_max_f32_e32 v28, v28, v28
	v_max_f32_e32 v28, 0, v28
	v_lshlrev_b32_e32 v0, 7, v0
	v_mul_f32_e32 v28, v28, v28
	v_and_b32_e32 v0, 0x3b00, v0
	global_store_short v[26:27], v44, off
	v_cvt_pk_bf16_f32 v28, v28, s0
	v_lshl_add_u64 v[44:45], v[66:67], 0, v[0:1]
	global_store_short v[44:45], v28, off
	v_or_b32_e32 v0, v88, v50
	v_max_f32_e32 v28, v29, v29
	v_max_f32_e32 v28, 0, v28
	v_lshlrev_b32_e32 v0, 7, v0
	v_mul_f32_e32 v28, v28, v28
	v_and_b32_e32 v0, 0x3b80, v0
	v_cvt_pk_bf16_f32 v47, v28, s0
	v_lshl_add_u64 v[28:29], v[66:67], 0, v[0:1]
	v_or_b32_e32 v0, v89, v46
	v_max_f32_e32 v30, v30, v30
	v_max_f32_e32 v30, 0, v30
	v_lshlrev_b32_e32 v0, 7, v0
	v_mul_f32_e32 v30, v30, v30
	v_and_b32_e32 v0, 0x3e00, v0
	global_store_short v[28:29], v47, off
	v_cvt_pk_bf16_f32 v30, v30, s0
	v_lshl_add_u64 v[46:47], v[66:67], 0, v[0:1]
	global_store_short v[46:47], v30, off
	v_or_b32_e32 v0, v89, v48
	v_max_f32_e32 v30, v31, v31
	v_max_f32_e32 v30, 0, v30
	v_lshlrev_b32_e32 v0, 7, v0
	v_mfma_f32_32x32x16_bf16 v[2:17], v[92:95], v[100:103], v[2:17]
	v_mul_f32_e32 v30, v30, v30
	v_and_b32_e32 v0, 0x3e80, v0
	v_cvt_pk_bf16_f32 v48, v30, s0
	v_lshl_add_u64 v[30:31], v[66:67], 0, v[0:1]
	v_or_b32_e32 v0, v89, v49
	v_max_f32_e32 v32, v32, v32
	v_max_f32_e32 v32, 0, v32
	v_lshlrev_b32_e32 v0, 7, v0
	v_mul_f32_e32 v32, v32, v32
	v_and_b32_e32 v0, 0x3f00, v0
	global_store_short v[30:31], v48, off
	v_cvt_pk_bf16_f32 v32, v32, s0
	v_lshl_add_u64 v[48:49], v[66:67], 0, v[0:1]
	global_store_short v[48:49], v32, off
	v_or_b32_e32 v0, v89, v50
	v_max_f32_e32 v32, v33, v33
	v_max_f32_e32 v32, 0, v32
	v_lshlrev_b32_e32 v0, 7, v0
	v_mul_f32_e32 v32, v32, v32
	v_and_b32_e32 v0, 0x3f80, v0
	v_cvt_pk_bf16_f32 v50, v32, s0
	v_lshl_add_u64 v[32:33], v[66:67], 0, v[0:1]
	v_max_f32_e32 v0, v2, v2
	v_max_f32_e32 v0, 0, v0
	v_mul_f32_e32 v0, v0, v0
	v_cvt_pk_bf16_f32 v0, v0, s0
	global_store_short v[32:33], v50, off
	global_store_short v[34:35], v0, off offset:64
	v_max_f32_e32 v0, v3, v3
	v_max_f32_e32 v0, 0, v0
	v_mul_f32_e32 v0, v0, v0
	v_cvt_pk_bf16_f32 v0, v0, s0
	global_store_short v[18:19], v0, off offset:64
	v_max_f32_e32 v0, v4, v4
	v_max_f32_e32 v0, 0, v0
	v_mul_f32_e32 v0, v0, v0
	v_cvt_pk_bf16_f32 v0, v0, s0
	global_store_short v[36:37], v0, off offset:64
	v_max_f32_e32 v0, v5, v5
	v_max_f32_e32 v0, 0, v0
	v_mul_f32_e32 v0, v0, v0
	v_cvt_pk_bf16_f32 v0, v0, s0
	global_store_short v[20:21], v0, off offset:64
	v_max_f32_e32 v0, v6, v6
	v_max_f32_e32 v0, 0, v0
	v_mul_f32_e32 v0, v0, v0
	v_cvt_pk_bf16_f32 v0, v0, s0
	global_store_short v[38:39], v0, off offset:64
	v_max_f32_e32 v0, v7, v7
	v_max_f32_e32 v0, 0, v0
	v_mul_f32_e32 v0, v0, v0
	v_cvt_pk_bf16_f32 v0, v0, s0
	global_store_short v[22:23], v0, off offset:64
	v_max_f32_e32 v0, v8, v8
	v_max_f32_e32 v0, 0, v0
	v_mul_f32_e32 v0, v0, v0
	v_cvt_pk_bf16_f32 v0, v0, s0
	global_store_short v[40:41], v0, off offset:64
	v_max_f32_e32 v0, v9, v9
	v_max_f32_e32 v0, 0, v0
	v_mul_f32_e32 v0, v0, v0
	v_cvt_pk_bf16_f32 v0, v0, s0
	global_store_short v[24:25], v0, off offset:64
	v_max_f32_e32 v0, v10, v10
	v_max_f32_e32 v0, 0, v0
	v_mul_f32_e32 v0, v0, v0
	v_cvt_pk_bf16_f32 v0, v0, s0
	global_store_short v[42:43], v0, off offset:64
	v_max_f32_e32 v0, v11, v11
	v_max_f32_e32 v0, 0, v0
	v_mul_f32_e32 v0, v0, v0
	v_cvt_pk_bf16_f32 v0, v0, s0
	global_store_short v[26:27], v0, off offset:64
	v_max_f32_e32 v0, v12, v12
	v_max_f32_e32 v0, 0, v0
	v_mul_f32_e32 v0, v0, v0
	v_cvt_pk_bf16_f32 v0, v0, s0
	global_store_short v[44:45], v0, off offset:64
	v_max_f32_e32 v0, v13, v13
	v_max_f32_e32 v0, 0, v0
	v_mul_f32_e32 v0, v0, v0
	v_cvt_pk_bf16_f32 v0, v0, s0
	global_store_short v[28:29], v0, off offset:64
	v_max_f32_e32 v0, v14, v14
	v_max_f32_e32 v0, 0, v0
	v_mul_f32_e32 v0, v0, v0
	v_cvt_pk_bf16_f32 v0, v0, s0
	global_store_short v[46:47], v0, off offset:64
	v_max_f32_e32 v0, v15, v15
	v_max_f32_e32 v0, 0, v0
	v_mul_f32_e32 v0, v0, v0
	v_cvt_pk_bf16_f32 v0, v0, s0
	global_store_short v[30:31], v0, off offset:64
	v_max_f32_e32 v0, v16, v16
	v_max_f32_e32 v0, 0, v0
	v_mul_f32_e32 v0, v0, v0
	v_cvt_pk_bf16_f32 v0, v0, s0
	global_store_short v[48:49], v0, off offset:64
	v_max_f32_e32 v0, v17, v17
	v_max_f32_e32 v0, 0, v0
	v_mul_f32_e32 v0, v0, v0
	v_cvt_pk_bf16_f32 v0, v0, s0
	s_cmp_lt_i32 s5, s2
	global_store_short v[32:33], v0, off offset:64
	s_cbranch_scc1 .LBB0_1298
	s_mov_b32 s10, 0x8000
	s_mov_b32 s34, 0xa000
	s_mov_b32 s35, 0x2b000
	s_mov_b64 s[42:43], s[8:9]

.LBB0_1363:
	v_readlane_b32 s0, v207, 2
	s_movk_i32 s61, 0x4000
	s_cmp_lt_u32 s6, s0
	s_cbranch_scc0 .LBB0_1365
	v_mov_b32_e32 v38, v133
	v_readlane_b32 s2, v208, 4
	v_ashrrev_i32_e32 v34, 3, v38
	v_ashrrev_i32_e32 v35, 31, v34
	v_lshlrev_b64 v[2:3], 7, v[34:35]
	v_readlane_b32 s3, v208, 5
	v_lshlrev_b32_e32 v0, 4, v38
	v_and_b32_e32 v0, 0x70, v0
	v_lshl_add_u64 v[2:3], s[2:3], 0, v[2:3]
	v_readlane_b32 s2, v208, 9
	s_lshl_b32 s0, s60, 1
	v_readlane_b32 s1, v208, 6
	v_lshl_add_u64 v[134:135], v[2:3], 0, v[0:1]
	v_add_u32_e32 v2, s2, v34
	s_add_u32 s0, s1, s0
	v_readlane_b32 s1, v208, 7
	v_ashrrev_i32_e32 v3, 31, v2
	s_addc_u32 s1, s1, 0
	v_lshlrev_b64 v[2:3], 13, v[2:3]
	v_lshl_add_u64 v[2:3], s[0:1], 0, v[2:3]
	v_add_co_u32_e32 v18, vcc, s53, v134
	v_lshl_add_u64 v[136:137], v[2:3], 0, v[0:1]
	s_nop 0
	v_addc_co_u32_e32 v19, vcc, 0, v135, vcc
	s_mov_b32 s0, 0x40000
	v_add_co_u32_e32 v140, vcc, s0, v136
	s_mov_b32 s0, 0x80000
	s_nop 0
	v_addc_co_u32_e32 v141, vcc, 0, v137, vcc
	v_add_co_u32_e32 v138, vcc, s0, v136
	s_movk_i32 s6, 0x4000
	s_nop 0
	v_addc_co_u32_e32 v139, vcc, 0, v137, vcc
	v_add_co_u32_e32 v36, vcc, s6, v134
	s_mov_b32 s0, 0xc0000
	s_nop 0
	v_addc_co_u32_e32 v37, vcc, 0, v135, vcc
	global_load_dwordx4 v[2:5], v[134:135], off
	global_load_dwordx4 v[6:9], v[136:137], off
	global_load_dwordx4 v[10:13], v[18:19], off offset:-4096
	global_load_dwordx4 v[14:17], v[140:141], off
	s_nop 0
	global_load_dwordx4 v[18:21], v[18:19], off
	v_add_co_u32_e32 v142, vcc, s0, v136
	global_load_dwordx4 v[22:25], v[138:139], off
	s_nop 0
	v_addc_co_u32_e32 v143, vcc, 0, v137, vcc
	global_load_dwordx4 v[26:29], v[36:37], off offset:-4096
	global_load_dwordx4 v[30:33], v[142:143], off
	global_load_dwordx4 v[90:93], v[36:37], off
	global_load_dwordx4 v[94:97], v[136:137], off offset:128
	s_movk_i32 s5, 0x6000
	v_add_co_u32_e32 v36, vcc, s5, v134
	v_lshlrev_b32_e32 v0, 7, v34
	v_lshrrev_b32_e32 v34, 1, v34
	v_addc_co_u32_e32 v37, vcc, 0, v135, vcc
	v_xor_b32_e32 v34, v34, v38
	global_load_dwordx4 v[114:117], v[36:37], off offset:-4096
	global_load_dwordx4 v[118:121], v[140:141], off offset:128
	global_load_dwordx4 v[98:101], v[36:37], off
	global_load_dwordx4 v[102:105], v[138:139], off offset:128
	v_add_co_u32_e32 v36, vcc, s10, v134
	v_lshlrev_b32_e32 v34, 4, v34
	s_nop 0
	v_addc_co_u32_e32 v37, vcc, 0, v135, vcc
	v_and_or_b32 v0, v34, s59, v0
	global_load_dwordx4 v[106:109], v[36:37], off offset:-4096
	global_load_dwordx4 v[110:113], v[142:143], off offset:128
	s_mov_b32 s0, 0xc000
	v_and_b32_e32 v146, 31, v38
	v_bfe_u32 v145, v38, 5, 1
	v_ashrrev_i32_e32 v144, 7, v38
	v_bfe_u32 v147, v38, 6, 1
	s_waitcnt vmcnt(15)
	ds_write_b128 v0, v[2:5]
	s_waitcnt vmcnt(14)
	ds_write_b128 v0, v[6:9] offset:32768
	s_waitcnt vmcnt(13)
	ds_write_b128 v0, v[10:13] offset:4096
	s_waitcnt vmcnt(12)
	ds_write_b128 v0, v[14:17] offset:36864
	s_waitcnt vmcnt(11)
	ds_write_b128 v0, v[18:21] offset:8192
	s_waitcnt vmcnt(10)
	ds_write_b128 v0, v[22:25] offset:40960
	s_waitcnt vmcnt(9)
	ds_write_b128 v0, v[26:29] offset:12288
	s_waitcnt vmcnt(8)
	ds_write_b128 v0, v[30:33] offset:45056
	v_add_co_u32_e32 v2, vcc, s34, v134
	s_waitcnt lgkmcnt(0)
	s_nop 0
	v_addc_co_u32_e32 v3, vcc, 0, v135, vcc
	s_barrier
	global_load_dwordx4 v[66:69], v[36:37], off
	global_load_dwordx4 v[70:73], v[136:137], off offset:256
	global_load_dwordx4 v[82:85], v[2:3], off offset:-4096
	global_load_dwordx4 v[86:89], v[140:141], off offset:256
	global_load_dwordx4 v[74:77], v[2:3], off
	global_load_dwordx4 v[78:81], v[138:139], off offset:256
	v_add_co_u32_e32 v168, vcc, s0, v134
	v_lshrrev_b32_e32 v4, 1, v38
	s_nop 0
	v_addc_co_u32_e32 v169, vcc, 0, v135, vcc
	global_load_dwordx4 v[122:125], v[168:169], off offset:-4096
	global_load_dwordx4 v[126:129], v[142:143], off offset:256
	v_lshlrev_b32_e32 v2, 7, v146
	v_bitop3_b32 v4, v4, v145, 7 bitop3:0x6c
	v_lshl_or_b32 v3, v144, 13, v2
	v_bfe_u32 v5, v38, 1, 3
	v_lshlrev_b32_e32 v4, 4, v4
	v_lshl_or_b32 v2, v147, 13, v2
	v_or_b32_e32 v153, v3, v4
	v_or_b32_e32 v154, v2, v4
	v_bitop3_b32 v4, v145, v5, 2 bitop3:0x36
	v_lshlrev_b32_e32 v4, 4, v4
	v_or_b32_e32 v155, v3, v4
	v_or_b32_e32 v152, v2, v4
	v_bitop3_b32 v4, v145, v5, 4 bitop3:0x36
	v_lshlrev_b32_e32 v4, 4, v4
	v_or_b32_e32 v151, v3, v4
	v_or_b32_e32 v150, v2, v4
	v_bitop3_b32 v4, v145, v5, 6 bitop3:0x36
	v_lshlrev_b32_e32 v4, 4, v4
	v_or_b32_e32 v149, v3, v4
	v_or_b32_e32 v148, v2, v4
	ds_read_b128 v[2:5], v153
	ds_read_b128 v[6:9], v154 offset:32768
	ds_read_b128 v[10:13], v153 offset:4096
	ds_read_b128 v[14:17], v154 offset:36864
	ds_read_b128 v[156:159], v155
	ds_read_b128 v[160:163], v152 offset:32768
	ds_read_b128 v[164:167], v155 offset:4096
	ds_read_b128 v[182:185], v152 offset:36864
	s_waitcnt lgkmcnt(6)
	v_mfma_f32_32x32x16_bf16 v[50:65], v[2:5], v[6:9], 0
	s_waitcnt lgkmcnt(4)
	v_mfma_f32_32x32x16_bf16 v[34:49], v[2:5], v[14:17], 0
	v_mfma_f32_32x32x16_bf16 v[18:33], v[10:13], v[6:9], 0
	v_mfma_f32_32x32x16_bf16 v[2:17], v[10:13], v[14:17], 0
	ds_read_b128 v[186:189], v151
	ds_read_b128 v[190:193], v151 offset:4096
	ds_read_b128 v[194:197], v150 offset:32768
	ds_read_b128 v[198:201], v150 offset:36864
	s_waitcnt lgkmcnt(6)
	v_mfma_f32_32x32x16_bf16 v[50:65], v[156:159], v[160:163], v[50:65]
	s_waitcnt lgkmcnt(4)
	v_mfma_f32_32x32x16_bf16 v[34:49], v[156:159], v[182:185], v[34:49]
	v_mfma_f32_32x32x16_bf16 v[18:33], v[164:167], v[160:163], v[18:33]
	v_mfma_f32_32x32x16_bf16 v[2:17], v[164:167], v[182:185], v[2:17]
	ds_read_b128 v[156:159], v149
	ds_read_b128 v[160:163], v149 offset:4096
	ds_read_b128 v[164:167], v148 offset:32768
	ds_read_b128 v[182:185], v148 offset:36864
	s_mov_b32 s0, 0xe000
	s_waitcnt vmcnt(15)
	ds_write_b128 v0, v[90:93] offset:16384
	s_waitcnt vmcnt(14)
	ds_write_b128 v0, v[94:97] offset:49152
	s_waitcnt vmcnt(13)
	ds_write_b128 v0, v[114:117] offset:20480
	s_waitcnt vmcnt(12)
	ds_write_b128 v0, v[118:121] offset:53248
	s_waitcnt vmcnt(11)
	ds_write_b128 v0, v[98:101] offset:24576
	s_waitcnt vmcnt(10)
	ds_write_b128 v0, v[102:105] offset:57344
	s_waitcnt vmcnt(9)
	ds_write_b128 v0, v[106:109] offset:28672
	s_waitcnt vmcnt(8)
	ds_write_b128 v0, v[110:113] offset:61440
	v_add_co_u32_e32 v106, vcc, s0, v134
	s_waitcnt lgkmcnt(0)
	s_nop 0
	v_addc_co_u32_e32 v107, vcc, 0, v135, vcc
	s_barrier
	global_load_dwordx4 v[90:93], v[168:169], off
	global_load_dwordx4 v[94:97], v[136:137], off offset:384
	global_load_dwordx4 v[98:101], v[106:107], off offset:-4096
	global_load_dwordx4 v[102:105], v[140:141], off offset:384
	s_nop 0
	global_load_dwordx4 v[106:109], v[106:107], off
	s_nop 0
	global_load_dwordx4 v[110:113], v[138:139], off offset:384
	v_add_co_u32_e32 v168, vcc, s56, v134
	v_mfma_f32_32x32x16_bf16 v[50:65], v[186:189], v[194:197], v[50:65]
	s_nop 0
	v_addc_co_u32_e32 v169, vcc, 0, v135, vcc
	global_load_dwordx4 v[114:117], v[168:169], off offset:-4096
	global_load_dwordx4 v[118:121], v[142:143], off offset:384
	v_mfma_f32_32x32x16_bf16 v[34:49], v[186:189], v[198:201], v[34:49]
	v_mfma_f32_32x32x16_bf16 v[18:33], v[190:193], v[194:197], v[18:33]
	v_mfma_f32_32x32x16_bf16 v[2:17], v[190:193], v[198:201], v[2:17]
	v_mfma_f32_32x32x16_bf16 v[50:65], v[156:159], v[164:167], v[50:65]
	v_mfma_f32_32x32x16_bf16 v[34:49], v[156:159], v[182:185], v[34:49]
	v_mfma_f32_32x32x16_bf16 v[18:33], v[160:163], v[164:167], v[18:33]
	v_mfma_f32_32x32x16_bf16 v[2:17], v[160:163], v[182:185], v[2:17]
	ds_read_b128 v[156:159], v153 offset:16384
	ds_read_b128 v[160:163], v154 offset:49152
	ds_read_b128 v[164:167], v153 offset:20480
	ds_read_b128 v[182:185], v154 offset:53248
	ds_read_b128 v[186:189], v155 offset:16384
	ds_read_b128 v[190:193], v152 offset:49152
	ds_read_b128 v[194:197], v155 offset:20480
	ds_read_b128 v[198:201], v152 offset:53248
	s_waitcnt lgkmcnt(6)
	v_mfma_f32_32x32x16_bf16 v[50:65], v[156:159], v[160:163], v[50:65]
	s_waitcnt lgkmcnt(4)
	v_mfma_f32_32x32x16_bf16 v[34:49], v[156:159], v[182:185], v[34:49]
	v_mfma_f32_32x32x16_bf16 v[18:33], v[164:167], v[160:163], v[18:33]
	v_mfma_f32_32x32x16_bf16 v[2:17], v[164:167], v[182:185], v[2:17]
	ds_read_b128 v[156:159], v151 offset:16384
	ds_read_b128 v[160:163], v151 offset:20480
	ds_read_b128 v[164:167], v150 offset:49152
	ds_read_b128 v[182:185], v150 offset:53248
	s_waitcnt lgkmcnt(6)
	v_mfma_f32_32x32x16_bf16 v[50:65], v[186:189], v[190:193], v[50:65]
	s_waitcnt lgkmcnt(4)
	v_mfma_f32_32x32x16_bf16 v[34:49], v[186:189], v[198:201], v[34:49]
	v_mfma_f32_32x32x16_bf16 v[18:33], v[194:197], v[190:193], v[18:33]
	v_mfma_f32_32x32x16_bf16 v[2:17], v[194:197], v[198:201], v[2:17]
	ds_read_b128 v[186:189], v149 offset:16384
	ds_read_b128 v[190:193], v149 offset:20480
	ds_read_b128 v[194:197], v148 offset:49152
	ds_read_b128 v[198:201], v148 offset:53248
	s_mov_b32 s0, 0x12000
	s_waitcnt vmcnt(15)
	ds_write_b128 v0, v[66:69]
	s_waitcnt vmcnt(14)
	ds_write_b128 v0, v[70:73] offset:32768
	s_waitcnt vmcnt(13)
	ds_write_b128 v0, v[82:85] offset:4096
	s_waitcnt vmcnt(12)
	ds_write_b128 v0, v[86:89] offset:36864
	s_waitcnt vmcnt(11)
	ds_write_b128 v0, v[74:77] offset:8192
	s_waitcnt vmcnt(10)
	ds_write_b128 v0, v[78:81] offset:40960
	s_waitcnt vmcnt(9)
	ds_write_b128 v0, v[122:125] offset:12288
	s_waitcnt vmcnt(8)
	ds_write_b128 v0, v[126:129] offset:45056
	v_add_co_u32_e32 v82, vcc, s0, v134
	s_mov_b32 s0, 0x14000
	s_nop 0
	v_addc_co_u32_e32 v83, vcc, 0, v135, vcc
	s_waitcnt lgkmcnt(0)
	s_barrier
	global_load_dwordx4 v[66:69], v[168:169], off
	global_load_dwordx4 v[70:73], v[136:137], off offset:512
	global_load_dwordx4 v[74:77], v[82:83], off offset:-4096
	global_load_dwordx4 v[78:81], v[140:141], off offset:512
	s_nop 0
	global_load_dwordx4 v[82:85], v[82:83], off
	s_nop 0
	global_load_dwordx4 v[86:89], v[138:139], off offset:512
	v_add_co_u32_e32 v168, vcc, s0, v134
	v_mfma_f32_32x32x16_bf16 v[50:65], v[156:159], v[164:167], v[50:65]
	s_nop 0
	v_addc_co_u32_e32 v169, vcc, 0, v135, vcc
	global_load_dwordx4 v[122:125], v[168:169], off offset:-4096
	global_load_dwordx4 v[126:129], v[142:143], off offset:512
	v_mfma_f32_32x32x16_bf16 v[34:49], v[156:159], v[182:185], v[34:49]
	v_mfma_f32_32x32x16_bf16 v[18:33], v[160:163], v[164:167], v[18:33]
	v_mfma_f32_32x32x16_bf16 v[2:17], v[160:163], v[182:185], v[2:17]
	v_mfma_f32_32x32x16_bf16 v[50:65], v[186:189], v[194:197], v[50:65]
	v_mfma_f32_32x32x16_bf16 v[34:49], v[186:189], v[198:201], v[34:49]
	v_mfma_f32_32x32x16_bf16 v[18:33], v[190:193], v[194:197], v[18:33]
	v_mfma_f32_32x32x16_bf16 v[2:17], v[190:193], v[198:201], v[2:17]
	ds_read_b128 v[156:159], v153
	ds_read_b128 v[160:163], v154 offset:32768
	ds_read_b128 v[164:167], v153 offset:4096
	ds_read_b128 v[182:185], v154 offset:36864
	ds_read_b128 v[186:189], v155
	ds_read_b128 v[190:193], v152 offset:32768
	ds_read_b128 v[194:197], v155 offset:4096
	ds_read_b128 v[198:201], v152 offset:36864
	s_waitcnt lgkmcnt(6)
	v_mfma_f32_32x32x16_bf16 v[50:65], v[156:159], v[160:163], v[50:65]
	s_waitcnt lgkmcnt(4)
	v_mfma_f32_32x32x16_bf16 v[34:49], v[156:159], v[182:185], v[34:49]
	v_mfma_f32_32x32x16_bf16 v[18:33], v[164:167], v[160:163], v[18:33]
	v_mfma_f32_32x32x16_bf16 v[2:17], v[164:167], v[182:185], v[2:17]
	ds_read_b128 v[156:159], v151
	ds_read_b128 v[160:163], v151 offset:4096
	ds_read_b128 v[164:167], v150 offset:32768
	ds_read_b128 v[182:185], v150 offset:36864
	s_waitcnt lgkmcnt(6)
	v_mfma_f32_32x32x16_bf16 v[50:65], v[186:189], v[190:193], v[50:65]
	s_waitcnt lgkmcnt(4)
	v_mfma_f32_32x32x16_bf16 v[34:49], v[186:189], v[198:201], v[34:49]
	v_mfma_f32_32x32x16_bf16 v[18:33], v[194:197], v[190:193], v[18:33]
	v_mfma_f32_32x32x16_bf16 v[2:17], v[194:197], v[198:201], v[2:17]
	ds_read_b128 v[186:189], v149
	ds_read_b128 v[190:193], v149 offset:4096
	ds_read_b128 v[194:197], v148 offset:32768
	ds_read_b128 v[198:201], v148 offset:36864
	s_mov_b32 s0, 0x16000
	s_waitcnt vmcnt(15)
	ds_write_b128 v0, v[90:93] offset:16384
	s_waitcnt vmcnt(14)
	ds_write_b128 v0, v[94:97] offset:49152
	s_waitcnt vmcnt(13)
	ds_write_b128 v0, v[98:101] offset:20480
	s_waitcnt vmcnt(12)
	ds_write_b128 v0, v[102:105] offset:53248
	s_waitcnt vmcnt(11)
	ds_write_b128 v0, v[106:109] offset:24576
	s_waitcnt vmcnt(10)
	ds_write_b128 v0, v[110:113] offset:57344
	s_waitcnt vmcnt(9)
	ds_write_b128 v0, v[114:117] offset:28672
	s_waitcnt vmcnt(8)
	ds_write_b128 v0, v[118:121] offset:61440
	v_add_co_u32_e32 v106, vcc, s0, v134
	s_mov_b32 s0, 0x18000
	s_nop 0
	v_addc_co_u32_e32 v107, vcc, 0, v135, vcc
	s_waitcnt lgkmcnt(0)
	s_barrier
	global_load_dwordx4 v[90:93], v[168:169], off
	global_load_dwordx4 v[94:97], v[136:137], off offset:640
	global_load_dwordx4 v[98:101], v[106:107], off offset:-4096
	global_load_dwordx4 v[102:105], v[140:141], off offset:640
	s_nop 0
	global_load_dwordx4 v[106:109], v[106:107], off
	s_nop 0
	global_load_dwordx4 v[110:113], v[138:139], off offset:640
	v_add_co_u32_e32 v168, vcc, s0, v134
	v_mfma_f32_32x32x16_bf16 v[50:65], v[156:159], v[164:167], v[50:65]
	s_nop 0
	v_addc_co_u32_e32 v169, vcc, 0, v135, vcc
	global_load_dwordx4 v[114:117], v[168:169], off offset:-4096
	global_load_dwordx4 v[118:121], v[142:143], off offset:640
	v_mfma_f32_32x32x16_bf16 v[34:49], v[156:159], v[182:185], v[34:49]
	v_mfma_f32_32x32x16_bf16 v[18:33], v[160:163], v[164:167], v[18:33]
	v_mfma_f32_32x32x16_bf16 v[2:17], v[160:163], v[182:185], v[2:17]
	v_mfma_f32_32x32x16_bf16 v[50:65], v[186:189], v[194:197], v[50:65]
	v_mfma_f32_32x32x16_bf16 v[34:49], v[186:189], v[198:201], v[34:49]
	v_mfma_f32_32x32x16_bf16 v[18:33], v[190:193], v[194:197], v[18:33]
	v_mfma_f32_32x32x16_bf16 v[2:17], v[190:193], v[198:201], v[2:17]
	ds_read_b128 v[156:159], v153 offset:16384
	ds_read_b128 v[160:163], v154 offset:49152
	ds_read_b128 v[164:167], v153 offset:20480
	ds_read_b128 v[182:185], v154 offset:53248
	ds_read_b128 v[186:189], v155 offset:16384
	ds_read_b128 v[190:193], v152 offset:49152
	ds_read_b128 v[194:197], v155 offset:20480
	ds_read_b128 v[198:201], v152 offset:53248
	s_waitcnt lgkmcnt(6)
	v_mfma_f32_32x32x16_bf16 v[50:65], v[156:159], v[160:163], v[50:65]
	s_waitcnt lgkmcnt(4)
	v_mfma_f32_32x32x16_bf16 v[34:49], v[156:159], v[182:185], v[34:49]
	v_mfma_f32_32x32x16_bf16 v[18:33], v[164:167], v[160:163], v[18:33]
	v_mfma_f32_32x32x16_bf16 v[2:17], v[164:167], v[182:185], v[2:17]
	ds_read_b128 v[156:159], v151 offset:16384
	ds_read_b128 v[160:163], v151 offset:20480
	ds_read_b128 v[164:167], v150 offset:49152
	ds_read_b128 v[182:185], v150 offset:53248
	s_waitcnt lgkmcnt(6)
	v_mfma_f32_32x32x16_bf16 v[50:65], v[186:189], v[190:193], v[50:65]
	s_waitcnt lgkmcnt(4)
	v_mfma_f32_32x32x16_bf16 v[34:49], v[186:189], v[198:201], v[34:49]
	v_mfma_f32_32x32x16_bf16 v[18:33], v[194:197], v[190:193], v[18:33]
	v_mfma_f32_32x32x16_bf16 v[2:17], v[194:197], v[198:201], v[2:17]
	ds_read_b128 v[186:189], v149 offset:16384
	ds_read_b128 v[190:193], v149 offset:20480
	ds_read_b128 v[194:197], v148 offset:49152
	ds_read_b128 v[198:201], v148 offset:53248
	s_mov_b32 s0, 0x1a000
	s_waitcnt vmcnt(15)
	ds_write_b128 v0, v[66:69]
	s_waitcnt vmcnt(14)
	ds_write_b128 v0, v[70:73] offset:32768
	s_waitcnt vmcnt(13)
	ds_write_b128 v0, v[74:77] offset:4096
	s_waitcnt vmcnt(12)
	ds_write_b128 v0, v[78:81] offset:36864
	s_waitcnt vmcnt(11)
	ds_write_b128 v0, v[82:85] offset:8192
	s_waitcnt vmcnt(10)
	ds_write_b128 v0, v[86:89] offset:40960
	s_waitcnt vmcnt(9)
	ds_write_b128 v0, v[122:125] offset:12288
	s_waitcnt vmcnt(8)
	ds_write_b128 v0, v[126:129] offset:45056
	v_add_co_u32_e32 v82, vcc, s0, v134
	s_mov_b32 s0, 0x1c000
	s_nop 0
	v_addc_co_u32_e32 v83, vcc, 0, v135, vcc
	s_waitcnt lgkmcnt(0)
	s_barrier
	global_load_dwordx4 v[66:69], v[168:169], off
	global_load_dwordx4 v[70:73], v[136:137], off offset:768
	global_load_dwordx4 v[74:77], v[82:83], off offset:-4096
	global_load_dwordx4 v[78:81], v[140:141], off offset:768
	s_nop 0
	global_load_dwordx4 v[82:85], v[82:83], off
	s_nop 0
	global_load_dwordx4 v[86:89], v[138:139], off offset:768
	v_add_co_u32_e32 v168, vcc, s0, v134
	v_mfma_f32_32x32x16_bf16 v[50:65], v[156:159], v[164:167], v[50:65]
	s_nop 0
	v_addc_co_u32_e32 v169, vcc, 0, v135, vcc
	global_load_dwordx4 v[122:125], v[168:169], off offset:-4096
	global_load_dwordx4 v[126:129], v[142:143], off offset:768
	v_mfma_f32_32x32x16_bf16 v[34:49], v[156:159], v[182:185], v[34:49]
	v_mfma_f32_32x32x16_bf16 v[18:33], v[160:163], v[164:167], v[18:33]
	v_mfma_f32_32x32x16_bf16 v[2:17], v[160:163], v[182:185], v[2:17]
	v_mfma_f32_32x32x16_bf16 v[50:65], v[186:189], v[194:197], v[50:65]
	v_mfma_f32_32x32x16_bf16 v[34:49], v[186:189], v[198:201], v[34:49]
	v_mfma_f32_32x32x16_bf16 v[18:33], v[190:193], v[194:197], v[18:33]
	v_mfma_f32_32x32x16_bf16 v[2:17], v[190:193], v[198:201], v[2:17]
	ds_read_b128 v[156:159], v153
	ds_read_b128 v[160:163], v154 offset:32768
	ds_read_b128 v[164:167], v153 offset:4096
	ds_read_b128 v[182:185], v154 offset:36864
	ds_read_b128 v[186:189], v155
	ds_read_b128 v[190:193], v152 offset:32768
	ds_read_b128 v[194:197], v155 offset:4096
	ds_read_b128 v[198:201], v152 offset:36864
	s_waitcnt lgkmcnt(6)
	v_mfma_f32_32x32x16_bf16 v[50:65], v[156:159], v[160:163], v[50:65]
	s_waitcnt lgkmcnt(4)
	v_mfma_f32_32x32x16_bf16 v[34:49], v[156:159], v[182:185], v[34:49]
	v_mfma_f32_32x32x16_bf16 v[18:33], v[164:167], v[160:163], v[18:33]
	v_mfma_f32_32x32x16_bf16 v[2:17], v[164:167], v[182:185], v[2:17]
	ds_read_b128 v[156:159], v151
	ds_read_b128 v[160:163], v151 offset:4096
	ds_read_b128 v[164:167], v150 offset:32768
	ds_read_b128 v[182:185], v150 offset:36864
	s_waitcnt lgkmcnt(6)
	v_mfma_f32_32x32x16_bf16 v[50:65], v[186:189], v[190:193], v[50:65]
	s_waitcnt lgkmcnt(4)
	v_mfma_f32_32x32x16_bf16 v[34:49], v[186:189], v[198:201], v[34:49]
	v_mfma_f32_32x32x16_bf16 v[18:33], v[194:197], v[190:193], v[18:33]
	v_mfma_f32_32x32x16_bf16 v[2:17], v[194:197], v[198:201], v[2:17]
	ds_read_b128 v[186:189], v149
	ds_read_b128 v[190:193], v149 offset:4096
	ds_read_b128 v[194:197], v148 offset:32768
	ds_read_b128 v[198:201], v148 offset:36864
	s_mov_b32 s0, 0x1e000
	s_waitcnt vmcnt(15)
	ds_write_b128 v0, v[90:93] offset:16384
	s_waitcnt vmcnt(14)
	ds_write_b128 v0, v[94:97] offset:49152
	s_waitcnt vmcnt(13)
	ds_write_b128 v0, v[98:101] offset:20480
	s_waitcnt vmcnt(12)
	ds_write_b128 v0, v[102:105] offset:53248
	v_add_co_u32_e32 v102, vcc, s0, v134
	s_mov_b32 s0, 0x1f000
	s_nop 0
	v_addc_co_u32_e32 v103, vcc, 0, v135, vcc
	s_waitcnt vmcnt(11)
	ds_write_b128 v0, v[106:109] offset:24576
	s_waitcnt vmcnt(10)
	ds_write_b128 v0, v[110:113] offset:57344
	s_waitcnt vmcnt(9)
	ds_write_b128 v0, v[114:117] offset:28672
	s_waitcnt vmcnt(8)
	ds_write_b128 v0, v[118:121] offset:61440
	v_add_co_u32_e32 v110, vcc, s0, v134
	s_waitcnt lgkmcnt(0)
	s_nop 0
	v_addc_co_u32_e32 v111, vcc, 0, v135, vcc
	s_barrier
	global_load_dwordx4 v[90:93], v[136:137], off offset:896
	global_load_dwordx4 v[94:97], v[140:141], off offset:896
	global_load_dwordx4 v[98:101], v[102:103], off offset:-4096
	s_nop 0
	global_load_dwordx4 v[102:105], v[102:103], off
	s_nop 0
	global_load_dwordx4 v[106:109], v[168:169], off
	s_nop 0
	global_load_dwordx4 v[110:113], v[110:111], off
	s_nop 0
	global_load_dwordx4 v[114:117], v[138:139], off offset:896
	global_load_dwordx4 v[118:121], v[142:143], off offset:896
	v_mfma_f32_32x32x16_bf16 v[50:65], v[156:159], v[164:167], v[50:65]
	v_mfma_f32_32x32x16_bf16 v[34:49], v[156:159], v[182:185], v[34:49]
	v_mfma_f32_32x32x16_bf16 v[18:33], v[160:163], v[164:167], v[18:33]
	v_mfma_f32_32x32x16_bf16 v[2:17], v[160:163], v[182:185], v[2:17]
	v_mfma_f32_32x32x16_bf16 v[50:65], v[186:189], v[194:197], v[50:65]
	v_mfma_f32_32x32x16_bf16 v[34:49], v[186:189], v[198:201], v[34:49]
	v_mfma_f32_32x32x16_bf16 v[18:33], v[190:193], v[194:197], v[18:33]
	ds_read_b128 v[134:137], v153 offset:16384
	ds_read_b128 v[138:141], v153 offset:20480
	ds_read_b128 v[156:159], v154 offset:49152
	ds_read_b128 v[160:163], v154 offset:53248
	ds_read_b128 v[164:167], v155 offset:16384
	ds_read_b128 v[182:185], v155 offset:20480
	ds_read_b128 v[186:189], v152 offset:49152
	ds_read_b128 v[194:197], v152 offset:53248
	v_mfma_f32_32x32x16_bf16 v[2:17], v[190:193], v[198:201], v[2:17]
	s_waitcnt lgkmcnt(5)
	v_mfma_f32_32x32x16_bf16 v[50:65], v[134:137], v[156:159], v[50:65]
	s_waitcnt lgkmcnt(4)
	v_mfma_f32_32x32x16_bf16 v[34:49], v[134:137], v[160:163], v[34:49]
	v_mfma_f32_32x32x16_bf16 v[18:33], v[138:141], v[156:159], v[18:33]
	v_mfma_f32_32x32x16_bf16 v[2:17], v[138:141], v[160:163], v[2:17]
	ds_read_b128 v[134:137], v151 offset:16384
	ds_read_b128 v[138:141], v151 offset:20480
	ds_read_b128 v[156:159], v150 offset:49152
	ds_read_b128 v[160:163], v150 offset:53248
	s_waitcnt lgkmcnt(5)
	v_mfma_f32_32x32x16_bf16 v[50:65], v[164:167], v[186:189], v[50:65]
	s_waitcnt lgkmcnt(4)
	v_mfma_f32_32x32x16_bf16 v[34:49], v[164:167], v[194:197], v[34:49]
	v_mfma_f32_32x32x16_bf16 v[18:33], v[182:185], v[186:189], v[18:33]
	v_mfma_f32_32x32x16_bf16 v[2:17], v[182:185], v[194:197], v[2:17]
	ds_read_b128 v[164:167], v149 offset:16384
	ds_read_b128 v[182:185], v149 offset:20480
	ds_read_b128 v[186:189], v148 offset:49152
	ds_read_b128 v[190:193], v148 offset:53248
	s_waitcnt vmcnt(15)
	ds_write_b128 v0, v[66:69]
	s_waitcnt vmcnt(14)
	ds_write_b128 v0, v[70:73] offset:32768
	s_waitcnt vmcnt(13)
	ds_write_b128 v0, v[74:77] offset:4096
	s_waitcnt vmcnt(12)
	ds_write_b128 v0, v[78:81] offset:36864
	s_waitcnt vmcnt(11)
	ds_write_b128 v0, v[82:85] offset:8192
	s_waitcnt vmcnt(10)
	ds_write_b128 v0, v[86:89] offset:40960
	s_waitcnt vmcnt(9)
	ds_write_b128 v0, v[122:125] offset:12288
	s_waitcnt vmcnt(8)
	ds_write_b128 v0, v[126:129] offset:45056
	s_waitcnt lgkmcnt(0)
	s_barrier
	ds_read_b128 v[66:69], v153
	ds_read_b128 v[70:73], v153 offset:4096
	ds_read_b128 v[74:77], v154 offset:32768
	ds_read_b128 v[78:81], v154 offset:36864
	ds_read_b128 v[82:85], v155
	ds_read_b128 v[86:89], v155 offset:4096
	ds_read_b128 v[122:125], v152 offset:32768
	ds_read_b128 v[126:129], v152 offset:36864
	v_mfma_f32_32x32x16_bf16 v[50:65], v[134:137], v[156:159], v[50:65]
	v_mfma_f32_32x32x16_bf16 v[34:49], v[134:137], v[160:163], v[34:49]
	v_mfma_f32_32x32x16_bf16 v[18:33], v[138:141], v[156:159], v[18:33]
	v_mfma_f32_32x32x16_bf16 v[2:17], v[138:141], v[160:163], v[2:17]
	v_mfma_f32_32x32x16_bf16 v[50:65], v[164:167], v[186:189], v[50:65]
	v_mfma_f32_32x32x16_bf16 v[34:49], v[164:167], v[190:193], v[34:49]
	v_mfma_f32_32x32x16_bf16 v[18:33], v[182:185], v[186:189], v[18:33]
	v_mfma_f32_32x32x16_bf16 v[2:17], v[182:185], v[190:193], v[2:17]
	s_waitcnt lgkmcnt(5)
	v_mfma_f32_32x32x16_bf16 v[50:65], v[66:69], v[74:77], v[50:65]
	s_waitcnt lgkmcnt(4)
	v_mfma_f32_32x32x16_bf16 v[34:49], v[66:69], v[78:81], v[34:49]
	v_mfma_f32_32x32x16_bf16 v[18:33], v[70:73], v[74:77], v[18:33]
	v_mfma_f32_32x32x16_bf16 v[2:17], v[70:73], v[78:81], v[2:17]
	ds_read_b128 v[66:69], v151
	ds_read_b128 v[70:73], v151 offset:4096
	ds_read_b128 v[74:77], v150 offset:32768
	ds_read_b128 v[78:81], v150 offset:36864
	s_waitcnt lgkmcnt(5)
	v_mfma_f32_32x32x16_bf16 v[50:65], v[82:85], v[122:125], v[50:65]
	s_waitcnt lgkmcnt(4)
	v_mfma_f32_32x32x16_bf16 v[34:49], v[82:85], v[126:129], v[34:49]
	v_mfma_f32_32x32x16_bf16 v[18:33], v[86:89], v[122:125], v[18:33]
	v_mfma_f32_32x32x16_bf16 v[2:17], v[86:89], v[126:129], v[2:17]
	ds_read_b128 v[82:85], v149
	ds_read_b128 v[86:89], v149 offset:4096
	ds_read_b128 v[122:125], v148 offset:32768
	ds_read_b128 v[126:129], v148 offset:36864
	s_waitcnt lgkmcnt(5)
	v_mfma_f32_32x32x16_bf16 v[50:65], v[66:69], v[74:77], v[50:65]
	s_waitcnt vmcnt(3)
	ds_write_b128 v0, v[106:109] offset:16384
	ds_write_b128 v0, v[90:93] offset:49152
	ds_write_b128 v0, v[98:101] offset:20480
	ds_write_b128 v0, v[94:97] offset:53248
	ds_write_b128 v0, v[102:105] offset:24576
	s_waitcnt vmcnt(1)
	ds_write_b128 v0, v[114:117] offset:57344
	ds_write_b128 v0, v[110:113] offset:28672
	s_waitcnt vmcnt(0)
	ds_write_b128 v0, v[118:121] offset:61440
	s_waitcnt lgkmcnt(0)
	s_barrier
	v_mfma_f32_32x32x16_bf16 v[34:49], v[66:69], v[78:81], v[34:49]
	v_mfma_f32_32x32x16_bf16 v[18:33], v[70:73], v[74:77], v[18:33]
	v_mfma_f32_32x32x16_bf16 v[2:17], v[70:73], v[78:81], v[2:17]
	v_mfma_f32_32x32x16_bf16 v[50:65], v[82:85], v[122:125], v[50:65]
	v_mfma_f32_32x32x16_bf16 v[34:49], v[82:85], v[126:129], v[34:49]
	ds_read_b128 v[66:69], v153 offset:16384
	ds_read_b128 v[70:73], v153 offset:20480
	ds_read_b128 v[74:77], v154 offset:49152
	ds_read_b128 v[78:81], v154 offset:53248
	ds_read_b128 v[82:85], v155 offset:16384
	ds_read_b128 v[90:93], v155 offset:20480
	ds_read_b128 v[94:97], v152 offset:49152
	ds_read_b128 v[98:101], v152 offset:53248
	v_mfma_f32_32x32x16_bf16 v[18:33], v[86:89], v[122:125], v[18:33]
	v_mfma_f32_32x32x16_bf16 v[2:17], v[86:89], v[126:129], v[2:17]
	s_waitcnt lgkmcnt(5)
	v_mfma_f32_32x32x16_bf16 v[50:65], v[66:69], v[74:77], v[50:65]
	s_waitcnt lgkmcnt(4)
	v_mfma_f32_32x32x16_bf16 v[34:49], v[66:69], v[78:81], v[34:49]
	v_mfma_f32_32x32x16_bf16 v[18:33], v[70:73], v[74:77], v[18:33]
	v_mfma_f32_32x32x16_bf16 v[2:17], v[70:73], v[78:81], v[2:17]
	ds_read_b128 v[66:69], v151 offset:16384
	ds_read_b128 v[70:73], v151 offset:20480
	ds_read_b128 v[74:77], v150 offset:49152
	ds_read_b128 v[78:81], v150 offset:53248
	s_waitcnt lgkmcnt(5)
	v_mfma_f32_32x32x16_bf16 v[50:65], v[82:85], v[94:97], v[50:65]
	s_waitcnt lgkmcnt(4)
	v_mfma_f32_32x32x16_bf16 v[34:49], v[82:85], v[98:101], v[34:49]
	v_mfma_f32_32x32x16_bf16 v[18:33], v[90:93], v[94:97], v[18:33]
	v_mfma_f32_32x32x16_bf16 v[2:17], v[90:93], v[98:101], v[2:17]
	ds_read_b128 v[82:85], v149 offset:16384
	ds_read_b128 v[86:89], v149 offset:20480
	ds_read_b128 v[90:93], v148 offset:49152
	ds_read_b128 v[94:97], v148 offset:53248
	s_waitcnt lgkmcnt(4)
	v_mfma_f32_32x32x16_bf16 v[50:65], v[66:69], v[74:77], v[50:65]
	v_mfma_f32_32x32x16_bf16 v[34:49], v[66:69], v[78:81], v[34:49]
	v_mfma_f32_32x32x16_bf16 v[18:33], v[70:73], v[74:77], v[18:33]
	v_mfma_f32_32x32x16_bf16 v[2:17], v[70:73], v[78:81], v[2:17]
	s_waitcnt lgkmcnt(0)
	s_barrier
	v_mfma_f32_32x32x16_bf16 v[50:65], v[82:85], v[90:93], v[50:65]
	v_mfma_f32_32x32x16_bf16 v[34:49], v[82:85], v[94:97], v[34:49]
	v_mfma_f32_32x32x16_bf16 v[18:33], v[86:89], v[90:93], v[18:33]
	v_mfma_f32_32x32x16_bf16 v[2:17], v[86:89], v[94:97], v[2:17]
	v_readlane_b32 s4, v209, 2
	v_and_b32_e32 v66, 31, v133
	v_bfe_u32 v67, v133, 6, 1
	v_lshlrev_b32_e32 v66, 2, v66
	s_lshr_b32 s0, s4, 6
	s_lshl_b32 s0, s0, 19
	s_add_u32 s0, s94, s0
	s_addc_u32 s1, s95, 0
	s_bfe_u32 s4, s4, 0x30003
	s_lshl_b32 s4, s4, 9
	v_lshl_add_u32 v66, v67, 8, v66
	v_add_u32_e32 v66, s4, v66
	v_readlane_b32 s4, v208, 62
	v_bfe_u32 v67, v133, 7, 1
	v_bfe_u32 v70, v133, 5, 1
	s_add_i32 s4, s4, 4
	s_mul_i32 s4, s4, 0x6000
	s_add_i32 s4, s4, 0x5000
	s_add_u32 s2, s90, s4
	s_addc_u32 s3, s91, 0
	global_load_dword v68, v66, s[2:3]
	global_load_dword v69, v66, s[2:3] offset:128
	v_lshlrev_b32_e32 v67, 18, v67
	v_lshl_add_u32 v67, v70, 14, v67
	v_add_u32_e32 v66, v67, v66
	s_waitcnt vmcnt(0)
	s_add_u32 s2, s0, 0x0
	s_addc_u32 s3, s1, 0
	v_mul_f32_e32 v72, v68, v50
	v_mul_f32_e32 v73, v69, v34
	global_atomic_add_f32 v66, v72, s[2:3]
	global_atomic_add_f32 v66, v73, s[2:3] offset:128
	s_add_u32 s2, s0, 0x1000
	s_addc_u32 s3, s1, 0
	v_mul_f32_e32 v74, v68, v51
	v_mul_f32_e32 v75, v69, v35
	global_atomic_add_f32 v66, v74, s[2:3]
	global_atomic_add_f32 v66, v75, s[2:3] offset:128
	s_add_u32 s2, s0, 0x2000
	s_addc_u32 s3, s1, 0
	v_mul_f32_e32 v76, v68, v52
	v_mul_f32_e32 v77, v69, v36
	global_atomic_add_f32 v66, v76, s[2:3]
	global_atomic_add_f32 v66, v77, s[2:3] offset:128
	s_add_u32 s2, s0, 0x3000
	s_addc_u32 s3, s1, 0
	v_mul_f32_e32 v78, v68, v53
	v_mul_f32_e32 v79, v69, v37
	global_atomic_add_f32 v66, v78, s[2:3]
	global_atomic_add_f32 v66, v79, s[2:3] offset:128
	s_add_u32 s2, s0, 0x8000
	s_addc_u32 s3, s1, 0
	v_mul_f32_e32 v72, v68, v54
	v_mul_f32_e32 v73, v69, v38
	global_atomic_add_f32 v66, v72, s[2:3]
	global_atomic_add_f32 v66, v73, s[2:3] offset:128
	s_add_u32 s2, s0, 0x9000
	s_addc_u32 s3, s1, 0
	v_mul_f32_e32 v74, v68, v55
	v_mul_f32_e32 v75, v69, v39
	global_atomic_add_f32 v66, v74, s[2:3]
	global_atomic_add_f32 v66, v75, s[2:3] offset:128
	s_add_u32 s2, s0, 0xa000
	s_addc_u32 s3, s1, 0
	v_mul_f32_e32 v76, v68, v56
	v_mul_f32_e32 v77, v69, v40
	global_atomic_add_f32 v66, v76, s[2:3]
	global_atomic_add_f32 v66, v77, s[2:3] offset:128
	s_add_u32 s2, s0, 0xb000
	s_addc_u32 s3, s1, 0
	v_mul_f32_e32 v78, v68, v57
	v_mul_f32_e32 v79, v69, v41
	global_atomic_add_f32 v66, v78, s[2:3]
	global_atomic_add_f32 v66, v79, s[2:3] offset:128
	s_add_u32 s2, s0, 0x10000
	s_addc_u32 s3, s1, 0
	v_mul_f32_e32 v72, v68, v58
	v_mul_f32_e32 v73, v69, v42
	global_atomic_add_f32 v66, v72, s[2:3]
	global_atomic_add_f32 v66, v73, s[2:3] offset:128
	s_add_u32 s2, s0, 0x11000
	s_addc_u32 s3, s1, 0
	v_mul_f32_e32 v74, v68, v59
	v_mul_f32_e32 v75, v69, v43
	global_atomic_add_f32 v66, v74, s[2:3]
	global_atomic_add_f32 v66, v75, s[2:3] offset:128
	s_add_u32 s2, s0, 0x12000
	s_addc_u32 s3, s1, 0
	v_mul_f32_e32 v76, v68, v60
	v_mul_f32_e32 v77, v69, v44
	global_atomic_add_f32 v66, v76, s[2:3]
	global_atomic_add_f32 v66, v77, s[2:3] offset:128
	s_add_u32 s2, s0, 0x13000
	s_addc_u32 s3, s1, 0
	v_mul_f32_e32 v78, v68, v61
	v_mul_f32_e32 v79, v69, v45
	global_atomic_add_f32 v66, v78, s[2:3]
	global_atomic_add_f32 v66, v79, s[2:3] offset:128
	s_add_u32 s2, s0, 0x18000
	s_addc_u32 s3, s1, 0
	v_mul_f32_e32 v72, v68, v62
	v_mul_f32_e32 v73, v69, v46
	global_atomic_add_f32 v66, v72, s[2:3]
	global_atomic_add_f32 v66, v73, s[2:3] offset:128
	s_add_u32 s2, s0, 0x19000
	s_addc_u32 s3, s1, 0
	v_mul_f32_e32 v74, v68, v63
	v_mul_f32_e32 v75, v69, v47
	global_atomic_add_f32 v66, v74, s[2:3]
	global_atomic_add_f32 v66, v75, s[2:3] offset:128
	s_add_u32 s2, s0, 0x1a000
	s_addc_u32 s3, s1, 0
	v_mul_f32_e32 v76, v68, v64
	v_mul_f32_e32 v77, v69, v48
	global_atomic_add_f32 v66, v76, s[2:3]
	global_atomic_add_f32 v66, v77, s[2:3] offset:128
	s_add_u32 s2, s0, 0x1b000
	s_addc_u32 s3, s1, 0
	v_mul_f32_e32 v78, v68, v65
	v_mul_f32_e32 v79, v69, v49
	global_atomic_add_f32 v66, v78, s[2:3]
	global_atomic_add_f32 v66, v79, s[2:3] offset:128
	s_add_u32 s2, s0, 0x20000
	s_addc_u32 s3, s1, 0
	v_mul_f32_e32 v72, v68, v18
	v_mul_f32_e32 v73, v69, v2
	global_atomic_add_f32 v66, v72, s[2:3]
	global_atomic_add_f32 v66, v73, s[2:3] offset:128
	s_add_u32 s2, s0, 0x21000
	s_addc_u32 s3, s1, 0
	v_mul_f32_e32 v74, v68, v19
	v_mul_f32_e32 v75, v69, v3
	global_atomic_add_f32 v66, v74, s[2:3]
	global_atomic_add_f32 v66, v75, s[2:3] offset:128
	s_add_u32 s2, s0, 0x22000
	s_addc_u32 s3, s1, 0
	v_mul_f32_e32 v76, v68, v20
	v_mul_f32_e32 v77, v69, v4
	global_atomic_add_f32 v66, v76, s[2:3]
	global_atomic_add_f32 v66, v77, s[2:3] offset:128
	s_add_u32 s2, s0, 0x23000
	s_addc_u32 s3, s1, 0
	v_mul_f32_e32 v78, v68, v21
	v_mul_f32_e32 v79, v69, v5
	global_atomic_add_f32 v66, v78, s[2:3]
	global_atomic_add_f32 v66, v79, s[2:3] offset:128
	s_add_u32 s2, s0, 0x28000
	s_addc_u32 s3, s1, 0
	v_mul_f32_e32 v72, v68, v22
	v_mul_f32_e32 v73, v69, v6
	global_atomic_add_f32 v66, v72, s[2:3]
	global_atomic_add_f32 v66, v73, s[2:3] offset:128
	s_add_u32 s2, s0, 0x29000
	s_addc_u32 s3, s1, 0
	v_mul_f32_e32 v74, v68, v23
	v_mul_f32_e32 v75, v69, v7
	global_atomic_add_f32 v66, v74, s[2:3]
	global_atomic_add_f32 v66, v75, s[2:3] offset:128
	s_add_u32 s2, s0, 0x2a000
	s_addc_u32 s3, s1, 0
	v_mul_f32_e32 v76, v68, v24
	v_mul_f32_e32 v77, v69, v8
	global_atomic_add_f32 v66, v76, s[2:3]
	global_atomic_add_f32 v66, v77, s[2:3] offset:128
	s_add_u32 s2, s0, 0x2b000
	s_addc_u32 s3, s1, 0
	v_mul_f32_e32 v78, v68, v25
	v_mul_f32_e32 v79, v69, v9
	global_atomic_add_f32 v66, v78, s[2:3]
	global_atomic_add_f32 v66, v79, s[2:3] offset:128
	s_add_u32 s2, s0, 0x30000
	s_addc_u32 s3, s1, 0
	v_mul_f32_e32 v72, v68, v26
	v_mul_f32_e32 v73, v69, v10
	global_atomic_add_f32 v66, v72, s[2:3]
	global_atomic_add_f32 v66, v73, s[2:3] offset:128
	s_add_u32 s2, s0, 0x31000
	s_addc_u32 s3, s1, 0
	v_mul_f32_e32 v74, v68, v27
	v_mul_f32_e32 v75, v69, v11
	global_atomic_add_f32 v66, v74, s[2:3]
	global_atomic_add_f32 v66, v75, s[2:3] offset:128
	s_add_u32 s2, s0, 0x32000
	s_addc_u32 s3, s1, 0
	v_mul_f32_e32 v76, v68, v28
	v_mul_f32_e32 v77, v69, v12
	global_atomic_add_f32 v66, v76, s[2:3]
	global_atomic_add_f32 v66, v77, s[2:3] offset:128
	s_add_u32 s2, s0, 0x33000
	s_addc_u32 s3, s1, 0
	v_mul_f32_e32 v78, v68, v29
	v_mul_f32_e32 v79, v69, v13
	global_atomic_add_f32 v66, v78, s[2:3]
	global_atomic_add_f32 v66, v79, s[2:3] offset:128
	s_add_u32 s2, s0, 0x38000
	s_addc_u32 s3, s1, 0
	v_mul_f32_e32 v72, v68, v30
	v_mul_f32_e32 v73, v69, v14
	global_atomic_add_f32 v66, v72, s[2:3]
	global_atomic_add_f32 v66, v73, s[2:3] offset:128
	s_add_u32 s2, s0, 0x39000
	s_addc_u32 s3, s1, 0
	v_mul_f32_e32 v74, v68, v31
	v_mul_f32_e32 v75, v69, v15
	global_atomic_add_f32 v66, v74, s[2:3]
	global_atomic_add_f32 v66, v75, s[2:3] offset:128
	s_add_u32 s2, s0, 0x3a000
	s_addc_u32 s3, s1, 0
	v_mul_f32_e32 v76, v68, v32
	v_mul_f32_e32 v77, v69, v16
	global_atomic_add_f32 v66, v76, s[2:3]
	global_atomic_add_f32 v66, v77, s[2:3] offset:128
	s_add_u32 s2, s0, 0x3b000
	s_addc_u32 s3, s1, 0
	v_mul_f32_e32 v78, v68, v33
	v_mul_f32_e32 v79, v69, v17
	global_atomic_add_f32 v66, v78, s[2:3]
	global_atomic_add_f32 v66, v79, s[2:3] offset:128

	.amdhsa_kernel _Z11mega_kernel6Params
		.amdhsa_group_segment_fixed_size 65560
		.amdhsa_private_segment_fixed_size 0
		.amdhsa_kernarg_size 696
		.amdhsa_user_sgpr_count 2
		.amdhsa_user_sgpr_dispatch_ptr 0
		.amdhsa_user_sgpr_queue_ptr 0
		.amdhsa_user_sgpr_kernarg_segment_ptr 1
		.amdhsa_user_sgpr_dispatch_id 0
		.amdhsa_user_sgpr_kernarg_preload_length 0
		.amdhsa_user_sgpr_kernarg_preload_offset 0
		.amdhsa_user_sgpr_private_segment_size 0
		.amdhsa_uses_dynamic_stack 0
		.amdhsa_enable_private_segment 0
		.amdhsa_system_sgpr_workgroup_id_x 1
		.amdhsa_system_sgpr_workgroup_id_y 0
		.amdhsa_system_sgpr_workgroup_id_z 0
		.amdhsa_system_sgpr_workgroup_info 0
		.amdhsa_system_vgpr_workitem_id 2
		.amdhsa_next_free_vgpr 216
		.amdhsa_next_free_sgpr 100
		.amdhsa_accum_offset 216
		.amdhsa_reserve_vcc 1
		.amdhsa_float_round_mode_32 0
		.amdhsa_float_round_mode_16_64 0
		.amdhsa_float_denorm_mode_32 3
		.amdhsa_float_denorm_mode_16_64 3
		.amdhsa_dx10_clamp 1
		.amdhsa_ieee_mode 1
		.amdhsa_fp16_overflow 0
		.amdhsa_tg_split 0
		.amdhsa_exception_fp_ieee_invalid_op 0
		.amdhsa_exception_fp_denorm_src 0
		.amdhsa_exception_fp_ieee_div_zero 0
		.amdhsa_exception_fp_ieee_overflow 0
		.amdhsa_exception_fp_ieee_underflow 0
		.amdhsa_exception_fp_ieee_inexact 0
		.amdhsa_exception_int_div_zero 0
	.end_amdhsa_kernel

amdhsa.kernels:
  - .agpr_count:     0
    .args:
      - .offset:         0
        .size:           440
        .value_kind:     by_value
      - .offset:         440
        .size:           4
        .value_kind:     hidden_block_count_x
      - .offset:         444
        .size:           4
        .value_kind:     hidden_block_count_y
      - .offset:         448
        .size:           4
        .value_kind:     hidden_block_count_z
      - .offset:         452
        .size:           2
        .value_kind:     hidden_group_size_x
      - .offset:         454
        .size:           2
        .value_kind:     hidden_group_size_y
      - .offset:         456
        .size:           2
        .value_kind:     hidden_group_size_z
      - .offset:         458
        .size:           2
        .value_kind:     hidden_remainder_x
      - .offset:         460
        .size:           2
        .value_kind:     hidden_remainder_y
      - .offset:         462
        .size:           2
        .value_kind:     hidden_remainder_z
      - .offset:         480
        .size:           8
        .value_kind:     hidden_global_offset_x
      - .offset:         488
        .size:           8
        .value_kind:     hidden_global_offset_y
      - .offset:         496
        .size:           8
        .value_kind:     hidden_global_offset_z
      - .offset:         504
        .size:           2
        .value_kind:     hidden_grid_dims
      - .offset:         528
        .size:           8
        .value_kind:     hidden_multigrid_sync_arg
    .group_segment_fixed_size: 65560
    .kernarg_segment_align: 8
    .kernarg_segment_size: 696
    .language:       OpenCL C
    .language_version:
      - 2
      - 0
    .max_flat_workgroup_size: 256
    .name:           _Z11mega_kernel6Params
    .private_segment_fixed_size: 0
    .sgpr_count:     106
    .sgpr_spill_count: 289
    .symbol:         _Z11mega_kernel6Params.kd
    .uniform_work_group_size: 1
    .uses_dynamic_stack: false
    .vgpr_count:     216
    .vgpr_spill_count: 0
    .wavefront_size: 64
